# plus: duplicate lgkmcnt(0) waits removed from the GEMM K-loops (6 per K-iteration)
# baseline (speedup 1.0000x reference)
; #define PG8_STAGE(bufoff, gbase, voff) do { _Pragma("unroll") for (int _i = 0; _i < 2; ++_i) \
;     __builtin_amdgcn_global_load_lds((const unsigned*)((const char*)(gbase) + (voff)[_i]), (LAS unsigned*)(lds + (bufoff) + ldsw + _i * 8192), 16, 0, 0); } while (0)
; #define PG8_LDA(dst, b, h) do { _Pragma("unroll") for (int m = 0; m < 4; ++m) _Pragma("unroll") for (int k = 0; k < 2; ++k) dst[m][k] = *(const LAS bf16x8*)(lds + PG8_SA(b, h) + aoff + m * 2048 + k * 1024); } while (0)
; #define PG8_LDB(dst, b, h) do { _Pragma("unroll") for (int n = 0; n < 2; ++n) _Pragma("unroll") for (int k = 0; k < 2; ++k) dst[n][k] = *(const LAS bf16x8*)(lds + PG8_SB(b, h) + boff + n * 2048 + k * 1024); } while (0)
; #define PG8_WAIT_V(n) asm volatile("s_waitcnt vmcnt(" #n ")" ::: "memory")
; template <class Epi, class Sched>
; DI void gemm_phase(LAS unsigned char* lds, const Gemm g, const Sched& S, const Epi& E) {
;     ...
;     for (int t = 0; t < nt; t += 2) {
;       const bool last = (t == nt - 2);
;       const char* a1 = cA + (size_t)(t + 1) * kstep;
;       const char* a2 = last ? nA : cA + (size_t)(t + 2) * kstep; const char* b2 = last ? nB : cB + (size_t)(t + 2) * kstep;
;       const char* a3 = a2 + kstep; const char* b3 = b2 + kstep;
;       PG8_LDB(B0, 0, 0); PG8_SCHED; PG8_LDA(At, 0, 0); PG8_STAGE(PG8_SA(1, 1), a1 + hstep, voffA);
;       PG8_WAIT_L(8); PG8_BAR; PG8_WAIT_L(0); PG8_MMA(0, 0, At, B0); PG8_BAR; PG8_SCHED;
;       PG8_LDB(B1, 0, 1); PG8_STAGE(PG8_SB(0, 0), b2, voffB);
;       PG8_BAR; PG8_WAIT_L(0); PG8_MMA(0, 1, At, B1); PG8_BAR;
;       PG8_LDA(At, 0, 1); PG8_STAGE(PG8_SA(0, 0), a2, voffA);
;       PG8_BAR; PG8_WAIT_L(0); PG8_MMA(1, 0, At, B0); PG8_BAR; PG8_SCHED;
;       PG8_STAGE(PG8_SB(0, 1), b2 + hstep, voffB);
;       PG8_WAIT_V(6); PG8_BAR; PG8_MMA(1, 1, At, B1); PG8_BAR;
;       PG8_LDB(B0, 1, 0); PG8_SCHED; PG8_LDA(At, 1, 0); PG8_STAGE(PG8_SA(0, 1), a2 + hstep, voffA);
;       PG8_WAIT_L(8); PG8_BAR; PG8_WAIT_L(0); PG8_MMA(0, 0, At, B0); PG8_BAR; PG8_SCHED;
;       PG8_LDB(B1, 1, 1); PG8_STAGE(PG8_SB(1, 0), b3, voffB);
;       PG8_BAR; PG8_WAIT_L(0); PG8_MMA(0, 1, At, B1); PG8_BAR;
;       PG8_LDA(At, 1, 1); PG8_STAGE(PG8_SA(1, 0), a3, voffA);
;       PG8_BAR; PG8_WAIT_L(0); PG8_MMA(1, 0, At, B0); PG8_BAR; PG8_SCHED;
;       PG8_STAGE(PG8_SB(1, 1), b3 + hstep, voffB);
;       PG8_WAIT_V(6); PG8_BAR; PG8_MMA(1, 1, At, B1); PG8_BAR;
;     }
.LBB0_370:
	s_add_u32 s4, s2, 0xfffc0080
	s_addc_u32 s5, s3, -1
	s_add_i32 s51, 0, 0x10000
	v_add_u32_e32 v144, s51, v155
	ds_read_b128 v[128:131], v144
	ds_read_b128 v[146:149], v144 offset:1024
	ds_read_b128 v[150:153], v144 offset:2048
	ds_read_b128 v[160:163], v144 offset:3072
	s_cmp_eq_u32 s50, 12
	s_cselect_b32 s21, s15, s5
	s_cselect_b32 s20, s29, s4
	s_cselect_b32 s5, s13, s49
	s_cselect_b32 s4, s36, s37
	v_lshl_add_u64 v[156:157], s[2:3], 0, v[140:141]
	s_add_i32 m0, s40, 0xc000
	ds_read_b128 v[164:167], v158
	ds_read_b128 v[168:171], v158 offset:1024
	ds_read_b128 v[172:175], v158 offset:2048
	ds_read_b128 v[176:179], v158 offset:3072
	ds_read_b128 v[196:199], v158 offset:4096
	ds_read_b128 v[200:203], v158 offset:5120
	ds_read_b128 v[204:207], v158 offset:6144
	ds_read_b128 v[208:211], v158 offset:7168
	global_load_lds_dwordx4 v[156:157], off
	v_lshl_add_u64 v[156:157], s[2:3], 0, v[142:143]
	s_add_i32 m0, s40, 0xe000
	s_nop 0
	global_load_lds_dwordx4 v[156:157], off
	s_waitcnt lgkmcnt(8)
	s_barrier
	s_waitcnt lgkmcnt(0)
	v_mfma_f32_16x16x32_bf16 v[124:127], v[128:131], v[164:167], v[124:127]
	v_mfma_f32_16x16x32_bf16 v[120:123], v[150:153], v[164:167], v[120:123]
	v_mfma_f32_16x16x32_bf16 v[108:111], v[128:131], v[172:175], v[108:111]
	v_mfma_f32_16x16x32_bf16 v[104:107], v[150:153], v[172:175], v[104:107]
	v_mfma_f32_16x16x32_bf16 v[92:95], v[128:131], v[196:199], v[92:95]
	v_mfma_f32_16x16x32_bf16 v[88:91], v[150:153], v[196:199], v[88:91]
	v_mfma_f32_16x16x32_bf16 v[76:79], v[128:131], v[204:207], v[76:79]
	v_mfma_f32_16x16x32_bf16 v[72:75], v[150:153], v[204:207], v[72:75]
	v_mfma_f32_16x16x32_bf16 v[124:127], v[146:149], v[168:171], v[124:127]
	v_mfma_f32_16x16x32_bf16 v[120:123], v[160:163], v[168:171], v[120:123]
	v_mfma_f32_16x16x32_bf16 v[108:111], v[146:149], v[176:179], v[108:111]
	v_mfma_f32_16x16x32_bf16 v[104:107], v[160:163], v[176:179], v[104:107]
	v_mfma_f32_16x16x32_bf16 v[92:95], v[146:149], v[200:203], v[92:95]
	v_mfma_f32_16x16x32_bf16 v[88:91], v[160:163], v[200:203], v[88:91]
	v_mfma_f32_16x16x32_bf16 v[76:79], v[146:149], v[208:211], v[76:79]
	v_mfma_f32_16x16x32_bf16 v[72:75], v[160:163], v[208:211], v[72:75]
	s_barrier
	s_add_i32 s54, 0, 0x14000
	s_add_i32 s51, s51, s34
	v_add_u32_e32 v144, s54, v155
	v_lshl_add_u64 v[156:157], s[4:5], 0, v[136:137]
	s_mov_b32 m0, s51
	ds_read_b128 v[212:215], v144
	ds_read_b128 v[216:219], v144 offset:1024
	ds_read_b128 v[220:223], v144 offset:2048
	ds_read_b128 v[224:227], v144 offset:3072
	global_load_lds_dwordx4 v[156:157], off
	v_lshl_add_u64 v[180:181], s[4:5], 0, v[132:133]
	s_add_i32 m0, s51, 0x2000
	s_nop 0
	global_load_lds_dwordx4 v[180:181], off
	s_barrier
	s_waitcnt lgkmcnt(0)
	v_mfma_f32_16x16x32_bf16 v[116:119], v[212:215], v[164:167], v[116:119]
	v_mfma_f32_16x16x32_bf16 v[112:115], v[220:223], v[164:167], v[112:115]
	v_mfma_f32_16x16x32_bf16 v[100:103], v[212:215], v[172:175], v[100:103]
	v_mfma_f32_16x16x32_bf16 v[96:99], v[220:223], v[172:175], v[96:99]
	v_mfma_f32_16x16x32_bf16 v[84:87], v[212:215], v[196:199], v[84:87]
	v_mfma_f32_16x16x32_bf16 v[80:83], v[220:223], v[196:199], v[80:83]
	v_mfma_f32_16x16x32_bf16 v[68:71], v[212:215], v[204:207], v[68:71]
	v_mfma_f32_16x16x32_bf16 v[64:67], v[220:223], v[204:207], v[64:67]
	v_mfma_f32_16x16x32_bf16 v[116:119], v[216:219], v[168:171], v[116:119]
	v_mfma_f32_16x16x32_bf16 v[112:115], v[224:227], v[168:171], v[112:115]
	v_mfma_f32_16x16x32_bf16 v[100:103], v[216:219], v[176:179], v[100:103]
	v_mfma_f32_16x16x32_bf16 v[96:99], v[224:227], v[176:179], v[96:99]
	v_mfma_f32_16x16x32_bf16 v[84:87], v[216:219], v[200:203], v[84:87]
	v_mfma_f32_16x16x32_bf16 v[80:83], v[224:227], v[200:203], v[80:83]
	v_mfma_f32_16x16x32_bf16 v[68:71], v[216:219], v[208:211], v[68:71]
	v_mfma_f32_16x16x32_bf16 v[64:67], v[224:227], v[208:211], v[64:67]
	s_mov_b32 m0, s40
	v_lshl_add_u64 v[228:229], s[20:21], 0, v[138:139]
	s_barrier
	ds_read_b128 v[164:167], v158 offset:16384
	ds_read_b128 v[168:171], v158 offset:17408
	ds_read_b128 v[172:175], v158 offset:18432
	ds_read_b128 v[176:179], v158 offset:19456
	ds_read_b128 v[196:199], v158 offset:20480
	ds_read_b128 v[200:203], v158 offset:21504
	ds_read_b128 v[204:207], v158 offset:22528
	ds_read_b128 v[208:211], v158 offset:23552
	global_load_lds_dwordx4 v[228:229], off
	v_lshl_add_u64 v[230:231], s[20:21], 0, v[134:135]
	s_mov_b32 m0, s41
	s_nop 0
	global_load_lds_dwordx4 v[230:231], off
	s_barrier
	s_waitcnt lgkmcnt(0)
	v_mfma_f32_16x16x32_bf16 v[60:63], v[128:131], v[164:167], v[60:63]
	v_mfma_f32_16x16x32_bf16 v[56:59], v[150:153], v[164:167], v[56:59]
	v_mfma_f32_16x16x32_bf16 v[44:47], v[128:131], v[172:175], v[44:47]
	v_mfma_f32_16x16x32_bf16 v[40:43], v[150:153], v[172:175], v[40:43]
	v_mfma_f32_16x16x32_bf16 v[28:31], v[128:131], v[196:199], v[28:31]
	v_mfma_f32_16x16x32_bf16 v[24:27], v[150:153], v[196:199], v[24:27]
	v_mfma_f32_16x16x32_bf16 v[12:15], v[128:131], v[204:207], v[12:15]
	v_mfma_f32_16x16x32_bf16 v[8:11], v[150:153], v[204:207], v[8:11]
	v_mfma_f32_16x16x32_bf16 v[60:63], v[146:149], v[168:171], v[60:63]
	v_mfma_f32_16x16x32_bf16 v[56:59], v[160:163], v[168:171], v[56:59]
	v_mfma_f32_16x16x32_bf16 v[44:47], v[146:149], v[176:179], v[44:47]
	v_mfma_f32_16x16x32_bf16 v[40:43], v[160:163], v[176:179], v[40:43]
	v_mfma_f32_16x16x32_bf16 v[28:31], v[146:149], v[200:203], v[28:31]
	v_mfma_f32_16x16x32_bf16 v[24:27], v[160:163], v[200:203], v[24:27]
	v_mfma_f32_16x16x32_bf16 v[12:15], v[146:149], v[208:211], v[12:15]
	v_mfma_f32_16x16x32_bf16 v[8:11], v[160:163], v[208:211], v[8:11]
	s_barrier
; #define PG8_STAGE(bufoff, gbase, voff) do { _Pragma("unroll") for (int _i = 0; _i < 2; ++_i) \
;     __builtin_amdgcn_global_load_lds((const unsigned*)((const char*)(gbase) + (voff)[_i]), (LAS unsigned*)(lds + (bufoff) + ldsw + _i * 8192), 16, 0, 0); } while (0)
; #define PG8_LDA(dst, b, h) do { _Pragma("unroll") for (int m = 0; m < 4; ++m) _Pragma("unroll") for (int k = 0; k < 2; ++k) dst[m][k] = *(const LAS bf16x8*)(lds + PG8_SA(b, h) + aoff + m * 2048 + k * 1024); } while (0)
; #define PG8_LDB(dst, b, h) do { _Pragma("unroll") for (int n = 0; n < 2; ++n) _Pragma("unroll") for (int k = 0; k < 2; ++k) dst[n][k] = *(const LAS bf16x8*)(lds + PG8_SB(b, h) + boff + n * 2048 + k * 1024); } while (0)
; #define PG8_WAIT_V(n) asm volatile("s_waitcnt vmcnt(" #n ")" ::: "memory")
; template <class Epi, class Sched>
; DI void gemm_phase(LAS unsigned char* lds, const Gemm g, const Sched& S, const Epi& E) {
;     ...
;     for (int t = 0; t < nt; t += 2) {
;       const bool last = (t == nt - 2);
;       const char* a1 = cA + (size_t)(t + 1) * kstep;
;       const char* a2 = last ? nA : cA + (size_t)(t + 2) * kstep; const char* b2 = last ? nB : cB + (size_t)(t + 2) * kstep;
;       const char* a3 = a2 + kstep; const char* b3 = b2 + kstep;
;       PG8_LDB(B0, 0, 0); PG8_SCHED; PG8_LDA(At, 0, 0); PG8_STAGE(PG8_SA(1, 1), a1 + hstep, voffA);
;       PG8_WAIT_L(8); PG8_BAR; PG8_WAIT_L(0); PG8_MMA(0, 0, At, B0); PG8_BAR; PG8_SCHED;
;       PG8_LDB(B1, 0, 1); PG8_STAGE(PG8_SB(0, 0), b2, voffB);
;       PG8_BAR; PG8_WAIT_L(0); PG8_MMA(0, 1, At, B1); PG8_BAR;
;       PG8_LDA(At, 0, 1); PG8_STAGE(PG8_SA(0, 0), a2, voffA);
;       PG8_BAR; PG8_WAIT_L(0); PG8_MMA(1, 0, At, B0); PG8_BAR; PG8_SCHED;
;       PG8_STAGE(PG8_SB(0, 1), b2 + hstep, voffB);
;       PG8_WAIT_V(6); PG8_BAR; PG8_MMA(1, 1, At, B1); PG8_BAR;
;       PG8_LDB(B0, 1, 0); PG8_SCHED; PG8_LDA(At, 1, 0); PG8_STAGE(PG8_SA(0, 1), a2 + hstep, voffA);
;       PG8_WAIT_L(8); PG8_BAR; PG8_WAIT_L(0); PG8_MMA(0, 0, At, B0); PG8_BAR; PG8_SCHED;
;       PG8_LDB(B1, 1, 1); PG8_STAGE(PG8_SB(1, 0), b3, voffB);
;       PG8_BAR; PG8_WAIT_L(0); PG8_MMA(0, 1, At, B1); PG8_BAR;
;       PG8_LDA(At, 1, 1); PG8_STAGE(PG8_SA(1, 0), a3, voffA);
;       PG8_BAR; PG8_WAIT_L(0); PG8_MMA(1, 0, At, B0); PG8_BAR; PG8_SCHED;
;       PG8_STAGE(PG8_SB(1, 1), b3 + hstep, voffB);
;       PG8_WAIT_V(6); PG8_BAR; PG8_MMA(1, 1, At, B1); PG8_BAR;
;     }
	s_add_u32 s52, s4, 0x40000
	s_addc_u32 s53, s5, 0
	s_add_i32 s51, s54, s34
	v_lshl_add_u64 v[128:129], s[52:53], 0, v[136:137]
	s_mov_b32 m0, s51
	s_nop 0
	global_load_lds_dwordx4 v[128:129], off
	v_lshl_add_u64 v[128:129], s[52:53], 0, v[132:133]
	s_add_i32 m0, s51, 0x2000
	s_nop 0
	global_load_lds_dwordx4 v[128:129], off
	s_waitcnt vmcnt(6)
	s_barrier
	v_mfma_f32_16x16x32_bf16 v[52:55], v[212:215], v[164:167], v[52:55]
	v_mfma_f32_16x16x32_bf16 v[48:51], v[220:223], v[164:167], v[48:51]
	v_mfma_f32_16x16x32_bf16 v[36:39], v[212:215], v[172:175], v[36:39]
	v_mfma_f32_16x16x32_bf16 v[32:35], v[220:223], v[172:175], v[32:35]
	v_mfma_f32_16x16x32_bf16 v[20:23], v[212:215], v[196:199], v[20:23]
	v_mfma_f32_16x16x32_bf16 v[16:19], v[220:223], v[196:199], v[16:19]
	v_mfma_f32_16x16x32_bf16 v[4:7], v[212:215], v[204:207], v[4:7]
	v_mfma_f32_16x16x32_bf16 v[0:3], v[220:223], v[204:207], v[0:3]
	v_mfma_f32_16x16x32_bf16 v[52:55], v[216:219], v[168:171], v[52:55]
	v_mfma_f32_16x16x32_bf16 v[48:51], v[224:227], v[168:171], v[48:51]
	v_mfma_f32_16x16x32_bf16 v[36:39], v[216:219], v[176:179], v[36:39]
	v_mfma_f32_16x16x32_bf16 v[32:35], v[224:227], v[176:179], v[32:35]
	v_mfma_f32_16x16x32_bf16 v[20:23], v[216:219], v[200:203], v[20:23]
	v_mfma_f32_16x16x32_bf16 v[16:19], v[224:227], v[200:203], v[16:19]
	v_mfma_f32_16x16x32_bf16 v[4:7], v[216:219], v[208:211], v[4:7]
	v_mfma_f32_16x16x32_bf16 v[0:3], v[224:227], v[208:211], v[0:3]
	s_add_i32 s51, 0, 0x18000
	v_add_u32_e32 v144, s51, v155
	s_barrier
	ds_read_b128 v[128:131], v144
	ds_read_b128 v[146:149], v144 offset:1024
	ds_read_b128 v[150:153], v144 offset:2048
	ds_read_b128 v[160:163], v144 offset:3072
	s_add_u32 s20, s20, 0x40000
	s_addc_u32 s21, s21, 0
	s_mov_b32 m0, s42
	v_lshl_add_u64 v[212:213], s[20:21], 0, v[138:139]
	ds_read_b128 v[164:167], v158 offset:32768
	ds_read_b128 v[168:171], v158 offset:33792
	ds_read_b128 v[172:175], v158 offset:34816
	ds_read_b128 v[176:179], v158 offset:35840
	ds_read_b128 v[196:199], v158 offset:36864
	ds_read_b128 v[200:203], v158 offset:37888
	ds_read_b128 v[204:207], v158 offset:38912
	ds_read_b128 v[208:211], v158 offset:39936
	global_load_lds_dwordx4 v[212:213], off
	v_lshl_add_u64 v[212:213], s[20:21], 0, v[134:135]
	s_mov_b32 m0, s43
	s_nop 0
	global_load_lds_dwordx4 v[212:213], off
	s_waitcnt lgkmcnt(8)
	s_barrier
	s_waitcnt lgkmcnt(0)
	v_mfma_f32_16x16x32_bf16 v[124:127], v[128:131], v[164:167], v[124:127]
	v_mfma_f32_16x16x32_bf16 v[120:123], v[150:153], v[164:167], v[120:123]
	v_mfma_f32_16x16x32_bf16 v[108:111], v[128:131], v[172:175], v[108:111]
	v_mfma_f32_16x16x32_bf16 v[104:107], v[150:153], v[172:175], v[104:107]
	v_mfma_f32_16x16x32_bf16 v[92:95], v[128:131], v[196:199], v[92:95]
	v_mfma_f32_16x16x32_bf16 v[88:91], v[150:153], v[196:199], v[88:91]
	v_mfma_f32_16x16x32_bf16 v[76:79], v[128:131], v[204:207], v[76:79]
	v_mfma_f32_16x16x32_bf16 v[72:75], v[150:153], v[204:207], v[72:75]
	v_mfma_f32_16x16x32_bf16 v[124:127], v[146:149], v[168:171], v[124:127]
	v_mfma_f32_16x16x32_bf16 v[120:123], v[160:163], v[168:171], v[120:123]
	v_mfma_f32_16x16x32_bf16 v[108:111], v[146:149], v[176:179], v[108:111]
	v_mfma_f32_16x16x32_bf16 v[104:107], v[160:163], v[176:179], v[104:107]
	v_mfma_f32_16x16x32_bf16 v[92:95], v[146:149], v[200:203], v[92:95]
	v_mfma_f32_16x16x32_bf16 v[88:91], v[160:163], v[200:203], v[88:91]
	v_mfma_f32_16x16x32_bf16 v[76:79], v[146:149], v[208:211], v[76:79]
	v_mfma_f32_16x16x32_bf16 v[72:75], v[160:163], v[208:211], v[72:75]
	s_barrier
	s_add_i32 s20, 0, 0x1c000
	s_add_i32 s21, s51, s34
	v_add_u32_e32 v144, s20, v155
	v_lshl_add_u64 v[156:157], v[156:157], 0, s[0:1]
	s_mov_b32 m0, s21
	ds_read_b128 v[212:215], v144
	ds_read_b128 v[216:219], v144 offset:1024
	ds_read_b128 v[220:223], v144 offset:2048
	ds_read_b128 v[224:227], v144 offset:3072
	global_load_lds_dwordx4 v[156:157], off
	v_lshl_add_u64 v[156:157], v[180:181], 0, s[0:1]
	s_add_i32 m0, s21, 0x2000
	s_nop 0
	global_load_lds_dwordx4 v[156:157], off
	s_barrier
	s_waitcnt lgkmcnt(0)
	v_mfma_f32_16x16x32_bf16 v[116:119], v[212:215], v[164:167], v[116:119]
	v_mfma_f32_16x16x32_bf16 v[112:115], v[220:223], v[164:167], v[112:115]
	v_mfma_f32_16x16x32_bf16 v[100:103], v[212:215], v[172:175], v[100:103]
	v_mfma_f32_16x16x32_bf16 v[96:99], v[220:223], v[172:175], v[96:99]
	v_mfma_f32_16x16x32_bf16 v[84:87], v[212:215], v[196:199], v[84:87]
	v_mfma_f32_16x16x32_bf16 v[80:83], v[220:223], v[196:199], v[80:83]
	v_mfma_f32_16x16x32_bf16 v[68:71], v[212:215], v[204:207], v[68:71]
	v_mfma_f32_16x16x32_bf16 v[64:67], v[220:223], v[204:207], v[64:67]
	v_mfma_f32_16x16x32_bf16 v[116:119], v[216:219], v[168:171], v[116:119]
	v_mfma_f32_16x16x32_bf16 v[112:115], v[224:227], v[168:171], v[112:115]
	v_mfma_f32_16x16x32_bf16 v[100:103], v[216:219], v[176:179], v[100:103]
	v_mfma_f32_16x16x32_bf16 v[96:99], v[224:227], v[176:179], v[96:99]
	v_mfma_f32_16x16x32_bf16 v[84:87], v[216:219], v[200:203], v[84:87]
	v_mfma_f32_16x16x32_bf16 v[80:83], v[224:227], v[200:203], v[80:83]
	v_mfma_f32_16x16x32_bf16 v[68:71], v[216:219], v[208:211], v[68:71]
	v_mfma_f32_16x16x32_bf16 v[64:67], v[224:227], v[208:211], v[64:67]
	s_mov_b32 m0, s46
	v_lshl_add_u64 v[156:157], v[228:229], 0, s[0:1]
	s_barrier
; #define PG8_WAIT_V(n) asm volatile("s_waitcnt vmcnt(" #n ")" ::: "memory")
; template <class Epi, class Sched>
; DI void gemm_phase(LAS unsigned char* lds, const Gemm g, const Sched& S, const Epi& E) {
;     ...
;     for (int t = 0; t < nt; t += 2) {
;       const bool last = (t == nt - 2);
;       const char* a1 = cA + (size_t)(t + 1) * kstep;
;       const char* a2 = last ? nA : cA + (size_t)(t + 2) * kstep; const char* b2 = last ? nB : cB + (size_t)(t + 2) * kstep;
;       const char* a3 = a2 + kstep; const char* b3 = b2 + kstep;
;       PG8_LDB(B0, 0, 0); PG8_SCHED; PG8_LDA(At, 0, 0); PG8_STAGE(PG8_SA(1, 1), a1 + hstep, voffA);
;       PG8_WAIT_L(8); PG8_BAR; PG8_WAIT_L(0); PG8_MMA(0, 0, At, B0); PG8_BAR; PG8_SCHED;
;       PG8_LDB(B1, 0, 1); PG8_STAGE(PG8_SB(0, 0), b2, voffB);
;       PG8_BAR; PG8_WAIT_L(0); PG8_MMA(0, 1, At, B1); PG8_BAR;
;       PG8_LDA(At, 0, 1); PG8_STAGE(PG8_SA(0, 0), a2, voffA);
;       PG8_BAR; PG8_WAIT_L(0); PG8_MMA(1, 0, At, B0); PG8_BAR; PG8_SCHED;
;       PG8_STAGE(PG8_SB(0, 1), b2 + hstep, voffB);
;       PG8_WAIT_V(6); PG8_BAR; PG8_MMA(1, 1, At, B1); PG8_BAR;
;       PG8_LDB(B0, 1, 0); PG8_SCHED; PG8_LDA(At, 1, 0); PG8_STAGE(PG8_SA(0, 1), a2 + hstep, voffA);
;       PG8_WAIT_L(8); PG8_BAR; PG8_WAIT_L(0); PG8_MMA(0, 0, At, B0); PG8_BAR; PG8_SCHED;
;       PG8_LDB(B1, 1, 1); PG8_STAGE(PG8_SB(1, 0), b3, voffB);
;       PG8_BAR; PG8_WAIT_L(0); PG8_MMA(0, 1, At, B1); PG8_BAR;
;       PG8_LDA(At, 1, 1); PG8_STAGE(PG8_SA(1, 0), a3, voffA);
;       PG8_BAR; PG8_WAIT_L(0); PG8_MMA(1, 0, At, B0); PG8_BAR; PG8_SCHED;
;       PG8_STAGE(PG8_SB(1, 1), b3 + hstep, voffB);
;       PG8_WAIT_V(6); PG8_BAR; PG8_MMA(1, 1, At, B1); PG8_BAR;
;     }
;   DI void operator()(const f32x4 (&acc)[2][2][4][2], const pg8::Unit& u, int wr, int wc, int fr_, int fq_) const {
;     ...
;             } else if (EPI == EPI_CIN) {
;               if (n == 0) {
;                 const int gb = u.pn * 256 + bj * 128 + wc * 32;
;                 const int f8 = gb + 8 * fq;
;                 const f32x4 v1 = acc[ai][bj][m][1];
;                 if (gb < 1024) st_bf8((u16*)(big + O_QD) + (size_t)token * 1024 + f8, v, v1, rinv * (0.125f * LOG2E));
;                 else if (gb < 2048) st_bf8((u16*)(big + O_KD) + (size_t)token * 1024 + (f8 - 1024), v, v1, rinv);
;                 else st_bf8((u16*)(big + O_VDT) + (size_t)token * 1024 + (f8 - 2048), v, v1, rinv);
;               }
	ds_read_b128 v[164:167], v158 offset:49152
	ds_read_b128 v[168:171], v158 offset:50176
	ds_read_b128 v[172:175], v158 offset:51200
	ds_read_b128 v[176:179], v158 offset:52224
	ds_read_b128 v[196:199], v158 offset:53248
	ds_read_b128 v[200:203], v158 offset:54272
	ds_read_b128 v[204:207], v158 offset:55296
	ds_read_b128 v[208:211], v158 offset:56320
	global_load_lds_dwordx4 v[156:157], off
	v_lshl_add_u64 v[156:157], v[230:231], 0, s[0:1]
	s_mov_b32 m0, s47
	s_nop 0
	global_load_lds_dwordx4 v[156:157], off
	s_barrier
	s_waitcnt lgkmcnt(0)
	v_mfma_f32_16x16x32_bf16 v[60:63], v[128:131], v[164:167], v[60:63]
	v_mfma_f32_16x16x32_bf16 v[56:59], v[150:153], v[164:167], v[56:59]
	v_mfma_f32_16x16x32_bf16 v[44:47], v[128:131], v[172:175], v[44:47]
	v_mfma_f32_16x16x32_bf16 v[40:43], v[150:153], v[172:175], v[40:43]
	v_mfma_f32_16x16x32_bf16 v[28:31], v[128:131], v[196:199], v[28:31]
	v_mfma_f32_16x16x32_bf16 v[24:27], v[150:153], v[196:199], v[24:27]
	v_mfma_f32_16x16x32_bf16 v[12:15], v[128:131], v[204:207], v[12:15]
	v_mfma_f32_16x16x32_bf16 v[8:11], v[150:153], v[204:207], v[8:11]
	v_mfma_f32_16x16x32_bf16 v[60:63], v[146:149], v[168:171], v[60:63]
	v_mfma_f32_16x16x32_bf16 v[56:59], v[160:163], v[168:171], v[56:59]
	v_mfma_f32_16x16x32_bf16 v[44:47], v[146:149], v[176:179], v[44:47]
	v_mfma_f32_16x16x32_bf16 v[40:43], v[160:163], v[176:179], v[40:43]
	v_mfma_f32_16x16x32_bf16 v[28:31], v[146:149], v[200:203], v[28:31]
	v_mfma_f32_16x16x32_bf16 v[24:27], v[160:163], v[200:203], v[24:27]
	v_mfma_f32_16x16x32_bf16 v[12:15], v[146:149], v[208:211], v[12:15]
	v_mfma_f32_16x16x32_bf16 v[8:11], v[160:163], v[208:211], v[8:11]
	s_barrier
	s_add_u32 s4, s4, 0x40080
	s_addc_u32 s5, s5, 0
	s_add_i32 s20, s20, s34
	v_lshl_add_u64 v[128:129], s[4:5], 0, v[136:137]
	s_mov_b32 m0, s20
	s_nop 0
	global_load_lds_dwordx4 v[128:129], off
	v_lshl_add_u64 v[128:129], s[4:5], 0, v[132:133]
	s_add_i32 m0, s20, 0x2000
	s_nop 0
	global_load_lds_dwordx4 v[128:129], off
	s_waitcnt vmcnt(6)
	s_barrier
	v_mfma_f32_16x16x32_bf16 v[52:55], v[212:215], v[164:167], v[52:55]
	v_mfma_f32_16x16x32_bf16 v[48:51], v[220:223], v[164:167], v[48:51]
	v_mfma_f32_16x16x32_bf16 v[36:39], v[212:215], v[172:175], v[36:39]
	v_mfma_f32_16x16x32_bf16 v[32:35], v[220:223], v[172:175], v[32:35]
	v_mfma_f32_16x16x32_bf16 v[20:23], v[212:215], v[196:199], v[20:23]
	v_mfma_f32_16x16x32_bf16 v[16:19], v[220:223], v[196:199], v[16:19]
	v_mfma_f32_16x16x32_bf16 v[4:7], v[212:215], v[204:207], v[4:7]
	v_mfma_f32_16x16x32_bf16 v[0:3], v[220:223], v[204:207], v[0:3]
	v_mfma_f32_16x16x32_bf16 v[52:55], v[216:219], v[168:171], v[52:55]
	v_mfma_f32_16x16x32_bf16 v[48:51], v[224:227], v[168:171], v[48:51]
	v_mfma_f32_16x16x32_bf16 v[36:39], v[216:219], v[176:179], v[36:39]
	v_mfma_f32_16x16x32_bf16 v[32:35], v[224:227], v[176:179], v[32:35]
	v_mfma_f32_16x16x32_bf16 v[20:23], v[216:219], v[200:203], v[20:23]
	v_mfma_f32_16x16x32_bf16 v[16:19], v[224:227], v[200:203], v[16:19]
	v_mfma_f32_16x16x32_bf16 v[4:7], v[216:219], v[208:211], v[4:7]
	v_mfma_f32_16x16x32_bf16 v[0:3], v[224:227], v[208:211], v[0:3]
	s_add_i32 s50, s50, 2
	s_add_u32 s2, s2, 0x100
	s_addc_u32 s3, s3, 0
	s_add_u32 s37, s37, 0x100
	s_addc_u32 s49, s49, 0
	s_cmp_gt_u32 s50, 13
	s_barrier
	s_cbranch_scc0 .LBB0_370
	v_mov_b32_e32 v128, v182
	s_lshl_b32 s2, s22, 10
	v_and_or_b32 v160, v128, 15, s44
	v_lshrrev_b32_e32 v128, 1, v128
	s_add_i32 s2, s2, 0
	v_and_b32_e32 v146, 24, v128
	v_lshl_add_u32 v128, v160, 2, s2
	v_add_u32_e32 v159, 0x20000, v128
	s_lshl_b32 s13, s28, 8
	s_lshl_b32 s3, s23, 8
	ds_read_b32 v154, v159
	v_add_u32_e32 v150, s13, v160
	s_or_b32 s20, s3, s45
	v_ashrrev_i32_e32 v151, 31, v150
	s_cmpk_gt_i32 s20, 0x3ff
	v_lshlrev_b64 v[128:129], 11, v[150:151]
	v_or_b32_e32 v148, s20, v146
	s_cselect_b64 s[4:5], -1, 0
	s_cmpk_gt_u32 s3, 0x7ff
	s_cselect_b64 s[2:3], -1, 0
	v_mov_b32_e32 v144, v148
	v_lshl_add_u64 v[152:153], s[10:11], 0, v[128:129]
	s_mov_b64 s[22:23], -1
	s_and_b64 vcc, exec, s[4:5]
	s_cbranch_vccz .LBB0_377
	s_waitcnt lgkmcnt(0)
	v_pk_mul_f32 v[128:129], v[124:125], v[154:155] op_sel_hi:[1,0]
	v_pk_mul_f32 v[130:131], v[126:127], v[154:155] op_sel_hi:[1,0]
	v_cvt_pk_bf16_f32 v128, v128, v129
	v_cvt_pk_bf16_f32 v129, v130, v131
	v_pk_mul_f32 v[130:131], v[120:121], v[154:155] op_sel_hi:[1,0]
	v_pk_mul_f32 v[162:163], v[122:123], v[154:155] op_sel_hi:[1,0]
	v_lshl_add_u64 v[156:157], v[144:145], 1, v[152:153]
	v_cvt_pk_bf16_f32 v130, v130, v131
	v_cvt_pk_bf16_f32 v131, v162, v163
	s_and_b64 vcc, exec, s[2:3]
	s_cbranch_vccz .LBB0_374
	v_add_co_u32_e32 v162, vcc, 0x7fff000, v156
	s_mov_b64 s[22:23], 0
	s_nop 0
	v_addc_co_u32_e32 v163, vcc, 0, v157, vcc
	global_store_dwordx4 v[162:163], v[128:131], off

; #define PG8_STAGE(bufoff, gbase, voff) do { _Pragma("unroll") for (int _i = 0; _i < 2; ++_i) \
;     __builtin_amdgcn_global_load_lds((const unsigned*)((const char*)(gbase) + (voff)[_i]), (LAS unsigned*)(lds + (bufoff) + ldsw + _i * 8192), 16, 0, 0); } while (0)
; #define PG8_LDA(dst, b, h) do { _Pragma("unroll") for (int m = 0; m < 4; ++m) _Pragma("unroll") for (int k = 0; k < 2; ++k) dst[m][k] = *(const LAS bf16x8*)(lds + PG8_SA(b, h) + aoff + m * 2048 + k * 1024); } while (0)
; #define PG8_LDB(dst, b, h) do { _Pragma("unroll") for (int n = 0; n < 2; ++n) _Pragma("unroll") for (int k = 0; k < 2; ++k) dst[n][k] = *(const LAS bf16x8*)(lds + PG8_SB(b, h) + boff + n * 2048 + k * 1024); } while (0)
; #define PG8_WAIT_V(n) asm volatile("s_waitcnt vmcnt(" #n ")" ::: "memory")
; template <class Epi, class Sched>
; DI void gemm_phase(LAS unsigned char* lds, const Gemm g, const Sched& S, const Epi& E) {
;     ...
;     for (int t = 0; t < nt; t += 2) {
;       const bool last = (t == nt - 2);
;       const char* a1 = cA + (size_t)(t + 1) * kstep;
;       const char* a2 = last ? nA : cA + (size_t)(t + 2) * kstep; const char* b2 = last ? nB : cB + (size_t)(t + 2) * kstep;
;       const char* a3 = a2 + kstep; const char* b3 = b2 + kstep;
;       PG8_LDB(B0, 0, 0); PG8_SCHED; PG8_LDA(At, 0, 0); PG8_STAGE(PG8_SA(1, 1), a1 + hstep, voffA);
;       PG8_WAIT_L(8); PG8_BAR; PG8_WAIT_L(0); PG8_MMA(0, 0, At, B0); PG8_BAR; PG8_SCHED;
;       PG8_LDB(B1, 0, 1); PG8_STAGE(PG8_SB(0, 0), b2, voffB);
;       PG8_BAR; PG8_WAIT_L(0); PG8_MMA(0, 1, At, B1); PG8_BAR;
;       PG8_LDA(At, 0, 1); PG8_STAGE(PG8_SA(0, 0), a2, voffA);
;       PG8_BAR; PG8_WAIT_L(0); PG8_MMA(1, 0, At, B0); PG8_BAR; PG8_SCHED;
;       PG8_STAGE(PG8_SB(0, 1), b2 + hstep, voffB);
;       PG8_WAIT_V(6); PG8_BAR; PG8_MMA(1, 1, At, B1); PG8_BAR;
;       PG8_LDB(B0, 1, 0); PG8_SCHED; PG8_LDA(At, 1, 0); PG8_STAGE(PG8_SA(0, 1), a2 + hstep, voffA);
;       PG8_WAIT_L(8); PG8_BAR; PG8_WAIT_L(0); PG8_MMA(0, 0, At, B0); PG8_BAR; PG8_SCHED;
;       PG8_LDB(B1, 1, 1); PG8_STAGE(PG8_SB(1, 0), b3, voffB);
;       PG8_BAR; PG8_WAIT_L(0); PG8_MMA(0, 1, At, B1); PG8_BAR;
;       PG8_LDA(At, 1, 1); PG8_STAGE(PG8_SA(1, 0), a3, voffA);
;       PG8_BAR; PG8_WAIT_L(0); PG8_MMA(1, 0, At, B0); PG8_BAR; PG8_SCHED;
;       PG8_STAGE(PG8_SB(1, 1), b3 + hstep, voffB);
;       PG8_WAIT_V(6); PG8_BAR; PG8_MMA(1, 1, At, B1); PG8_BAR;
;     }
.LBB0_689:
	s_add_u32 s22, s20, 0xfffc0080
	s_addc_u32 s23, s21, -1
	s_add_i32 s42, 0, 0x10000
	v_add_u32_e32 v144, s42, v196
	ds_read_b128 v[128:131], v144
	ds_read_b128 v[132:135], v144 offset:1024
	ds_read_b128 v[150:153], v144 offset:2048
	ds_read_b128 v[154:157], v144 offset:3072
	s_cmp_eq_u32 s41, 12
	s_cselect_b32 s29, s13, s23
	s_cselect_b32 s28, s37, s22
	s_cselect_b32 s23, s15, s40
	s_cselect_b32 s22, s38, s39
	v_lshl_add_u64 v[206:207], s[20:21], 0, v[146:147]
	s_add_i32 m0, s56, 0xc000
	ds_read_b128 v[158:161], v197
	ds_read_b128 v[162:165], v197 offset:1024
	ds_read_b128 v[166:169], v197 offset:2048
	ds_read_b128 v[170:173], v197 offset:3072
	ds_read_b128 v[174:177], v197 offset:4096
	ds_read_b128 v[178:181], v197 offset:5120
	ds_read_b128 v[198:201], v197 offset:6144
	ds_read_b128 v[202:205], v197 offset:7168
	global_load_lds_dwordx4 v[206:207], off
	v_lshl_add_u64 v[206:207], s[20:21], 0, v[148:149]
	s_add_i32 m0, s56, 0xe000
	s_nop 0
	global_load_lds_dwordx4 v[206:207], off
	s_waitcnt lgkmcnt(8)
	s_barrier
	s_waitcnt lgkmcnt(0)
	v_mfma_f32_16x16x32_bf16 v[124:127], v[128:131], v[158:161], v[124:127]
	v_mfma_f32_16x16x32_bf16 v[120:123], v[150:153], v[158:161], v[120:123]
	v_mfma_f32_16x16x32_bf16 v[108:111], v[128:131], v[166:169], v[108:111]
	v_mfma_f32_16x16x32_bf16 v[104:107], v[150:153], v[166:169], v[104:107]
	v_mfma_f32_16x16x32_bf16 v[92:95], v[128:131], v[174:177], v[92:95]
	v_mfma_f32_16x16x32_bf16 v[88:91], v[150:153], v[174:177], v[88:91]
	v_mfma_f32_16x16x32_bf16 v[76:79], v[128:131], v[198:201], v[76:79]
	v_mfma_f32_16x16x32_bf16 v[72:75], v[150:153], v[198:201], v[72:75]
	v_mfma_f32_16x16x32_bf16 v[124:127], v[132:135], v[162:165], v[124:127]
	v_mfma_f32_16x16x32_bf16 v[120:123], v[154:157], v[162:165], v[120:123]
	v_mfma_f32_16x16x32_bf16 v[108:111], v[132:135], v[170:173], v[108:111]
	v_mfma_f32_16x16x32_bf16 v[104:107], v[154:157], v[170:173], v[104:107]
	v_mfma_f32_16x16x32_bf16 v[92:95], v[132:135], v[178:181], v[92:95]
	v_mfma_f32_16x16x32_bf16 v[88:91], v[154:157], v[178:181], v[88:91]
	v_mfma_f32_16x16x32_bf16 v[76:79], v[132:135], v[202:205], v[76:79]
	v_mfma_f32_16x16x32_bf16 v[72:75], v[154:157], v[202:205], v[72:75]
	s_barrier
	s_add_i32 s44, 0, 0x14000
	s_add_i32 s42, s42, s52
	v_add_u32_e32 v144, s44, v196
	v_lshl_add_u64 v[222:223], s[22:23], 0, v[140:141]
	s_mov_b32 m0, s42
	ds_read_b128 v[206:209], v144
	ds_read_b128 v[210:213], v144 offset:1024
	ds_read_b128 v[214:217], v144 offset:2048
	ds_read_b128 v[218:221], v144 offset:3072
	global_load_lds_dwordx4 v[222:223], off
	v_lshl_add_u64 v[224:225], s[22:23], 0, v[136:137]
	s_add_i32 m0, s42, 0x2000
	s_nop 0
	global_load_lds_dwordx4 v[224:225], off
	s_barrier
	s_waitcnt lgkmcnt(0)
	v_mfma_f32_16x16x32_bf16 v[116:119], v[206:209], v[158:161], v[116:119]
	v_mfma_f32_16x16x32_bf16 v[112:115], v[214:217], v[158:161], v[112:115]
	v_mfma_f32_16x16x32_bf16 v[100:103], v[206:209], v[166:169], v[100:103]
	v_mfma_f32_16x16x32_bf16 v[96:99], v[214:217], v[166:169], v[96:99]
	v_mfma_f32_16x16x32_bf16 v[84:87], v[206:209], v[174:177], v[84:87]
	v_mfma_f32_16x16x32_bf16 v[80:83], v[214:217], v[174:177], v[80:83]
	v_mfma_f32_16x16x32_bf16 v[68:71], v[206:209], v[198:201], v[68:71]
	v_mfma_f32_16x16x32_bf16 v[64:67], v[214:217], v[198:201], v[64:67]
	v_mfma_f32_16x16x32_bf16 v[116:119], v[210:213], v[162:165], v[116:119]
	v_mfma_f32_16x16x32_bf16 v[112:115], v[218:221], v[162:165], v[112:115]
	v_mfma_f32_16x16x32_bf16 v[100:103], v[210:213], v[170:173], v[100:103]
	v_mfma_f32_16x16x32_bf16 v[96:99], v[218:221], v[170:173], v[96:99]
	v_mfma_f32_16x16x32_bf16 v[84:87], v[210:213], v[178:181], v[84:87]
	v_mfma_f32_16x16x32_bf16 v[80:83], v[218:221], v[178:181], v[80:83]
	v_mfma_f32_16x16x32_bf16 v[68:71], v[210:213], v[202:205], v[68:71]
	v_mfma_f32_16x16x32_bf16 v[64:67], v[218:221], v[202:205], v[64:67]
	s_mov_b32 m0, s56
	v_lshl_add_u64 v[226:227], s[28:29], 0, v[142:143]
	s_barrier
	ds_read_b128 v[158:161], v197 offset:16384
	ds_read_b128 v[162:165], v197 offset:17408
	ds_read_b128 v[166:169], v197 offset:18432
	ds_read_b128 v[170:173], v197 offset:19456
	ds_read_b128 v[174:177], v197 offset:20480
	ds_read_b128 v[178:181], v197 offset:21504
	ds_read_b128 v[198:201], v197 offset:22528
	ds_read_b128 v[202:205], v197 offset:23552
	global_load_lds_dwordx4 v[226:227], off
	v_lshl_add_u64 v[228:229], s[28:29], 0, v[138:139]
	s_mov_b32 m0, s57
	s_nop 0
	global_load_lds_dwordx4 v[228:229], off
	s_barrier
	s_waitcnt lgkmcnt(0)
	v_mfma_f32_16x16x32_bf16 v[60:63], v[128:131], v[158:161], v[60:63]
	v_mfma_f32_16x16x32_bf16 v[56:59], v[150:153], v[158:161], v[56:59]
	v_mfma_f32_16x16x32_bf16 v[44:47], v[128:131], v[166:169], v[44:47]
	v_mfma_f32_16x16x32_bf16 v[40:43], v[150:153], v[166:169], v[40:43]
	v_mfma_f32_16x16x32_bf16 v[28:31], v[128:131], v[174:177], v[28:31]
	v_mfma_f32_16x16x32_bf16 v[24:27], v[150:153], v[174:177], v[24:27]
	v_mfma_f32_16x16x32_bf16 v[12:15], v[128:131], v[198:201], v[12:15]
	v_mfma_f32_16x16x32_bf16 v[8:11], v[150:153], v[198:201], v[8:11]
	v_mfma_f32_16x16x32_bf16 v[60:63], v[132:135], v[162:165], v[60:63]
	v_mfma_f32_16x16x32_bf16 v[56:59], v[154:157], v[162:165], v[56:59]
	v_mfma_f32_16x16x32_bf16 v[44:47], v[132:135], v[170:173], v[44:47]
	v_mfma_f32_16x16x32_bf16 v[40:43], v[154:157], v[170:173], v[40:43]
	v_mfma_f32_16x16x32_bf16 v[28:31], v[132:135], v[178:181], v[28:31]
	v_mfma_f32_16x16x32_bf16 v[24:27], v[154:157], v[178:181], v[24:27]
	v_mfma_f32_16x16x32_bf16 v[12:15], v[132:135], v[202:205], v[12:15]
	v_mfma_f32_16x16x32_bf16 v[8:11], v[154:157], v[202:205], v[8:11]
	s_barrier
; #define PG8_STAGE(bufoff, gbase, voff) do { _Pragma("unroll") for (int _i = 0; _i < 2; ++_i) \
;     __builtin_amdgcn_global_load_lds((const unsigned*)((const char*)(gbase) + (voff)[_i]), (LAS unsigned*)(lds + (bufoff) + ldsw + _i * 8192), 16, 0, 0); } while (0)
; #define PG8_LDA(dst, b, h) do { _Pragma("unroll") for (int m = 0; m < 4; ++m) _Pragma("unroll") for (int k = 0; k < 2; ++k) dst[m][k] = *(const LAS bf16x8*)(lds + PG8_SA(b, h) + aoff + m * 2048 + k * 1024); } while (0)
; #define PG8_LDB(dst, b, h) do { _Pragma("unroll") for (int n = 0; n < 2; ++n) _Pragma("unroll") for (int k = 0; k < 2; ++k) dst[n][k] = *(const LAS bf16x8*)(lds + PG8_SB(b, h) + boff + n * 2048 + k * 1024); } while (0)
; #define PG8_WAIT_V(n) asm volatile("s_waitcnt vmcnt(" #n ")" ::: "memory")
; template <class Epi, class Sched>
; DI void gemm_phase(LAS unsigned char* lds, const Gemm g, const Sched& S, const Epi& E) {
;     ...
;     for (int t = 0; t < nt; t += 2) {
;       const bool last = (t == nt - 2);
;       const char* a1 = cA + (size_t)(t + 1) * kstep;
;       const char* a2 = last ? nA : cA + (size_t)(t + 2) * kstep; const char* b2 = last ? nB : cB + (size_t)(t + 2) * kstep;
;       const char* a3 = a2 + kstep; const char* b3 = b2 + kstep;
;       PG8_LDB(B0, 0, 0); PG8_SCHED; PG8_LDA(At, 0, 0); PG8_STAGE(PG8_SA(1, 1), a1 + hstep, voffA);
;       PG8_WAIT_L(8); PG8_BAR; PG8_WAIT_L(0); PG8_MMA(0, 0, At, B0); PG8_BAR; PG8_SCHED;
;       PG8_LDB(B1, 0, 1); PG8_STAGE(PG8_SB(0, 0), b2, voffB);
;       PG8_BAR; PG8_WAIT_L(0); PG8_MMA(0, 1, At, B1); PG8_BAR;
;       PG8_LDA(At, 0, 1); PG8_STAGE(PG8_SA(0, 0), a2, voffA);
;       PG8_BAR; PG8_WAIT_L(0); PG8_MMA(1, 0, At, B0); PG8_BAR; PG8_SCHED;
;       PG8_STAGE(PG8_SB(0, 1), b2 + hstep, voffB);
;       PG8_WAIT_V(6); PG8_BAR; PG8_MMA(1, 1, At, B1); PG8_BAR;
;       PG8_LDB(B0, 1, 0); PG8_SCHED; PG8_LDA(At, 1, 0); PG8_STAGE(PG8_SA(0, 1), a2 + hstep, voffA);
;       PG8_WAIT_L(8); PG8_BAR; PG8_WAIT_L(0); PG8_MMA(0, 0, At, B0); PG8_BAR; PG8_SCHED;
;       PG8_LDB(B1, 1, 1); PG8_STAGE(PG8_SB(1, 0), b3, voffB);
;       PG8_BAR; PG8_WAIT_L(0); PG8_MMA(0, 1, At, B1); PG8_BAR;
;       PG8_LDA(At, 1, 1); PG8_STAGE(PG8_SA(1, 0), a3, voffA);
;       PG8_BAR; PG8_WAIT_L(0); PG8_MMA(1, 0, At, B0); PG8_BAR; PG8_SCHED;
;       PG8_STAGE(PG8_SB(1, 1), b3 + hstep, voffB);
;       PG8_WAIT_V(6); PG8_BAR; PG8_MMA(1, 1, At, B1); PG8_BAR;
;     }
	s_add_u32 s42, s22, 0x40000
	s_addc_u32 s43, s23, 0
	s_add_i32 s44, s44, s52
	v_lshl_add_u64 v[128:129], s[42:43], 0, v[140:141]
	s_mov_b32 m0, s44
	s_nop 0
	global_load_lds_dwordx4 v[128:129], off
	v_lshl_add_u64 v[128:129], s[42:43], 0, v[136:137]
	s_add_i32 m0, s44, 0x2000
	s_nop 0
	global_load_lds_dwordx4 v[128:129], off
	s_waitcnt vmcnt(6)
	s_barrier
	v_mfma_f32_16x16x32_bf16 v[52:55], v[206:209], v[158:161], v[52:55]
	v_mfma_f32_16x16x32_bf16 v[48:51], v[214:217], v[158:161], v[48:51]
	v_mfma_f32_16x16x32_bf16 v[36:39], v[206:209], v[166:169], v[36:39]
	v_mfma_f32_16x16x32_bf16 v[32:35], v[214:217], v[166:169], v[32:35]
	v_mfma_f32_16x16x32_bf16 v[20:23], v[206:209], v[174:177], v[20:23]
	v_mfma_f32_16x16x32_bf16 v[16:19], v[214:217], v[174:177], v[16:19]
	v_mfma_f32_16x16x32_bf16 v[4:7], v[206:209], v[198:201], v[4:7]
	v_mfma_f32_16x16x32_bf16 v[0:3], v[214:217], v[198:201], v[0:3]
	v_mfma_f32_16x16x32_bf16 v[52:55], v[210:213], v[162:165], v[52:55]
	v_mfma_f32_16x16x32_bf16 v[48:51], v[218:221], v[162:165], v[48:51]
	v_mfma_f32_16x16x32_bf16 v[36:39], v[210:213], v[170:173], v[36:39]
	v_mfma_f32_16x16x32_bf16 v[32:35], v[218:221], v[170:173], v[32:35]
	v_mfma_f32_16x16x32_bf16 v[20:23], v[210:213], v[178:181], v[20:23]
	v_mfma_f32_16x16x32_bf16 v[16:19], v[218:221], v[178:181], v[16:19]
	v_mfma_f32_16x16x32_bf16 v[4:7], v[210:213], v[202:205], v[4:7]
	v_mfma_f32_16x16x32_bf16 v[0:3], v[218:221], v[202:205], v[0:3]
	s_add_i32 s42, 0, 0x18000
	v_add_u32_e32 v144, s42, v196
	s_barrier
	ds_read_b128 v[128:131], v144
	ds_read_b128 v[132:135], v144 offset:1024
	ds_read_b128 v[150:153], v144 offset:2048
	ds_read_b128 v[154:157], v144 offset:3072
	s_add_u32 s28, s28, 0x40000
	s_addc_u32 s29, s29, 0
	s_mov_b32 m0, s58
	v_lshl_add_u64 v[206:207], s[28:29], 0, v[142:143]
	ds_read_b128 v[158:161], v197 offset:32768
	ds_read_b128 v[162:165], v197 offset:33792
	ds_read_b128 v[166:169], v197 offset:34816
	ds_read_b128 v[170:173], v197 offset:35840
	ds_read_b128 v[174:177], v197 offset:36864
	ds_read_b128 v[178:181], v197 offset:37888
	ds_read_b128 v[198:201], v197 offset:38912
	ds_read_b128 v[202:205], v197 offset:39936
	global_load_lds_dwordx4 v[206:207], off
	v_lshl_add_u64 v[206:207], s[28:29], 0, v[138:139]
	s_mov_b32 m0, s59
	s_nop 0
	global_load_lds_dwordx4 v[206:207], off
	s_waitcnt lgkmcnt(8)
	s_barrier
	s_waitcnt lgkmcnt(0)
	v_mfma_f32_16x16x32_bf16 v[124:127], v[128:131], v[158:161], v[124:127]
	v_mfma_f32_16x16x32_bf16 v[120:123], v[150:153], v[158:161], v[120:123]
	v_mfma_f32_16x16x32_bf16 v[108:111], v[128:131], v[166:169], v[108:111]
	v_mfma_f32_16x16x32_bf16 v[104:107], v[150:153], v[166:169], v[104:107]
	v_mfma_f32_16x16x32_bf16 v[92:95], v[128:131], v[174:177], v[92:95]
	v_mfma_f32_16x16x32_bf16 v[88:91], v[150:153], v[174:177], v[88:91]
	v_mfma_f32_16x16x32_bf16 v[76:79], v[128:131], v[198:201], v[76:79]
	v_mfma_f32_16x16x32_bf16 v[72:75], v[150:153], v[198:201], v[72:75]
	v_mfma_f32_16x16x32_bf16 v[124:127], v[132:135], v[162:165], v[124:127]
	v_mfma_f32_16x16x32_bf16 v[120:123], v[154:157], v[162:165], v[120:123]
	v_mfma_f32_16x16x32_bf16 v[108:111], v[132:135], v[170:173], v[108:111]
	v_mfma_f32_16x16x32_bf16 v[104:107], v[154:157], v[170:173], v[104:107]
	v_mfma_f32_16x16x32_bf16 v[92:95], v[132:135], v[178:181], v[92:95]
	v_mfma_f32_16x16x32_bf16 v[88:91], v[154:157], v[178:181], v[88:91]
	v_mfma_f32_16x16x32_bf16 v[76:79], v[132:135], v[202:205], v[76:79]
	v_mfma_f32_16x16x32_bf16 v[72:75], v[154:157], v[202:205], v[72:75]
	s_barrier
	s_add_i32 s28, 0, 0x1c000
	s_add_i32 s29, s42, s52
	v_add_u32_e32 v144, s28, v196
	v_lshl_add_u64 v[222:223], v[222:223], 0, s[0:1]
	s_mov_b32 m0, s29
	ds_read_b128 v[206:209], v144
	ds_read_b128 v[210:213], v144 offset:1024
	ds_read_b128 v[214:217], v144 offset:2048
	ds_read_b128 v[218:221], v144 offset:3072
	global_load_lds_dwordx4 v[222:223], off
	v_lshl_add_u64 v[222:223], v[224:225], 0, s[0:1]
	s_add_i32 m0, s29, 0x2000
	s_nop 0
	global_load_lds_dwordx4 v[222:223], off
	s_barrier
	s_waitcnt lgkmcnt(0)
	v_mfma_f32_16x16x32_bf16 v[116:119], v[206:209], v[158:161], v[116:119]
	v_mfma_f32_16x16x32_bf16 v[112:115], v[214:217], v[158:161], v[112:115]
	v_mfma_f32_16x16x32_bf16 v[100:103], v[206:209], v[166:169], v[100:103]
	v_mfma_f32_16x16x32_bf16 v[96:99], v[214:217], v[166:169], v[96:99]
	v_mfma_f32_16x16x32_bf16 v[84:87], v[206:209], v[174:177], v[84:87]
	v_mfma_f32_16x16x32_bf16 v[80:83], v[214:217], v[174:177], v[80:83]
	v_mfma_f32_16x16x32_bf16 v[68:71], v[206:209], v[198:201], v[68:71]
	v_mfma_f32_16x16x32_bf16 v[64:67], v[214:217], v[198:201], v[64:67]
	v_mfma_f32_16x16x32_bf16 v[116:119], v[210:213], v[162:165], v[116:119]
	v_mfma_f32_16x16x32_bf16 v[112:115], v[218:221], v[162:165], v[112:115]
	v_mfma_f32_16x16x32_bf16 v[100:103], v[210:213], v[170:173], v[100:103]
	v_mfma_f32_16x16x32_bf16 v[96:99], v[218:221], v[170:173], v[96:99]
	v_mfma_f32_16x16x32_bf16 v[84:87], v[210:213], v[178:181], v[84:87]
	v_mfma_f32_16x16x32_bf16 v[80:83], v[218:221], v[178:181], v[80:83]
	v_mfma_f32_16x16x32_bf16 v[68:71], v[210:213], v[202:205], v[68:71]
	v_mfma_f32_16x16x32_bf16 v[64:67], v[218:221], v[202:205], v[64:67]
	s_mov_b32 m0, s62
	v_lshl_add_u64 v[222:223], v[226:227], 0, s[0:1]
	s_barrier
; #define PG8_WAIT_V(n) asm volatile("s_waitcnt vmcnt(" #n ")" ::: "memory")
; template <class Epi, class Sched>
; DI void gemm_phase(LAS unsigned char* lds, const Gemm g, const Sched& S, const Epi& E) {
;     ...
;     for (int t = 0; t < nt; t += 2) {
;       const bool last = (t == nt - 2);
;       const char* a1 = cA + (size_t)(t + 1) * kstep;
;       const char* a2 = last ? nA : cA + (size_t)(t + 2) * kstep; const char* b2 = last ? nB : cB + (size_t)(t + 2) * kstep;
;       const char* a3 = a2 + kstep; const char* b3 = b2 + kstep;
;       PG8_LDB(B0, 0, 0); PG8_SCHED; PG8_LDA(At, 0, 0); PG8_STAGE(PG8_SA(1, 1), a1 + hstep, voffA);
;       PG8_WAIT_L(8); PG8_BAR; PG8_WAIT_L(0); PG8_MMA(0, 0, At, B0); PG8_BAR; PG8_SCHED;
;       PG8_LDB(B1, 0, 1); PG8_STAGE(PG8_SB(0, 0), b2, voffB);
;       PG8_BAR; PG8_WAIT_L(0); PG8_MMA(0, 1, At, B1); PG8_BAR;
;       PG8_LDA(At, 0, 1); PG8_STAGE(PG8_SA(0, 0), a2, voffA);
;       PG8_BAR; PG8_WAIT_L(0); PG8_MMA(1, 0, At, B0); PG8_BAR; PG8_SCHED;
;       PG8_STAGE(PG8_SB(0, 1), b2 + hstep, voffB);
;       PG8_WAIT_V(6); PG8_BAR; PG8_MMA(1, 1, At, B1); PG8_BAR;
;       PG8_LDB(B0, 1, 0); PG8_SCHED; PG8_LDA(At, 1, 0); PG8_STAGE(PG8_SA(0, 1), a2 + hstep, voffA);
;       PG8_WAIT_L(8); PG8_BAR; PG8_WAIT_L(0); PG8_MMA(0, 0, At, B0); PG8_BAR; PG8_SCHED;
;       PG8_LDB(B1, 1, 1); PG8_STAGE(PG8_SB(1, 0), b3, voffB);
;       PG8_BAR; PG8_WAIT_L(0); PG8_MMA(0, 1, At, B1); PG8_BAR;
;       PG8_LDA(At, 1, 1); PG8_STAGE(PG8_SA(1, 0), a3, voffA);
;       PG8_BAR; PG8_WAIT_L(0); PG8_MMA(1, 0, At, B0); PG8_BAR; PG8_SCHED;
;       PG8_STAGE(PG8_SB(1, 1), b3 + hstep, voffB);
;       PG8_WAIT_V(6); PG8_BAR; PG8_MMA(1, 1, At, B1); PG8_BAR;
;     }
;   DI void operator()(const f32x4 (&acc)[2][2][4][2], const pg8::Unit& u, int wr, int wc, int fr_, int fq_) const {
;     ...
;             if (EPI == EPI_ABIN) {
;               if (n == 0) {
;                 const int gb = u.pn * 256 + bj * 128 + wc * 32; const int f8 = gb + 8 * fq;
;                 const f32x4 v1 = acc[ai][bj][m][1];
;                 if (gb < 384) st_bf8((u16*)(big + E_CQ) + (size_t)token * 384 + f8, v, v1, rinv);
;                 else if (gb < 640) st_bf8((u16*)(big + E_CKV) + (size_t)token * 256 + (f8 - 384), v, v1, rinv);
;                 else if (gb < 672) {
;                   f32x4 a0 = v, a1 = v1;
;                   rope_perm(a0, a1, fq, t_ & 63, tcos, tsin, token & (S_ - 1));
	ds_read_b128 v[158:161], v197 offset:49152
	ds_read_b128 v[162:165], v197 offset:50176
	ds_read_b128 v[166:169], v197 offset:51200
	ds_read_b128 v[170:173], v197 offset:52224
	ds_read_b128 v[174:177], v197 offset:53248
	ds_read_b128 v[178:181], v197 offset:54272
	ds_read_b128 v[198:201], v197 offset:55296
	ds_read_b128 v[202:205], v197 offset:56320
	global_load_lds_dwordx4 v[222:223], off
	v_lshl_add_u64 v[222:223], v[228:229], 0, s[0:1]
	s_mov_b32 m0, s63
	s_nop 0
	global_load_lds_dwordx4 v[222:223], off
	s_barrier
	s_waitcnt lgkmcnt(0)
	v_mfma_f32_16x16x32_bf16 v[60:63], v[128:131], v[158:161], v[60:63]
	v_mfma_f32_16x16x32_bf16 v[56:59], v[150:153], v[158:161], v[56:59]
	v_mfma_f32_16x16x32_bf16 v[44:47], v[128:131], v[166:169], v[44:47]
	v_mfma_f32_16x16x32_bf16 v[40:43], v[150:153], v[166:169], v[40:43]
	v_mfma_f32_16x16x32_bf16 v[28:31], v[128:131], v[174:177], v[28:31]
	v_mfma_f32_16x16x32_bf16 v[24:27], v[150:153], v[174:177], v[24:27]
	v_mfma_f32_16x16x32_bf16 v[12:15], v[128:131], v[198:201], v[12:15]
	v_mfma_f32_16x16x32_bf16 v[8:11], v[150:153], v[198:201], v[8:11]
	v_mfma_f32_16x16x32_bf16 v[60:63], v[132:135], v[162:165], v[60:63]
	v_mfma_f32_16x16x32_bf16 v[56:59], v[154:157], v[162:165], v[56:59]
	v_mfma_f32_16x16x32_bf16 v[44:47], v[132:135], v[170:173], v[44:47]
	v_mfma_f32_16x16x32_bf16 v[40:43], v[154:157], v[170:173], v[40:43]
	v_mfma_f32_16x16x32_bf16 v[28:31], v[132:135], v[178:181], v[28:31]
	v_mfma_f32_16x16x32_bf16 v[24:27], v[154:157], v[178:181], v[24:27]
	v_mfma_f32_16x16x32_bf16 v[12:15], v[132:135], v[202:205], v[12:15]
	v_mfma_f32_16x16x32_bf16 v[8:11], v[154:157], v[202:205], v[8:11]
	s_barrier
	s_add_u32 s22, s22, 0x40080
	s_addc_u32 s23, s23, 0
	s_add_i32 s28, s28, s52
	v_lshl_add_u64 v[128:129], s[22:23], 0, v[140:141]
	s_mov_b32 m0, s28
	s_nop 0
	global_load_lds_dwordx4 v[128:129], off
	v_lshl_add_u64 v[128:129], s[22:23], 0, v[136:137]
	s_add_i32 m0, s28, 0x2000
	s_nop 0
	global_load_lds_dwordx4 v[128:129], off
	s_waitcnt vmcnt(6)
	s_barrier
	v_mfma_f32_16x16x32_bf16 v[52:55], v[206:209], v[158:161], v[52:55]
	v_mfma_f32_16x16x32_bf16 v[48:51], v[214:217], v[158:161], v[48:51]
	v_mfma_f32_16x16x32_bf16 v[36:39], v[206:209], v[166:169], v[36:39]
	v_mfma_f32_16x16x32_bf16 v[32:35], v[214:217], v[166:169], v[32:35]
	v_mfma_f32_16x16x32_bf16 v[20:23], v[206:209], v[174:177], v[20:23]
	v_mfma_f32_16x16x32_bf16 v[16:19], v[214:217], v[174:177], v[16:19]
	v_mfma_f32_16x16x32_bf16 v[4:7], v[206:209], v[198:201], v[4:7]
	v_mfma_f32_16x16x32_bf16 v[0:3], v[214:217], v[198:201], v[0:3]
	v_mfma_f32_16x16x32_bf16 v[52:55], v[210:213], v[162:165], v[52:55]
	v_mfma_f32_16x16x32_bf16 v[48:51], v[218:221], v[162:165], v[48:51]
	v_mfma_f32_16x16x32_bf16 v[36:39], v[210:213], v[170:173], v[36:39]
	v_mfma_f32_16x16x32_bf16 v[32:35], v[218:221], v[170:173], v[32:35]
	v_mfma_f32_16x16x32_bf16 v[20:23], v[210:213], v[178:181], v[20:23]
	v_mfma_f32_16x16x32_bf16 v[16:19], v[218:221], v[178:181], v[16:19]
	v_mfma_f32_16x16x32_bf16 v[4:7], v[210:213], v[202:205], v[4:7]
	v_mfma_f32_16x16x32_bf16 v[0:3], v[218:221], v[202:205], v[0:3]
	s_add_i32 s41, s41, 2
	s_add_u32 s20, s20, 0x100
	s_addc_u32 s21, s21, 0
	s_add_u32 s39, s39, 0x100
	s_addc_u32 s40, s40, 0
	s_cmp_gt_u32 s41, 13
	s_barrier
	s_cbranch_scc0 .LBB0_689
	v_mov_b32_e32 v128, v182
	s_lshl_b32 s20, s34, 10
	v_bfe_u32 v129, v128, 4, 2
	v_and_or_b32 v201, v128, 15, s60
	s_lshl_b32 s13, s35, 8
	v_lshlrev_b32_e32 v128, 2, v128
	s_movk_i32 s21, 0x80
	s_add_i32 s20, s20, 0
	s_lshl_b32 s15, s36, 8
	v_bitop3_b32 v198, v128, s21, v190 bitop3:0x6c
	v_lshl_add_u32 v128, v201, 2, s20
	s_or_b32 s20, s13, s61
	v_add_u32_e32 v200, 0x20000, v128
	s_cmpk_gt_i32 s20, 0x17f
	ds_read_b32 v156, v200
	s_cselect_b64 s[28:29], -1, 0
	s_cmpk_gt_u32 s13, 0x27f
	s_cselect_b64 s[46:47], -1, 0
	s_cmpk_gt_u32 s20, 0x29f
	s_cselect_b64 s[40:41], -1, 0
	s_cmpk_gt_u32 s20, 0x49f
	v_lshlrev_b32_e32 v144, 3, v129
	v_add_u32_e32 v154, s15, v201
	s_cselect_b64 s[34:35], -1, 0
	s_cmpk_gt_u32 s20, 0x69f
	v_ashrrev_i32_e32 v155, 31, v154
	v_lshlrev_b32_e32 v128, 4, v154
	v_or_b32_e32 v150, s20, v144
	s_cselect_b64 s[22:23], -1, 0
	s_cmpk_lt_u32 s20, 0x8a0
	v_and_b32_e32 v199, 8, v144
	v_cmp_lt_u32_e64 s[92:93], 1, v129
	v_lshlrev_b64 v[164:165], 10, v[154:155]
	s_waitcnt lgkmcnt(0)
	v_mul_f32_e32 v162, 0x3e38aa3b, v156
	v_and_b32_e32 v157, 0xfcf0, v128
	v_lshlrev_b64 v[160:161], 6, v[154:155]
	v_lshlrev_b64 v[158:159], 9, v[154:155]
	s_cselect_b64 s[20:21], -1, 0
	v_mov_b32_e32 v152, v150
	v_mov_b32_e32 v153, v145
	s_mov_b64 s[36:37], -1
	s_and_b64 vcc, exec, s[28:29]
	s_cbranch_vccz .LBB0_714
	s_and_b64 vcc, exec, s[46:47]
	s_cbranch_vccz .LBB0_711
	s_and_b64 vcc, exec, s[40:41]
	s_cbranch_vccz .LBB0_704
	s_and_b64 vcc, exec, s[34:35]
	s_cbranch_vccz .LBB0_701
	s_and_b64 vcc, exec, s[22:23]
	s_cbranch_vccz .LBB0_698
	s_andn2_b64 vcc, exec, s[20:21]
	s_cbranch_vccnz .LBB0_697
	v_lshl_add_u64 v[128:129], s[2:3], 0, v[164:165]
	v_lshl_add_u64 v[132:133], v[152:153], 1, v[128:129]
	v_pk_mul_f32 v[128:129], v[124:125], v[156:157] op_sel_hi:[1,0]
	v_pk_mul_f32 v[130:131], v[126:127], v[156:157] op_sel_hi:[1,0]
	v_cvt_pk_bf16_f32 v128, v128, v129
	v_cvt_pk_bf16_f32 v129, v130, v131
	v_pk_mul_f32 v[130:131], v[120:121], v[156:157] op_sel_hi:[1,0]
	v_pk_mul_f32 v[134:135], v[122:123], v[156:157] op_sel_hi:[1,0]
	v_add_co_u32_e32 v132, vcc, 0x69ff000, v132
	v_cvt_pk_bf16_f32 v130, v130, v131
	v_cvt_pk_bf16_f32 v131, v134, v135
	v_addc_co_u32_e32 v133, vcc, 0, v133, vcc
	global_store_dwordx4 v[132:133], v[128:131], off offset:704

; #define PG8_STAGE(bufoff, gbase, voff) do { _Pragma("unroll") for (int _i = 0; _i < 2; ++_i) \
;     __builtin_amdgcn_global_load_lds((const unsigned*)((const char*)(gbase) + (voff)[_i]), (LAS unsigned*)(lds + (bufoff) + ldsw + _i * 8192), 16, 0, 0); } while (0)
; #define PG8_LDA(dst, b, h) do { _Pragma("unroll") for (int m = 0; m < 4; ++m) _Pragma("unroll") for (int k = 0; k < 2; ++k) dst[m][k] = *(const LAS bf16x8*)(lds + PG8_SA(b, h) + aoff + m * 2048 + k * 1024); } while (0)
; #define PG8_LDB(dst, b, h) do { _Pragma("unroll") for (int n = 0; n < 2; ++n) _Pragma("unroll") for (int k = 0; k < 2; ++k) dst[n][k] = *(const LAS bf16x8*)(lds + PG8_SB(b, h) + boff + n * 2048 + k * 1024); } while (0)
; #define PG8_WAIT_V(n) asm volatile("s_waitcnt vmcnt(" #n ")" ::: "memory")
; template <class Epi, class Sched>
; DI void gemm_phase(LAS unsigned char* lds, const Gemm g, const Sched& S, const Epi& E) {
;     ...
;     for (int t = 0; t < nt; t += 2) {
;       const bool last = (t == nt - 2);
;       const char* a1 = cA + (size_t)(t + 1) * kstep;
;       const char* a2 = last ? nA : cA + (size_t)(t + 2) * kstep; const char* b2 = last ? nB : cB + (size_t)(t + 2) * kstep;
;       const char* a3 = a2 + kstep; const char* b3 = b2 + kstep;
;       PG8_LDB(B0, 0, 0); PG8_SCHED; PG8_LDA(At, 0, 0); PG8_STAGE(PG8_SA(1, 1), a1 + hstep, voffA);
;       PG8_WAIT_L(8); PG8_BAR; PG8_WAIT_L(0); PG8_MMA(0, 0, At, B0); PG8_BAR; PG8_SCHED;
;       PG8_LDB(B1, 0, 1); PG8_STAGE(PG8_SB(0, 0), b2, voffB);
;       PG8_BAR; PG8_WAIT_L(0); PG8_MMA(0, 1, At, B1); PG8_BAR;
;       PG8_LDA(At, 0, 1); PG8_STAGE(PG8_SA(0, 0), a2, voffA);
;       PG8_BAR; PG8_WAIT_L(0); PG8_MMA(1, 0, At, B0); PG8_BAR; PG8_SCHED;
;       PG8_STAGE(PG8_SB(0, 1), b2 + hstep, voffB);
;       PG8_WAIT_V(6); PG8_BAR; PG8_MMA(1, 1, At, B1); PG8_BAR;
;       PG8_LDB(B0, 1, 0); PG8_SCHED; PG8_LDA(At, 1, 0); PG8_STAGE(PG8_SA(0, 1), a2 + hstep, voffA);
;       PG8_WAIT_L(8); PG8_BAR; PG8_WAIT_L(0); PG8_MMA(0, 0, At, B0); PG8_BAR; PG8_SCHED;
;       PG8_LDB(B1, 1, 1); PG8_STAGE(PG8_SB(1, 0), b3, voffB);
;       PG8_BAR; PG8_WAIT_L(0); PG8_MMA(0, 1, At, B1); PG8_BAR;
;       PG8_LDA(At, 1, 1); PG8_STAGE(PG8_SA(1, 0), a3, voffA);
;       PG8_BAR; PG8_WAIT_L(0); PG8_MMA(1, 0, At, B0); PG8_BAR; PG8_SCHED;
;       PG8_STAGE(PG8_SB(1, 1), b3 + hstep, voffB);
;       PG8_WAIT_V(6); PG8_BAR; PG8_MMA(1, 1, At, B1); PG8_BAR;
;     }
.LBB0_1202:
	s_add_u32 s20, s18, 0x100
	s_addc_u32 s21, s19, 0
	s_add_i32 s55, 0, 0x10000
	v_add_u32_e32 v144, s55, v162
	ds_read_b128 v[140:143], v144
	ds_read_b128 v[146:149], v144 offset:1024
	ds_read_b128 v[150:153], v144 offset:2048
	ds_read_b128 v[154:157], v144 offset:3072
	s_cmp_eq_u32 s54, 2
	s_cselect_b32 s29, s3, s21
	s_cselect_b32 s28, s2, s20
	s_cselect_b32 s23, s5, s53
	s_cselect_b32 s22, s4, s52
	v_lshl_add_u64 v[180:181], s[18:19], 0, v[136:137]
	s_add_i32 m0, s38, 0xc000
	ds_read_b128 v[158:161], v163
	ds_read_b128 v[164:167], v163 offset:1024
	ds_read_b128 v[168:171], v163 offset:2048
	ds_read_b128 v[172:175], v163 offset:3072
	ds_read_b128 v[176:179], v163 offset:4096
	ds_read_b128 v[196:199], v163 offset:5120
	ds_read_b128 v[200:203], v163 offset:6144
	ds_read_b128 v[204:207], v163 offset:7168
	global_load_lds_dwordx4 v[180:181], off
	v_lshl_add_u64 v[180:181], s[18:19], 0, v[138:139]
	s_add_i32 m0, s38, 0xe000
	s_nop 0
	global_load_lds_dwordx4 v[180:181], off
	s_waitcnt lgkmcnt(8)
	s_barrier
	s_waitcnt lgkmcnt(0)
	v_mfma_f32_16x16x32_bf16 v[124:127], v[140:143], v[158:161], v[124:127]
	v_mfma_f32_16x16x32_bf16 v[120:123], v[150:153], v[158:161], v[120:123]
	v_mfma_f32_16x16x32_bf16 v[108:111], v[140:143], v[168:171], v[108:111]
	v_mfma_f32_16x16x32_bf16 v[104:107], v[150:153], v[168:171], v[104:107]
	v_mfma_f32_16x16x32_bf16 v[92:95], v[140:143], v[176:179], v[92:95]
	v_mfma_f32_16x16x32_bf16 v[88:91], v[150:153], v[176:179], v[88:91]
	v_mfma_f32_16x16x32_bf16 v[76:79], v[140:143], v[200:203], v[76:79]
	v_mfma_f32_16x16x32_bf16 v[72:75], v[150:153], v[200:203], v[72:75]
	v_mfma_f32_16x16x32_bf16 v[124:127], v[146:149], v[164:167], v[124:127]
	v_mfma_f32_16x16x32_bf16 v[120:123], v[154:157], v[164:167], v[120:123]
	v_mfma_f32_16x16x32_bf16 v[108:111], v[146:149], v[172:175], v[108:111]
	v_mfma_f32_16x16x32_bf16 v[104:107], v[154:157], v[172:175], v[104:107]
	v_mfma_f32_16x16x32_bf16 v[92:95], v[146:149], v[196:199], v[92:95]
	v_mfma_f32_16x16x32_bf16 v[88:91], v[154:157], v[196:199], v[88:91]
	v_mfma_f32_16x16x32_bf16 v[76:79], v[146:149], v[204:207], v[76:79]
	v_mfma_f32_16x16x32_bf16 v[72:75], v[154:157], v[204:207], v[72:75]
	s_barrier
	s_add_i32 s56, 0, 0x14000
	s_add_i32 s18, s55, s35
	v_add_u32_e32 v144, s56, v162
	v_lshl_add_u64 v[180:181], s[22:23], 0, v[130:131]
	s_mov_b32 m0, s18
	ds_read_b128 v[208:211], v144
	ds_read_b128 v[212:215], v144 offset:1024
	ds_read_b128 v[216:219], v144 offset:2048
	ds_read_b128 v[220:223], v144 offset:3072
	global_load_lds_dwordx4 v[180:181], off
	v_lshl_add_u64 v[224:225], s[22:23], 0, v[134:135]
	s_add_i32 m0, s18, 0x2000
	s_nop 0
	global_load_lds_dwordx4 v[224:225], off
	s_barrier
	s_waitcnt lgkmcnt(0)
	v_mfma_f32_16x16x32_bf16 v[116:119], v[208:211], v[158:161], v[116:119]
	v_mfma_f32_16x16x32_bf16 v[112:115], v[216:219], v[158:161], v[112:115]
	v_mfma_f32_16x16x32_bf16 v[100:103], v[208:211], v[168:171], v[100:103]
	v_mfma_f32_16x16x32_bf16 v[96:99], v[216:219], v[168:171], v[96:99]
	v_mfma_f32_16x16x32_bf16 v[84:87], v[208:211], v[176:179], v[84:87]
	v_mfma_f32_16x16x32_bf16 v[80:83], v[216:219], v[176:179], v[80:83]
	v_mfma_f32_16x16x32_bf16 v[68:71], v[208:211], v[200:203], v[68:71]
	v_mfma_f32_16x16x32_bf16 v[64:67], v[216:219], v[200:203], v[64:67]
	v_mfma_f32_16x16x32_bf16 v[116:119], v[212:215], v[164:167], v[116:119]
	v_mfma_f32_16x16x32_bf16 v[112:115], v[220:223], v[164:167], v[112:115]
	v_mfma_f32_16x16x32_bf16 v[100:103], v[212:215], v[172:175], v[100:103]
	v_mfma_f32_16x16x32_bf16 v[96:99], v[220:223], v[172:175], v[96:99]
	v_mfma_f32_16x16x32_bf16 v[84:87], v[212:215], v[196:199], v[84:87]
	v_mfma_f32_16x16x32_bf16 v[80:83], v[220:223], v[196:199], v[80:83]
	v_mfma_f32_16x16x32_bf16 v[68:71], v[212:215], v[204:207], v[68:71]
	v_mfma_f32_16x16x32_bf16 v[64:67], v[220:223], v[204:207], v[64:67]
	s_mov_b32 m0, s38
	v_lshl_add_u64 v[226:227], s[28:29], 0, v[128:129]
	s_barrier
	ds_read_b128 v[158:161], v163 offset:16384
	ds_read_b128 v[164:167], v163 offset:17408
	ds_read_b128 v[168:171], v163 offset:18432
	ds_read_b128 v[172:175], v163 offset:19456
	ds_read_b128 v[176:179], v163 offset:20480
	ds_read_b128 v[196:199], v163 offset:21504
	ds_read_b128 v[200:203], v163 offset:22528
	ds_read_b128 v[204:207], v163 offset:23552
	global_load_lds_dwordx4 v[226:227], off
	v_lshl_add_u64 v[228:229], s[28:29], 0, v[132:133]
	s_mov_b32 m0, s39
	s_nop 0
	global_load_lds_dwordx4 v[228:229], off
	s_barrier
	s_waitcnt lgkmcnt(0)
	v_mfma_f32_16x16x32_bf16 v[60:63], v[140:143], v[158:161], v[60:63]
	v_mfma_f32_16x16x32_bf16 v[56:59], v[150:153], v[158:161], v[56:59]
	v_mfma_f32_16x16x32_bf16 v[44:47], v[140:143], v[168:171], v[44:47]
	v_mfma_f32_16x16x32_bf16 v[40:43], v[150:153], v[168:171], v[40:43]
	v_mfma_f32_16x16x32_bf16 v[28:31], v[140:143], v[176:179], v[28:31]
	v_mfma_f32_16x16x32_bf16 v[24:27], v[150:153], v[176:179], v[24:27]
	v_mfma_f32_16x16x32_bf16 v[12:15], v[140:143], v[200:203], v[12:15]
	v_mfma_f32_16x16x32_bf16 v[8:11], v[150:153], v[200:203], v[8:11]
	v_mfma_f32_16x16x32_bf16 v[60:63], v[146:149], v[164:167], v[60:63]
	v_mfma_f32_16x16x32_bf16 v[56:59], v[154:157], v[164:167], v[56:59]
	v_mfma_f32_16x16x32_bf16 v[44:47], v[146:149], v[172:175], v[44:47]
	v_mfma_f32_16x16x32_bf16 v[40:43], v[154:157], v[172:175], v[40:43]
	v_mfma_f32_16x16x32_bf16 v[28:31], v[146:149], v[196:199], v[28:31]
	v_mfma_f32_16x16x32_bf16 v[24:27], v[154:157], v[196:199], v[24:27]
	v_mfma_f32_16x16x32_bf16 v[12:15], v[146:149], v[204:207], v[12:15]
	v_mfma_f32_16x16x32_bf16 v[8:11], v[154:157], v[204:207], v[8:11]
	s_barrier
; #define PG8_STAGE(bufoff, gbase, voff) do { _Pragma("unroll") for (int _i = 0; _i < 2; ++_i) \
;     __builtin_amdgcn_global_load_lds((const unsigned*)((const char*)(gbase) + (voff)[_i]), (LAS unsigned*)(lds + (bufoff) + ldsw + _i * 8192), 16, 0, 0); } while (0)
; #define PG8_LDA(dst, b, h) do { _Pragma("unroll") for (int m = 0; m < 4; ++m) _Pragma("unroll") for (int k = 0; k < 2; ++k) dst[m][k] = *(const LAS bf16x8*)(lds + PG8_SA(b, h) + aoff + m * 2048 + k * 1024); } while (0)
; #define PG8_LDB(dst, b, h) do { _Pragma("unroll") for (int n = 0; n < 2; ++n) _Pragma("unroll") for (int k = 0; k < 2; ++k) dst[n][k] = *(const LAS bf16x8*)(lds + PG8_SB(b, h) + boff + n * 2048 + k * 1024); } while (0)
; #define PG8_WAIT_V(n) asm volatile("s_waitcnt vmcnt(" #n ")" ::: "memory")
; template <class Epi, class Sched>
; DI void gemm_phase(LAS unsigned char* lds, const Gemm g, const Sched& S, const Epi& E) {
;     ...
;     for (int t = 0; t < nt; t += 2) {
;       const bool last = (t == nt - 2);
;       const char* a1 = cA + (size_t)(t + 1) * kstep;
;       const char* a2 = last ? nA : cA + (size_t)(t + 2) * kstep; const char* b2 = last ? nB : cB + (size_t)(t + 2) * kstep;
;       const char* a3 = a2 + kstep; const char* b3 = b2 + kstep;
;       PG8_LDB(B0, 0, 0); PG8_SCHED; PG8_LDA(At, 0, 0); PG8_STAGE(PG8_SA(1, 1), a1 + hstep, voffA);
;       PG8_WAIT_L(8); PG8_BAR; PG8_WAIT_L(0); PG8_MMA(0, 0, At, B0); PG8_BAR; PG8_SCHED;
;       PG8_LDB(B1, 0, 1); PG8_STAGE(PG8_SB(0, 0), b2, voffB);
;       PG8_BAR; PG8_WAIT_L(0); PG8_MMA(0, 1, At, B1); PG8_BAR;
;       PG8_LDA(At, 0, 1); PG8_STAGE(PG8_SA(0, 0), a2, voffA);
;       PG8_BAR; PG8_WAIT_L(0); PG8_MMA(1, 0, At, B0); PG8_BAR; PG8_SCHED;
;       PG8_STAGE(PG8_SB(0, 1), b2 + hstep, voffB);
;       PG8_WAIT_V(6); PG8_BAR; PG8_MMA(1, 1, At, B1); PG8_BAR;
;       PG8_LDB(B0, 1, 0); PG8_SCHED; PG8_LDA(At, 1, 0); PG8_STAGE(PG8_SA(0, 1), a2 + hstep, voffA);
;       PG8_WAIT_L(8); PG8_BAR; PG8_WAIT_L(0); PG8_MMA(0, 0, At, B0); PG8_BAR; PG8_SCHED;
;       PG8_LDB(B1, 1, 1); PG8_STAGE(PG8_SB(1, 0), b3, voffB);
;       PG8_BAR; PG8_WAIT_L(0); PG8_MMA(0, 1, At, B1); PG8_BAR;
;       PG8_LDA(At, 1, 1); PG8_STAGE(PG8_SA(1, 0), a3, voffA);
;       PG8_BAR; PG8_WAIT_L(0); PG8_MMA(1, 0, At, B0); PG8_BAR; PG8_SCHED;
;       PG8_STAGE(PG8_SB(1, 1), b3 + hstep, voffB);
;       PG8_WAIT_V(6); PG8_BAR; PG8_MMA(1, 1, At, B1); PG8_BAR;
;     }
	s_add_u32 s18, s22, 0x18000
	s_addc_u32 s19, s23, 0
	s_add_i32 s55, s56, s35
	v_lshl_add_u64 v[140:141], s[18:19], 0, v[130:131]
	s_mov_b32 m0, s55
	s_nop 0
	global_load_lds_dwordx4 v[140:141], off
	v_lshl_add_u64 v[140:141], s[18:19], 0, v[134:135]
	s_add_i32 m0, s55, 0x2000
	s_nop 0
	global_load_lds_dwordx4 v[140:141], off
	s_waitcnt vmcnt(6)
	s_barrier
	v_mfma_f32_16x16x32_bf16 v[52:55], v[208:211], v[158:161], v[52:55]
	v_mfma_f32_16x16x32_bf16 v[48:51], v[216:219], v[158:161], v[48:51]
	v_mfma_f32_16x16x32_bf16 v[36:39], v[208:211], v[168:171], v[36:39]
	v_mfma_f32_16x16x32_bf16 v[32:35], v[216:219], v[168:171], v[32:35]
	v_mfma_f32_16x16x32_bf16 v[20:23], v[208:211], v[176:179], v[20:23]
	v_mfma_f32_16x16x32_bf16 v[16:19], v[216:219], v[176:179], v[16:19]
	v_mfma_f32_16x16x32_bf16 v[4:7], v[208:211], v[200:203], v[4:7]
	v_mfma_f32_16x16x32_bf16 v[0:3], v[216:219], v[200:203], v[0:3]
	v_mfma_f32_16x16x32_bf16 v[52:55], v[212:215], v[164:167], v[52:55]
	v_mfma_f32_16x16x32_bf16 v[48:51], v[220:223], v[164:167], v[48:51]
	v_mfma_f32_16x16x32_bf16 v[36:39], v[212:215], v[172:175], v[36:39]
	v_mfma_f32_16x16x32_bf16 v[32:35], v[220:223], v[172:175], v[32:35]
	v_mfma_f32_16x16x32_bf16 v[20:23], v[212:215], v[196:199], v[20:23]
	v_mfma_f32_16x16x32_bf16 v[16:19], v[220:223], v[196:199], v[16:19]
	v_mfma_f32_16x16x32_bf16 v[4:7], v[212:215], v[204:207], v[4:7]
	v_mfma_f32_16x16x32_bf16 v[0:3], v[220:223], v[204:207], v[0:3]
	s_add_i32 s55, 0, 0x18000
	v_add_u32_e32 v144, s55, v162
	s_barrier
	ds_read_b128 v[140:143], v144
	ds_read_b128 v[146:149], v144 offset:1024
	ds_read_b128 v[150:153], v144 offset:2048
	ds_read_b128 v[154:157], v144 offset:3072
	s_add_u32 s18, s28, 0x18000
	s_addc_u32 s19, s29, 0
	s_mov_b32 m0, s40
	v_lshl_add_u64 v[208:209], s[18:19], 0, v[128:129]
	ds_read_b128 v[158:161], v163 offset:32768
	ds_read_b128 v[164:167], v163 offset:33792
	ds_read_b128 v[168:171], v163 offset:34816
	ds_read_b128 v[172:175], v163 offset:35840
	ds_read_b128 v[176:179], v163 offset:36864
	ds_read_b128 v[196:199], v163 offset:37888
	ds_read_b128 v[200:203], v163 offset:38912
	ds_read_b128 v[204:207], v163 offset:39936
	global_load_lds_dwordx4 v[208:209], off
	v_lshl_add_u64 v[208:209], s[18:19], 0, v[132:133]
	s_mov_b32 m0, s41
	s_nop 0
	global_load_lds_dwordx4 v[208:209], off
	s_waitcnt lgkmcnt(8)
	s_barrier
	s_waitcnt lgkmcnt(0)
	v_mfma_f32_16x16x32_bf16 v[124:127], v[140:143], v[158:161], v[124:127]
	v_mfma_f32_16x16x32_bf16 v[120:123], v[150:153], v[158:161], v[120:123]
	v_mfma_f32_16x16x32_bf16 v[108:111], v[140:143], v[168:171], v[108:111]
	v_mfma_f32_16x16x32_bf16 v[104:107], v[150:153], v[168:171], v[104:107]
	v_mfma_f32_16x16x32_bf16 v[92:95], v[140:143], v[176:179], v[92:95]
	v_mfma_f32_16x16x32_bf16 v[88:91], v[150:153], v[176:179], v[88:91]
	v_mfma_f32_16x16x32_bf16 v[76:79], v[140:143], v[200:203], v[76:79]
	v_mfma_f32_16x16x32_bf16 v[72:75], v[150:153], v[200:203], v[72:75]
	v_mfma_f32_16x16x32_bf16 v[124:127], v[146:149], v[164:167], v[124:127]
	v_mfma_f32_16x16x32_bf16 v[120:123], v[154:157], v[164:167], v[120:123]
	v_mfma_f32_16x16x32_bf16 v[108:111], v[146:149], v[172:175], v[108:111]
	v_mfma_f32_16x16x32_bf16 v[104:107], v[154:157], v[172:175], v[104:107]
	v_mfma_f32_16x16x32_bf16 v[92:95], v[146:149], v[196:199], v[92:95]
	v_mfma_f32_16x16x32_bf16 v[88:91], v[154:157], v[196:199], v[88:91]
	v_mfma_f32_16x16x32_bf16 v[76:79], v[146:149], v[204:207], v[76:79]
	v_mfma_f32_16x16x32_bf16 v[72:75], v[154:157], v[204:207], v[72:75]
	s_barrier
	s_add_i32 s28, 0, 0x1c000
	s_add_i32 s18, s55, s35
	v_add_u32_e32 v144, s28, v162
	v_lshl_add_u64 v[180:181], v[180:181], 0, s[0:1]
	s_mov_b32 m0, s18
	ds_read_b128 v[208:211], v144
	ds_read_b128 v[212:215], v144 offset:1024
	ds_read_b128 v[216:219], v144 offset:2048
	ds_read_b128 v[220:223], v144 offset:3072
	global_load_lds_dwordx4 v[180:181], off
	v_lshl_add_u64 v[180:181], v[224:225], 0, s[0:1]
	s_add_i32 m0, s18, 0x2000
	s_nop 0
	global_load_lds_dwordx4 v[180:181], off
	s_barrier
	s_waitcnt lgkmcnt(0)
	v_mfma_f32_16x16x32_bf16 v[116:119], v[208:211], v[158:161], v[116:119]
	v_mfma_f32_16x16x32_bf16 v[112:115], v[216:219], v[158:161], v[112:115]
	v_mfma_f32_16x16x32_bf16 v[100:103], v[208:211], v[168:171], v[100:103]
	v_mfma_f32_16x16x32_bf16 v[96:99], v[216:219], v[168:171], v[96:99]
	v_mfma_f32_16x16x32_bf16 v[84:87], v[208:211], v[176:179], v[84:87]
	v_mfma_f32_16x16x32_bf16 v[80:83], v[216:219], v[176:179], v[80:83]
	v_mfma_f32_16x16x32_bf16 v[68:71], v[208:211], v[200:203], v[68:71]
	v_mfma_f32_16x16x32_bf16 v[64:67], v[216:219], v[200:203], v[64:67]
	v_mfma_f32_16x16x32_bf16 v[116:119], v[212:215], v[164:167], v[116:119]
	v_mfma_f32_16x16x32_bf16 v[112:115], v[220:223], v[164:167], v[112:115]
	v_mfma_f32_16x16x32_bf16 v[100:103], v[212:215], v[172:175], v[100:103]
	v_mfma_f32_16x16x32_bf16 v[96:99], v[220:223], v[172:175], v[96:99]
	v_mfma_f32_16x16x32_bf16 v[84:87], v[212:215], v[196:199], v[84:87]
	v_mfma_f32_16x16x32_bf16 v[80:83], v[220:223], v[196:199], v[80:83]
	v_mfma_f32_16x16x32_bf16 v[68:71], v[212:215], v[204:207], v[68:71]
	v_mfma_f32_16x16x32_bf16 v[64:67], v[220:223], v[204:207], v[64:67]
	s_mov_b32 m0, s44
	v_lshl_add_u64 v[180:181], v[226:227], 0, s[0:1]
	s_barrier
	ds_read_b128 v[158:161], v163 offset:49152
	ds_read_b128 v[164:167], v163 offset:50176
	ds_read_b128 v[168:171], v163 offset:51200
	ds_read_b128 v[172:175], v163 offset:52224
	ds_read_b128 v[176:179], v163 offset:53248
	ds_read_b128 v[196:199], v163 offset:54272
	ds_read_b128 v[200:203], v163 offset:55296
	ds_read_b128 v[204:207], v163 offset:56320
	global_load_lds_dwordx4 v[180:181], off
	v_lshl_add_u64 v[180:181], v[228:229], 0, s[0:1]
	s_mov_b32 m0, s45
	s_nop 0
	global_load_lds_dwordx4 v[180:181], off
	s_barrier
; #define PG8_STAGE(bufoff, gbase, voff) do { _Pragma("unroll") for (int _i = 0; _i < 2; ++_i) \
;     __builtin_amdgcn_global_load_lds((const unsigned*)((const char*)(gbase) + (voff)[_i]), (LAS unsigned*)(lds + (bufoff) + ldsw + _i * 8192), 16, 0, 0); } while (0)
; #define PG8_LDA(dst, b, h) do { _Pragma("unroll") for (int m = 0; m < 4; ++m) _Pragma("unroll") for (int k = 0; k < 2; ++k) dst[m][k] = *(const LAS bf16x8*)(lds + PG8_SA(b, h) + aoff + m * 2048 + k * 1024); } while (0)
; #define PG8_LDB(dst, b, h) do { _Pragma("unroll") for (int n = 0; n < 2; ++n) _Pragma("unroll") for (int k = 0; k < 2; ++k) dst[n][k] = *(const LAS bf16x8*)(lds + PG8_SB(b, h) + boff + n * 2048 + k * 1024); } while (0)
; #define PG8_WAIT_V(n) asm volatile("s_waitcnt vmcnt(" #n ")" ::: "memory")
; #define PG8_WAIT_L(n) asm volatile("s_waitcnt lgkmcnt(" #n ")" ::: "memory")
; #define PG8_BAR __builtin_amdgcn_s_barrier()
; #define PG8_SCHED __builtin_amdgcn_sched_barrier(0)
; template <class Epi, class Sched>
; DI void gemm_phase(LAS unsigned char* lds, const Gemm g, const Sched& S, const Epi& E) {
;     ...
;       PG8_WAIT_V(6); PG8_BAR; PG8_MMA(1, 1, At, B1); PG8_BAR;
;       PG8_LDB(B0, 1, 0); PG8_SCHED; PG8_LDA(At, 1, 0); PG8_STAGE(PG8_SA(0, 1), a2 + hstep, voffA);
;       PG8_WAIT_L(8); PG8_BAR; PG8_WAIT_L(0); PG8_MMA(0, 0, At, B0); PG8_BAR; PG8_SCHED;
;       PG8_LDB(B1, 1, 1); PG8_STAGE(PG8_SB(1, 0), b3, voffB);
;       PG8_BAR; PG8_WAIT_L(0); PG8_MMA(0, 1, At, B1); PG8_BAR;
;       PG8_LDA(At, 1, 1); PG8_STAGE(PG8_SA(1, 0), a3, voffA);
;       PG8_BAR; PG8_WAIT_L(0); PG8_MMA(1, 0, At, B0); PG8_BAR; PG8_SCHED;
;       PG8_STAGE(PG8_SB(1, 1), b3 + hstep, voffB);
;       PG8_WAIT_V(6); PG8_BAR; PG8_MMA(1, 1, At, B1); PG8_BAR;
; DI void rope_perm(f32x4& a0, f32x4& a1, int fq, int lane, const float* tcos, const float* tsin, int pos) {
;   f32x4 p0, p1;
; #pragma unroll
;   for (int e = 0; e < 4; ++e) { p0[e] = shx(a0[e], 32, lane); p1[e] = shx(a1[e], 32, lane); }
;   const int jb = 8 * (fq & 1);
;   const f32x4 c0 = *(const f32x4*)(tcos + pos * 16 + jb), c1 = *(const f32x4*)(tcos + pos * 16 + jb + 4);
;   const f32x4 s0 = *(const f32x4*)(tsin + pos * 16 + jb), s1 = *(const f32x4*)(tsin + pos * 16 + jb + 4);
;   if (fq < 2) { a0 = a0 * c0 - p0 * s0; a1 = a1 * c1 - p1 * s1; }
;   else        { a0 = a0 * c0 + p0 * s0; a1 = a1 * c1 + p1 * s1; }
	s_waitcnt lgkmcnt(0)
	v_mfma_f32_16x16x32_bf16 v[60:63], v[140:143], v[158:161], v[60:63]
	v_mfma_f32_16x16x32_bf16 v[56:59], v[150:153], v[158:161], v[56:59]
	v_mfma_f32_16x16x32_bf16 v[44:47], v[140:143], v[168:171], v[44:47]
	v_mfma_f32_16x16x32_bf16 v[40:43], v[150:153], v[168:171], v[40:43]
	v_mfma_f32_16x16x32_bf16 v[28:31], v[140:143], v[176:179], v[28:31]
	v_mfma_f32_16x16x32_bf16 v[24:27], v[150:153], v[176:179], v[24:27]
	v_mfma_f32_16x16x32_bf16 v[12:15], v[140:143], v[200:203], v[12:15]
	v_mfma_f32_16x16x32_bf16 v[8:11], v[150:153], v[200:203], v[8:11]
	v_mfma_f32_16x16x32_bf16 v[60:63], v[146:149], v[164:167], v[60:63]
	v_mfma_f32_16x16x32_bf16 v[56:59], v[154:157], v[164:167], v[56:59]
	v_mfma_f32_16x16x32_bf16 v[44:47], v[146:149], v[172:175], v[44:47]
	v_mfma_f32_16x16x32_bf16 v[40:43], v[154:157], v[172:175], v[40:43]
	v_mfma_f32_16x16x32_bf16 v[28:31], v[146:149], v[196:199], v[28:31]
	v_mfma_f32_16x16x32_bf16 v[24:27], v[154:157], v[196:199], v[24:27]
	v_mfma_f32_16x16x32_bf16 v[12:15], v[146:149], v[204:207], v[12:15]
	v_mfma_f32_16x16x32_bf16 v[8:11], v[154:157], v[204:207], v[8:11]
	s_barrier
	s_add_u32 s18, s22, 0x18080
	s_addc_u32 s19, s23, 0
	s_add_i32 s22, s28, s35
	v_lshl_add_u64 v[140:141], s[18:19], 0, v[130:131]
	s_mov_b32 m0, s22
	s_nop 0
	global_load_lds_dwordx4 v[140:141], off
	v_lshl_add_u64 v[140:141], s[18:19], 0, v[134:135]
	s_add_i32 m0, s22, 0x2000
	s_nop 0
	global_load_lds_dwordx4 v[140:141], off
	s_waitcnt vmcnt(6)
	s_barrier
	v_mfma_f32_16x16x32_bf16 v[52:55], v[208:211], v[158:161], v[52:55]
	v_mfma_f32_16x16x32_bf16 v[48:51], v[216:219], v[158:161], v[48:51]
	v_mfma_f32_16x16x32_bf16 v[36:39], v[208:211], v[168:171], v[36:39]
	v_mfma_f32_16x16x32_bf16 v[32:35], v[216:219], v[168:171], v[32:35]
	v_mfma_f32_16x16x32_bf16 v[20:23], v[208:211], v[176:179], v[20:23]
	v_mfma_f32_16x16x32_bf16 v[16:19], v[216:219], v[176:179], v[16:19]
	v_mfma_f32_16x16x32_bf16 v[4:7], v[208:211], v[200:203], v[4:7]
	v_mfma_f32_16x16x32_bf16 v[0:3], v[216:219], v[200:203], v[0:3]
	v_mfma_f32_16x16x32_bf16 v[52:55], v[212:215], v[164:167], v[52:55]
	v_mfma_f32_16x16x32_bf16 v[48:51], v[220:223], v[164:167], v[48:51]
	v_mfma_f32_16x16x32_bf16 v[36:39], v[212:215], v[172:175], v[36:39]
	v_mfma_f32_16x16x32_bf16 v[32:35], v[220:223], v[172:175], v[32:35]
	v_mfma_f32_16x16x32_bf16 v[20:23], v[212:215], v[196:199], v[20:23]
	v_mfma_f32_16x16x32_bf16 v[16:19], v[220:223], v[196:199], v[16:19]
	v_mfma_f32_16x16x32_bf16 v[4:7], v[212:215], v[204:207], v[4:7]
	v_mfma_f32_16x16x32_bf16 v[0:3], v[220:223], v[204:207], v[0:3]
	s_add_i32 s54, s54, 2
	s_add_u32 s52, s52, 0x100
	s_addc_u32 s53, s53, 0
	s_cmp_gt_u32 s54, 3
	s_mov_b64 s[18:19], s[20:21]
	s_barrier
	s_cbranch_scc0 .LBB0_1202
	v_mov_b32_e32 v140, v182
	s_lshl_b32 s19, s51, 10
	s_lshl_b32 s18, s49, 8
	s_or_b32 s18, s18, s43
	v_and_or_b32 v167, v140, 15, s42
	v_lshlrev_b32_e32 v141, 2, v140
	s_movk_i32 s20, 0x80
	s_add_i32 s19, s19, 0
	v_bitop3_b32 v164, v141, s20, v190 bitop3:0x6c
	v_lshl_add_u32 v141, v167, 2, s19
	s_mul_hi_i32 s19, s18, 0x2aaaaaab
	v_add_u32_e32 v166, 0x20000, v141
	s_lshr_b32 s20, s19, 31
	s_lshr_b32 s19, s19, 4
	s_lshl_b32 s50, s50, 8
	ds_read_b32 v144, v166
	s_add_i32 s19, s19, s20
	v_add_u32_e32 v165, s50, v167
	s_mulk_i32 s19, 0x60
	v_bfe_u32 v168, v140, 4, 2
	v_lshrrev_b32_e32 v140, 1, v140
	v_lshlrev_b32_e32 v141, 4, v165
	s_sub_i32 s19, s18, s19
	v_and_b32_e32 v140, 8, v140
	v_and_b32_e32 v141, 0xfcf0, v141
	s_cmp_eq_u32 s19, 64
	v_cmp_lt_u32_e64 s[78:79], 1, v168
	s_cselect_b64 s[20:21], -1, 0
	s_cmp_lg_u32 s19, 64
	v_lshlrev_b32_e32 v142, 2, v141
	v_lshlrev_b32_e32 v140, 2, v140
	s_cbranch_scc1 .LBB0_1209
	v_mov_b32_e32 v143, v145
	v_lshl_add_u64 v[146:147], s[12:13], 0, v[142:143]
	v_mov_b32_e32 v141, v145
	v_lshl_add_u64 v[152:153], s[14:15], 0, v[142:143]
	v_lshl_add_u64 v[146:147], v[146:147], 0, v[140:141]
	v_lshl_add_u64 v[152:153], v[152:153], 0, v[140:141]
	global_load_dwordx4 v[148:151], v[146:147], off
	global_load_dwordx4 v[154:157], v[152:153], off
	global_load_dwordx4 v[170:173], v[152:153], off offset:16
	global_load_dwordx4 v[174:177], v[146:147], off offset:16
	ds_bpermute_b32 v152, v164, v124
	ds_bpermute_b32 v160, v164, v120
	ds_bpermute_b32 v153, v164, v125
	ds_bpermute_b32 v161, v164, v121
	ds_bpermute_b32 v158, v164, v126
	ds_bpermute_b32 v178, v164, v122
	ds_bpermute_b32 v159, v164, v127
	ds_bpermute_b32 v179, v164, v123
	s_waitcnt vmcnt(0) lgkmcnt(0)
	v_pk_mul_f32 v[154:155], v[154:155], v[152:153]
	v_pk_mul_f32 v[146:147], v[126:127], v[150:151]
	v_pk_mul_f32 v[150:151], v[124:125], v[148:149]
	v_pk_mul_f32 v[158:159], v[156:157], v[158:159]
	v_pk_mul_f32 v[148:149], v[170:171], v[160:161]
	v_pk_mul_f32 v[152:153], v[172:173], v[178:179]
	v_pk_mul_f32 v[156:157], v[122:123], v[176:177]
	v_pk_mul_f32 v[160:161], v[120:121], v[174:175]
	s_and_saveexec_b64 s[22:23], s[78:79]
	s_xor_b64 s[22:23], exec, s[22:23]
	v_pk_add_f32 v[126:127], v[146:147], v[158:159]
	v_pk_add_f32 v[124:125], v[150:151], v[154:155]
	v_pk_add_f32 v[122:123], v[156:157], v[152:153]
	v_pk_add_f32 v[120:121], v[160:161], v[148:149]
	s_andn2_saveexec_b64 s[22:23], s[22:23]
	v_sub_f32_e32 v127, v147, v159
	v_sub_f32_e32 v126, v146, v158
	v_sub_f32_e32 v125, v151, v155
	v_sub_f32_e32 v124, v150, v154
	v_sub_f32_e32 v123, v157, v153
	v_sub_f32_e32 v122, v156, v152
	v_sub_f32_e32 v121, v161, v149
	v_sub_f32_e32 v120, v160, v148
	s_or_b64 exec, exec, s[22:23]

; #define PG8_STAGE(bufoff, gbase, voff) do { _Pragma("unroll") for (int _i = 0; _i < 2; ++_i) \
;     __builtin_amdgcn_global_load_lds((const unsigned*)((const char*)(gbase) + (voff)[_i]), (LAS unsigned*)(lds + (bufoff) + ldsw + _i * 8192), 16, 0, 0); } while (0)
; #define PG8_LDA(dst, b, h) do { _Pragma("unroll") for (int m = 0; m < 4; ++m) _Pragma("unroll") for (int k = 0; k < 2; ++k) dst[m][k] = *(const LAS bf16x8*)(lds + PG8_SA(b, h) + aoff + m * 2048 + k * 1024); } while (0)
; #define PG8_LDB(dst, b, h) do { _Pragma("unroll") for (int n = 0; n < 2; ++n) _Pragma("unroll") for (int k = 0; k < 2; ++k) dst[n][k] = *(const LAS bf16x8*)(lds + PG8_SB(b, h) + boff + n * 2048 + k * 1024); } while (0)
; #define PG8_MMA(ai, bj, At, Bt) do { __builtin_amdgcn_s_setprio(1); _Pragma("unroll") for (int m = 0; m < 4; ++m) _Pragma("unroll") for (int n = 0; n < 2; ++n) _Pragma("unroll") for (int k = 0; k < 2; ++k) \
;     acc[ai][bj][m][n] = __builtin_amdgcn_mfma_f32_16x16x32_bf16(Bt[n][k], At[m][k], acc[ai][bj][m][n], 0, 0, 0); __builtin_amdgcn_s_setprio(0); } while (0)
; #define PG8_BAR __builtin_amdgcn_s_barrier()
; template <class Epi, class Sched>
; DI void gemm_phase(LAS unsigned char* lds, const Gemm g, const Sched& S, const Epi& E) {
;     ...
;     const bool has_next = S.next(ui + 1, nxt);
;     const char* nA = has_next ? (const char*)g.A + (size_t)nxt.pm * tstep : cA; const char* nB = has_next ? (const char*)g.Bt + (size_t)nxt.pn * tstep : cB;
; #pragma unroll 1
;     for (int t = 0; t < nt; t += 2) {
;       const bool last = (t == nt - 2);
;       const char* a1 = cA + (size_t)(t + 1) * kstep;
;       const char* a2 = last ? nA : cA + (size_t)(t + 2) * kstep; const char* b2 = last ? nB : cB + (size_t)(t + 2) * kstep;
;       const char* a3 = a2 + kstep; const char* b3 = b2 + kstep;
;       PG8_LDB(B0, 0, 0); PG8_SCHED; PG8_LDA(At, 0, 0); PG8_STAGE(PG8_SA(1, 1), a1 + hstep, voffA);
;       PG8_WAIT_L(8); PG8_BAR; PG8_WAIT_L(0); PG8_MMA(0, 0, At, B0); PG8_BAR; PG8_SCHED;
;       PG8_LDB(B1, 0, 1); PG8_STAGE(PG8_SB(0, 0), b2, voffB);
;       PG8_BAR; PG8_WAIT_L(0); PG8_MMA(0, 1, At, B1); PG8_BAR;
;       PG8_LDA(At, 0, 1); PG8_STAGE(PG8_SA(0, 0), a2, voffA);
;       PG8_BAR; PG8_WAIT_L(0); PG8_MMA(1, 0, At, B0); PG8_BAR; PG8_SCHED;
;       PG8_STAGE(PG8_SB(0, 1), b2 + hstep, voffB);
;       PG8_WAIT_V(6); PG8_BAR; PG8_MMA(1, 1, At, B1); PG8_BAR;
.LBB0_1346:
	s_add_u32 s48, s28, s40
	s_addc_u32 s49, s29, s41
	s_add_u32 s44, s48, 0x100
	s_addc_u32 s45, s49, 0
	s_and_b64 s[42:43], s[36:37], exec
	s_cselect_b32 s45, s15, s45
	s_cselect_b32 s44, s21, s44
	s_add_u32 s40, s22, s40
	s_addc_u32 s41, s23, s41
	s_add_u32 s40, s40, 0x100
	s_addc_u32 s41, s41, 0
	s_add_i32 s70, 0, 0x10000
	s_and_b64 s[36:37], s[36:37], exec
	s_cselect_b32 s47, s13, s41
	s_cselect_b32 s46, s24, s40
	s_add_u32 s48, s48, 0x10080
	s_addc_u32 s49, s49, 0
	s_add_i32 s74, s70, s51
	s_add_i32 m0, s56, 0xc000
	s_add_i32 s75, s56, 0xe000
	s_add_i32 s73, 0, 0x14000
	s_add_i32 s72, s74, 0x2000
	s_add_u32 s42, s46, 0x10000
	v_add_u32_e32 v140, s70, v142
	s_addc_u32 s43, s47, 0
	s_add_i32 s69, s73, s51
	ds_read_b128 v[136:139], v140
	ds_read_b128 v[146:149], v140 offset:1024
	ds_read_b128 v[150:153], v140 offset:2048
	ds_read_b128 v[154:157], v140 offset:3072
	s_add_i32 s68, s69, 0x2000
	s_add_i32 s67, 0, 0x18000
	s_add_u32 s40, s44, 0x10000
	s_addc_u32 s41, s45, 0
	s_add_i32 s66, s67, s51
	s_add_i32 s65, 0, 0x1c000
	s_add_i32 s64, s66, 0x2000
	s_add_u32 s36, s46, 0x10080
	s_addc_u32 s37, s47, 0
	s_add_i32 s71, s65, s51
	s_add_i32 s70, s71, 0x2000
	v_lshl_add_u64 v[140:141], s[48:49], 0, v[128:129]
	ds_read_b128 v[158:161], v143
	ds_read_b128 v[162:165], v143 offset:1024
	ds_read_b128 v[166:169], v143 offset:2048
	ds_read_b128 v[170:173], v143 offset:3072
	ds_read_b128 v[174:177], v143 offset:4096
	ds_read_b128 v[178:181], v143 offset:5120
	ds_read_b128 v[196:199], v143 offset:6144
	ds_read_b128 v[200:203], v143 offset:7168
	global_load_lds_dwordx4 v[140:141], off
	v_lshl_add_u64 v[140:141], s[48:49], 0, v[132:133]
	s_mov_b32 m0, s75
	s_nop 0
	global_load_lds_dwordx4 v[140:141], off
	s_waitcnt lgkmcnt(8)
	s_barrier
	s_waitcnt lgkmcnt(0)
	v_mfma_f32_16x16x32_bf16 v[124:127], v[136:139], v[158:161], v[124:127]
	v_mfma_f32_16x16x32_bf16 v[120:123], v[150:153], v[158:161], v[120:123]
	v_mfma_f32_16x16x32_bf16 v[108:111], v[136:139], v[166:169], v[108:111]
	v_mfma_f32_16x16x32_bf16 v[104:107], v[150:153], v[166:169], v[104:107]
	v_mfma_f32_16x16x32_bf16 v[92:95], v[136:139], v[174:177], v[92:95]
	v_mfma_f32_16x16x32_bf16 v[88:91], v[150:153], v[174:177], v[88:91]
	v_mfma_f32_16x16x32_bf16 v[76:79], v[136:139], v[196:199], v[76:79]
	v_mfma_f32_16x16x32_bf16 v[72:75], v[150:153], v[196:199], v[72:75]
	v_mfma_f32_16x16x32_bf16 v[124:127], v[146:149], v[162:165], v[124:127]
	v_mfma_f32_16x16x32_bf16 v[120:123], v[154:157], v[162:165], v[120:123]
	v_mfma_f32_16x16x32_bf16 v[108:111], v[146:149], v[170:173], v[108:111]
	v_mfma_f32_16x16x32_bf16 v[104:107], v[154:157], v[170:173], v[104:107]
	v_mfma_f32_16x16x32_bf16 v[92:95], v[146:149], v[178:181], v[92:95]
	v_mfma_f32_16x16x32_bf16 v[88:91], v[154:157], v[178:181], v[88:91]
	v_mfma_f32_16x16x32_bf16 v[76:79], v[146:149], v[200:203], v[76:79]
	v_mfma_f32_16x16x32_bf16 v[72:75], v[154:157], v[200:203], v[72:75]
	s_barrier
	v_add_u32_e32 v140, s73, v142
	s_mov_b32 m0, s74
	ds_read_b128 v[204:207], v140
	ds_read_b128 v[208:211], v140 offset:1024
	ds_read_b128 v[212:215], v140 offset:2048
	ds_read_b128 v[216:219], v140 offset:3072
	v_lshl_add_u64 v[140:141], s[46:47], 0, v[130:131]
	global_load_lds_dwordx4 v[140:141], off
	v_lshl_add_u64 v[220:221], s[46:47], 0, v[134:135]
	s_mov_b32 m0, s72
	s_nop 0
	global_load_lds_dwordx4 v[220:221], off
	s_barrier
	s_waitcnt lgkmcnt(0)
	v_mfma_f32_16x16x32_bf16 v[116:119], v[204:207], v[158:161], v[116:119]
	v_mfma_f32_16x16x32_bf16 v[112:115], v[212:215], v[158:161], v[112:115]
	v_mfma_f32_16x16x32_bf16 v[100:103], v[204:207], v[166:169], v[100:103]
	v_mfma_f32_16x16x32_bf16 v[96:99], v[212:215], v[166:169], v[96:99]
	v_mfma_f32_16x16x32_bf16 v[84:87], v[204:207], v[174:177], v[84:87]
	v_mfma_f32_16x16x32_bf16 v[80:83], v[212:215], v[174:177], v[80:83]
	v_mfma_f32_16x16x32_bf16 v[68:71], v[204:207], v[196:199], v[68:71]
	v_mfma_f32_16x16x32_bf16 v[64:67], v[212:215], v[196:199], v[64:67]
	v_mfma_f32_16x16x32_bf16 v[116:119], v[208:211], v[162:165], v[116:119]
	v_mfma_f32_16x16x32_bf16 v[112:115], v[216:219], v[162:165], v[112:115]
	v_mfma_f32_16x16x32_bf16 v[100:103], v[208:211], v[170:173], v[100:103]
	v_mfma_f32_16x16x32_bf16 v[96:99], v[216:219], v[170:173], v[96:99]
	v_mfma_f32_16x16x32_bf16 v[84:87], v[208:211], v[178:181], v[84:87]
	v_mfma_f32_16x16x32_bf16 v[80:83], v[216:219], v[178:181], v[80:83]
	v_mfma_f32_16x16x32_bf16 v[68:71], v[208:211], v[200:203], v[68:71]
	v_mfma_f32_16x16x32_bf16 v[64:67], v[216:219], v[200:203], v[64:67]
	s_mov_b32 m0, s56
	v_lshl_add_u64 v[222:223], s[44:45], 0, v[128:129]
	s_barrier
	ds_read_b128 v[158:161], v143 offset:16384
	ds_read_b128 v[162:165], v143 offset:17408
	ds_read_b128 v[166:169], v143 offset:18432
	ds_read_b128 v[170:173], v143 offset:19456
	ds_read_b128 v[174:177], v143 offset:20480
	ds_read_b128 v[178:181], v143 offset:21504
	ds_read_b128 v[196:199], v143 offset:22528
	ds_read_b128 v[200:203], v143 offset:23552
	global_load_lds_dwordx4 v[222:223], off
	v_lshl_add_u64 v[224:225], s[44:45], 0, v[132:133]
	s_mov_b32 m0, s57
	s_nop 0
	global_load_lds_dwordx4 v[224:225], off
	s_barrier
; #define PG8_STAGE(bufoff, gbase, voff) do { _Pragma("unroll") for (int _i = 0; _i < 2; ++_i) \
;     __builtin_amdgcn_global_load_lds((const unsigned*)((const char*)(gbase) + (voff)[_i]), (LAS unsigned*)(lds + (bufoff) + ldsw + _i * 8192), 16, 0, 0); } while (0)
; #define PG8_LDA(dst, b, h) do { _Pragma("unroll") for (int m = 0; m < 4; ++m) _Pragma("unroll") for (int k = 0; k < 2; ++k) dst[m][k] = *(const LAS bf16x8*)(lds + PG8_SA(b, h) + aoff + m * 2048 + k * 1024); } while (0)
; #define PG8_LDB(dst, b, h) do { _Pragma("unroll") for (int n = 0; n < 2; ++n) _Pragma("unroll") for (int k = 0; k < 2; ++k) dst[n][k] = *(const LAS bf16x8*)(lds + PG8_SB(b, h) + boff + n * 2048 + k * 1024); } while (0)
; #define PG8_MMA(ai, bj, At, Bt) do { __builtin_amdgcn_s_setprio(1); _Pragma("unroll") for (int m = 0; m < 4; ++m) _Pragma("unroll") for (int n = 0; n < 2; ++n) _Pragma("unroll") for (int k = 0; k < 2; ++k) \
;     acc[ai][bj][m][n] = __builtin_amdgcn_mfma_f32_16x16x32_bf16(Bt[n][k], At[m][k], acc[ai][bj][m][n], 0, 0, 0); __builtin_amdgcn_s_setprio(0); } while (0)
; #define PG8_WAIT_V(n) asm volatile("s_waitcnt vmcnt(" #n ")" ::: "memory")
; #define PG8_WAIT_L(n) asm volatile("s_waitcnt lgkmcnt(" #n ")" ::: "memory")
; #define PG8_BAR __builtin_amdgcn_s_barrier()
; #define PG8_SCHED __builtin_amdgcn_sched_barrier(0)
; template <class Epi, class Sched>
; DI void gemm_phase(LAS unsigned char* lds, const Gemm g, const Sched& S, const Epi& E) {
;     ...
;       PG8_BAR; PG8_WAIT_L(0); PG8_MMA(1, 0, At, B0); PG8_BAR; PG8_SCHED;
;       PG8_STAGE(PG8_SB(0, 1), b2 + hstep, voffB);
;       PG8_WAIT_V(6); PG8_BAR; PG8_MMA(1, 1, At, B1); PG8_BAR;
;       PG8_LDB(B0, 1, 0); PG8_SCHED; PG8_LDA(At, 1, 0); PG8_STAGE(PG8_SA(0, 1), a2 + hstep, voffA);
;       PG8_WAIT_L(8); PG8_BAR; PG8_WAIT_L(0); PG8_MMA(0, 0, At, B0); PG8_BAR; PG8_SCHED;
;       PG8_LDB(B1, 1, 1); PG8_STAGE(PG8_SB(1, 0), b3, voffB);
;       PG8_BAR; PG8_WAIT_L(0); PG8_MMA(0, 1, At, B1); PG8_BAR;
;       PG8_LDA(At, 1, 1); PG8_STAGE(PG8_SA(1, 0), a3, voffA);
;       PG8_BAR; PG8_WAIT_L(0); PG8_MMA(1, 0, At, B0); PG8_BAR; PG8_SCHED;
	s_waitcnt lgkmcnt(0)
	v_mfma_f32_16x16x32_bf16 v[60:63], v[136:139], v[158:161], v[60:63]
	v_mfma_f32_16x16x32_bf16 v[56:59], v[150:153], v[158:161], v[56:59]
	v_mfma_f32_16x16x32_bf16 v[44:47], v[136:139], v[166:169], v[44:47]
	v_mfma_f32_16x16x32_bf16 v[40:43], v[150:153], v[166:169], v[40:43]
	v_mfma_f32_16x16x32_bf16 v[28:31], v[136:139], v[174:177], v[28:31]
	v_mfma_f32_16x16x32_bf16 v[24:27], v[150:153], v[174:177], v[24:27]
	v_mfma_f32_16x16x32_bf16 v[12:15], v[136:139], v[196:199], v[12:15]
	v_mfma_f32_16x16x32_bf16 v[8:11], v[150:153], v[196:199], v[8:11]
	v_mfma_f32_16x16x32_bf16 v[60:63], v[146:149], v[162:165], v[60:63]
	v_mfma_f32_16x16x32_bf16 v[56:59], v[154:157], v[162:165], v[56:59]
	v_mfma_f32_16x16x32_bf16 v[44:47], v[146:149], v[170:173], v[44:47]
	v_mfma_f32_16x16x32_bf16 v[40:43], v[154:157], v[170:173], v[40:43]
	v_mfma_f32_16x16x32_bf16 v[28:31], v[146:149], v[178:181], v[28:31]
	v_mfma_f32_16x16x32_bf16 v[24:27], v[154:157], v[178:181], v[24:27]
	v_mfma_f32_16x16x32_bf16 v[12:15], v[146:149], v[200:203], v[12:15]
	v_mfma_f32_16x16x32_bf16 v[8:11], v[154:157], v[200:203], v[8:11]
	s_barrier
	s_mov_b32 m0, s69
	v_lshl_add_u64 v[136:137], s[42:43], 0, v[130:131]
	global_load_lds_dwordx4 v[136:137], off
	v_lshl_add_u64 v[136:137], s[42:43], 0, v[134:135]
	s_mov_b32 m0, s68
	s_nop 0
	global_load_lds_dwordx4 v[136:137], off
	s_waitcnt vmcnt(6)
	s_barrier
	v_mfma_f32_16x16x32_bf16 v[52:55], v[204:207], v[158:161], v[52:55]
	v_mfma_f32_16x16x32_bf16 v[48:51], v[212:215], v[158:161], v[48:51]
	v_mfma_f32_16x16x32_bf16 v[36:39], v[204:207], v[166:169], v[36:39]
	v_mfma_f32_16x16x32_bf16 v[32:35], v[212:215], v[166:169], v[32:35]
	v_mfma_f32_16x16x32_bf16 v[20:23], v[204:207], v[174:177], v[20:23]
	v_mfma_f32_16x16x32_bf16 v[16:19], v[212:215], v[174:177], v[16:19]
	v_mfma_f32_16x16x32_bf16 v[4:7], v[204:207], v[196:199], v[4:7]
	v_mfma_f32_16x16x32_bf16 v[0:3], v[212:215], v[196:199], v[0:3]
	v_mfma_f32_16x16x32_bf16 v[52:55], v[208:211], v[162:165], v[52:55]
	v_mfma_f32_16x16x32_bf16 v[48:51], v[216:219], v[162:165], v[48:51]
	v_mfma_f32_16x16x32_bf16 v[36:39], v[208:211], v[170:173], v[36:39]
	v_mfma_f32_16x16x32_bf16 v[32:35], v[216:219], v[170:173], v[32:35]
	v_mfma_f32_16x16x32_bf16 v[20:23], v[208:211], v[178:181], v[20:23]
	v_mfma_f32_16x16x32_bf16 v[16:19], v[216:219], v[178:181], v[16:19]
	v_mfma_f32_16x16x32_bf16 v[4:7], v[208:211], v[200:203], v[4:7]
	v_mfma_f32_16x16x32_bf16 v[0:3], v[216:219], v[200:203], v[0:3]
	v_add_u32_e32 v144, s67, v142
	s_barrier
	ds_read_b128 v[136:139], v144
	ds_read_b128 v[146:149], v144 offset:1024
	ds_read_b128 v[150:153], v144 offset:2048
	ds_read_b128 v[154:157], v144 offset:3072
	s_mov_b32 m0, s58
	v_lshl_add_u64 v[204:205], s[40:41], 0, v[128:129]
	ds_read_b128 v[158:161], v143 offset:32768
	ds_read_b128 v[162:165], v143 offset:33792
	ds_read_b128 v[166:169], v143 offset:34816
	ds_read_b128 v[170:173], v143 offset:35840
	ds_read_b128 v[174:177], v143 offset:36864
	ds_read_b128 v[178:181], v143 offset:37888
	ds_read_b128 v[196:199], v143 offset:38912
	ds_read_b128 v[200:203], v143 offset:39936
	global_load_lds_dwordx4 v[204:205], off
	v_lshl_add_u64 v[204:205], s[40:41], 0, v[132:133]
	s_mov_b32 m0, s59
	s_nop 0
	global_load_lds_dwordx4 v[204:205], off
	s_waitcnt lgkmcnt(8)
	s_barrier
	s_waitcnt lgkmcnt(0)
	v_mfma_f32_16x16x32_bf16 v[124:127], v[136:139], v[158:161], v[124:127]
	v_mfma_f32_16x16x32_bf16 v[120:123], v[150:153], v[158:161], v[120:123]
	v_mfma_f32_16x16x32_bf16 v[108:111], v[136:139], v[166:169], v[108:111]
	v_mfma_f32_16x16x32_bf16 v[104:107], v[150:153], v[166:169], v[104:107]
	v_mfma_f32_16x16x32_bf16 v[92:95], v[136:139], v[174:177], v[92:95]
	v_mfma_f32_16x16x32_bf16 v[88:91], v[150:153], v[174:177], v[88:91]
	v_mfma_f32_16x16x32_bf16 v[76:79], v[136:139], v[196:199], v[76:79]
	v_mfma_f32_16x16x32_bf16 v[72:75], v[150:153], v[196:199], v[72:75]
	v_mfma_f32_16x16x32_bf16 v[124:127], v[146:149], v[162:165], v[124:127]
	v_mfma_f32_16x16x32_bf16 v[120:123], v[154:157], v[162:165], v[120:123]
	v_mfma_f32_16x16x32_bf16 v[108:111], v[146:149], v[170:173], v[108:111]
	v_mfma_f32_16x16x32_bf16 v[104:107], v[154:157], v[170:173], v[104:107]
	v_mfma_f32_16x16x32_bf16 v[92:95], v[146:149], v[178:181], v[92:95]
	v_mfma_f32_16x16x32_bf16 v[88:91], v[154:157], v[178:181], v[88:91]
	v_mfma_f32_16x16x32_bf16 v[76:79], v[146:149], v[200:203], v[76:79]
	v_mfma_f32_16x16x32_bf16 v[72:75], v[154:157], v[200:203], v[72:75]
	s_barrier
	s_mov_b32 m0, s66
	v_add_u32_e32 v144, s65, v142
	v_lshl_add_u64 v[140:141], v[140:141], 0, s[0:1]
	ds_read_b128 v[204:207], v144
	ds_read_b128 v[208:211], v144 offset:1024
	ds_read_b128 v[212:215], v144 offset:2048
	ds_read_b128 v[216:219], v144 offset:3072
	global_load_lds_dwordx4 v[140:141], off
	v_lshl_add_u64 v[140:141], v[220:221], 0, s[0:1]
	s_mov_b32 m0, s64
	s_nop 0
	global_load_lds_dwordx4 v[140:141], off
	s_barrier
; #define PG8_STAGE(bufoff, gbase, voff) do { _Pragma("unroll") for (int _i = 0; _i < 2; ++_i) \
;     __builtin_amdgcn_global_load_lds((const unsigned*)((const char*)(gbase) + (voff)[_i]), (LAS unsigned*)(lds + (bufoff) + ldsw + _i * 8192), 16, 0, 0); } while (0)
; #define PG8_MMA(ai, bj, At, Bt) do { __builtin_amdgcn_s_setprio(1); _Pragma("unroll") for (int m = 0; m < 4; ++m) _Pragma("unroll") for (int n = 0; n < 2; ++n) _Pragma("unroll") for (int k = 0; k < 2; ++k) \
;     acc[ai][bj][m][n] = __builtin_amdgcn_mfma_f32_16x16x32_bf16(Bt[n][k], At[m][k], acc[ai][bj][m][n], 0, 0, 0); __builtin_amdgcn_s_setprio(0); } while (0)
; #define PG8_WAIT_V(n) asm volatile("s_waitcnt vmcnt(" #n ")" ::: "memory")
; #define PG8_WAIT_L(n) asm volatile("s_waitcnt lgkmcnt(" #n ")" ::: "memory")
; #define PG8_BAR __builtin_amdgcn_s_barrier()
; #define PG8_SCHED __builtin_amdgcn_sched_barrier(0)
; template <class Epi, class Sched>
; DI void gemm_phase(LAS unsigned char* lds, const Gemm g, const Sched& S, const Epi& E) {
;     ...
;       PG8_BAR; PG8_WAIT_L(0); PG8_MMA(1, 0, At, B0); PG8_BAR; PG8_SCHED;
;       PG8_STAGE(PG8_SB(1, 1), b3 + hstep, voffB);
;       PG8_WAIT_V(6); PG8_BAR; PG8_MMA(1, 1, At, B1); PG8_BAR;
;   DI void operator()(const f32x4 (&acc)[2][2][4][2], const pg8::Unit& u, int wr, int wc, int fr_, int fq_) const {
;     ...
;             } else if (EPI == EPI_UKV) {
;               if (n == 0) {
;                 const int gb = u.pn * 256 + bj * 128 + wc * 32;
;                 const int hd = gb >> 7, within = (gb & 127) + 8 * fq;
;                 const f32x4 v1 = acc[ai][bj][m][1];
;                 if (within < 64) st_bf8((u16*)(big + E_KNOPE) + (size_t)token * 512 + hd * 64 + within, v, v1, rinv);
;                 else st_bf8((u16*)(big + E_VMLAT) + (size_t)token * 512 + hd * 64 + (within - 64), v, v1, rinv);
	s_waitcnt lgkmcnt(0)
	v_mfma_f32_16x16x32_bf16 v[116:119], v[204:207], v[158:161], v[116:119]
	v_mfma_f32_16x16x32_bf16 v[112:115], v[212:215], v[158:161], v[112:115]
	v_mfma_f32_16x16x32_bf16 v[100:103], v[204:207], v[166:169], v[100:103]
	v_mfma_f32_16x16x32_bf16 v[96:99], v[212:215], v[166:169], v[96:99]
	v_mfma_f32_16x16x32_bf16 v[84:87], v[204:207], v[174:177], v[84:87]
	v_mfma_f32_16x16x32_bf16 v[80:83], v[212:215], v[174:177], v[80:83]
	v_mfma_f32_16x16x32_bf16 v[68:71], v[204:207], v[196:199], v[68:71]
	v_mfma_f32_16x16x32_bf16 v[64:67], v[212:215], v[196:199], v[64:67]
	v_mfma_f32_16x16x32_bf16 v[116:119], v[208:211], v[162:165], v[116:119]
	v_mfma_f32_16x16x32_bf16 v[112:115], v[216:219], v[162:165], v[112:115]
	v_mfma_f32_16x16x32_bf16 v[100:103], v[208:211], v[170:173], v[100:103]
	v_mfma_f32_16x16x32_bf16 v[96:99], v[216:219], v[170:173], v[96:99]
	v_mfma_f32_16x16x32_bf16 v[84:87], v[208:211], v[178:181], v[84:87]
	v_mfma_f32_16x16x32_bf16 v[80:83], v[216:219], v[178:181], v[80:83]
	v_mfma_f32_16x16x32_bf16 v[68:71], v[208:211], v[200:203], v[68:71]
	v_mfma_f32_16x16x32_bf16 v[64:67], v[216:219], v[200:203], v[64:67]
	s_mov_b32 m0, s62
	v_lshl_add_u64 v[140:141], v[222:223], 0, s[0:1]
	s_barrier
	ds_read_b128 v[158:161], v143 offset:49152
	ds_read_b128 v[162:165], v143 offset:50176
	ds_read_b128 v[166:169], v143 offset:51200
	ds_read_b128 v[170:173], v143 offset:52224
	ds_read_b128 v[174:177], v143 offset:53248
	ds_read_b128 v[178:181], v143 offset:54272
	ds_read_b128 v[196:199], v143 offset:55296
	ds_read_b128 v[200:203], v143 offset:56320
	global_load_lds_dwordx4 v[140:141], off
	v_lshl_add_u64 v[140:141], v[224:225], 0, s[0:1]
	s_mov_b32 m0, s63
	s_nop 0
	global_load_lds_dwordx4 v[140:141], off
	s_barrier
	s_waitcnt lgkmcnt(0)
	v_mfma_f32_16x16x32_bf16 v[60:63], v[136:139], v[158:161], v[60:63]
	v_mfma_f32_16x16x32_bf16 v[56:59], v[150:153], v[158:161], v[56:59]
	v_mfma_f32_16x16x32_bf16 v[44:47], v[136:139], v[166:169], v[44:47]
	v_mfma_f32_16x16x32_bf16 v[40:43], v[150:153], v[166:169], v[40:43]
	v_mfma_f32_16x16x32_bf16 v[28:31], v[136:139], v[174:177], v[28:31]
	v_mfma_f32_16x16x32_bf16 v[24:27], v[150:153], v[174:177], v[24:27]
	v_mfma_f32_16x16x32_bf16 v[12:15], v[136:139], v[196:199], v[12:15]
	v_mfma_f32_16x16x32_bf16 v[8:11], v[150:153], v[196:199], v[8:11]
	v_mfma_f32_16x16x32_bf16 v[60:63], v[146:149], v[162:165], v[60:63]
	v_mfma_f32_16x16x32_bf16 v[56:59], v[154:157], v[162:165], v[56:59]
	v_mfma_f32_16x16x32_bf16 v[44:47], v[146:149], v[170:173], v[44:47]
	v_mfma_f32_16x16x32_bf16 v[40:43], v[154:157], v[170:173], v[40:43]
	v_mfma_f32_16x16x32_bf16 v[28:31], v[146:149], v[178:181], v[28:31]
	v_mfma_f32_16x16x32_bf16 v[24:27], v[154:157], v[178:181], v[24:27]
	v_mfma_f32_16x16x32_bf16 v[12:15], v[146:149], v[200:203], v[12:15]
	v_mfma_f32_16x16x32_bf16 v[8:11], v[154:157], v[200:203], v[8:11]
	s_barrier
	s_mov_b32 m0, s71
	v_lshl_add_u64 v[136:137], s[36:37], 0, v[130:131]
	global_load_lds_dwordx4 v[136:137], off
	v_lshl_add_u64 v[136:137], s[36:37], 0, v[134:135]
	s_mov_b32 m0, s70
	s_nop 0
	global_load_lds_dwordx4 v[136:137], off
	s_waitcnt vmcnt(6)
	s_barrier
	v_mfma_f32_16x16x32_bf16 v[52:55], v[204:207], v[158:161], v[52:55]
	v_mfma_f32_16x16x32_bf16 v[48:51], v[212:215], v[158:161], v[48:51]
	v_mfma_f32_16x16x32_bf16 v[36:39], v[204:207], v[166:169], v[36:39]
	v_mfma_f32_16x16x32_bf16 v[32:35], v[212:215], v[166:169], v[32:35]
	v_mfma_f32_16x16x32_bf16 v[20:23], v[204:207], v[174:177], v[20:23]
	v_mfma_f32_16x16x32_bf16 v[16:19], v[212:215], v[174:177], v[16:19]
	v_mfma_f32_16x16x32_bf16 v[4:7], v[204:207], v[196:199], v[4:7]
	v_mfma_f32_16x16x32_bf16 v[0:3], v[212:215], v[196:199], v[0:3]
	v_mfma_f32_16x16x32_bf16 v[52:55], v[208:211], v[162:165], v[52:55]
	v_mfma_f32_16x16x32_bf16 v[48:51], v[216:219], v[162:165], v[48:51]
	v_mfma_f32_16x16x32_bf16 v[36:39], v[208:211], v[170:173], v[36:39]
	v_mfma_f32_16x16x32_bf16 v[32:35], v[216:219], v[170:173], v[32:35]
	v_mfma_f32_16x16x32_bf16 v[20:23], v[208:211], v[178:181], v[20:23]
	v_mfma_f32_16x16x32_bf16 v[16:19], v[216:219], v[178:181], v[16:19]
	v_mfma_f32_16x16x32_bf16 v[4:7], v[208:211], v[200:203], v[4:7]
	v_mfma_f32_16x16x32_bf16 v[0:3], v[216:219], v[200:203], v[0:3]
	s_andn2_b64 vcc, exec, s[34:35]
	s_mov_b64 s[36:37], -1
	s_mov_b64 s[34:35], 0
	s_mov_b64 s[40:41], 0x100
	s_barrier
	s_cbranch_vccz .LBB0_1346
	v_mov_b32_e32 v136, v182
	s_lshl_b32 s3, s3, 10
	s_add_i32 s3, s3, 0
	v_and_or_b32 v147, v136, 15, s60
	v_lshl_add_u32 v137, v147, 2, s3
	v_add_u32_e32 v146, 0x20000, v137
	ds_read_b32 v138, v146
	s_lshl_b32 s13, s20, 8
	v_lshrrev_b32_e32 v136, 1, v136
	v_and_or_b32 v139, v136, 24, s61
	v_add_u32_e32 v136, s13, v147
	v_ashrrev_i32_e32 v137, 31, v136
	s_waitcnt lgkmcnt(0)
	v_pk_mul_f32 v[124:125], v[124:125], v[138:139] op_sel_hi:[1,0]
	v_pk_mul_f32 v[126:127], v[126:127], v[138:139] op_sel_hi:[1,0]
	v_pk_mul_f32 v[120:121], v[120:121], v[138:139] op_sel_hi:[1,0]
	v_lshlrev_b64 v[140:141], 10, v[136:137]
	s_lshl_b32 s20, s2, 7
	v_cvt_pk_bf16_f32 v124, v124, v125
	v_cvt_pk_bf16_f32 v125, v126, v127
	v_cvt_pk_bf16_f32 v126, v120, v121
	v_pk_mul_f32 v[120:121], v[122:123], v[138:139] op_sel_hi:[1,0]
	s_ashr_i32 s21, s20, 31
	v_cvt_pk_bf16_f32 v127, v120, v121
	v_lshl_add_u64 v[120:121], s[6:7], 0, v[140:141]
	s_mov_b64 s[2:3], -1
	s_and_b64 vcc, exec, s[4:5]
	v_lshl_add_u64 v[120:121], s[20:21], 1, v[120:121]
	v_lshlrev_b32_e32 v144, 1, v139
	s_cbranch_vccz .LBB0_1349
	v_lshl_add_u64 v[122:123], v[120:121], 0, v[144:145]
	v_add_co_u32_e32 v122, vcc, 0xd9ff000, v122
	s_mov_b64 s[2:3], 0
	s_nop 0
	v_addc_co_u32_e32 v123, vcc, 0, v123, vcc
	global_store_dwordx4 v[122:123], v[124:127], off offset:3968

; #define PG8_STAGE(bufoff, gbase, voff) do { _Pragma("unroll") for (int _i = 0; _i < 2; ++_i) \
;     __builtin_amdgcn_global_load_lds((const unsigned*)((const char*)(gbase) + (voff)[_i]), (LAS unsigned*)(lds + (bufoff) + ldsw + _i * 8192), 16, 0, 0); } while (0)
; #define PG8_LDA(dst, b, h) do { _Pragma("unroll") for (int m = 0; m < 4; ++m) _Pragma("unroll") for (int k = 0; k < 2; ++k) dst[m][k] = *(const LAS bf16x8*)(lds + PG8_SA(b, h) + aoff + m * 2048 + k * 1024); } while (0)
; #define PG8_LDB(dst, b, h) do { _Pragma("unroll") for (int n = 0; n < 2; ++n) _Pragma("unroll") for (int k = 0; k < 2; ++k) dst[n][k] = *(const LAS bf16x8*)(lds + PG8_SB(b, h) + boff + n * 2048 + k * 1024); } while (0)
; #define PG8_MMA(ai, bj, At, Bt) do { __builtin_amdgcn_s_setprio(1); _Pragma("unroll") for (int m = 0; m < 4; ++m) _Pragma("unroll") for (int n = 0; n < 2; ++n) _Pragma("unroll") for (int k = 0; k < 2; ++k) \
;     acc[ai][bj][m][n] = __builtin_amdgcn_mfma_f32_16x16x32_bf16(Bt[n][k], At[m][k], acc[ai][bj][m][n], 0, 0, 0); __builtin_amdgcn_s_setprio(0); } while (0)
; template <class Epi, class Sched>
; DI void gemm_phase(LAS unsigned char* lds, const Gemm g, const Sched& S, const Epi& E) {
;     ...
;       const bool last = (t == nt - 2);
;       const char* a1 = cA + (size_t)(t + 1) * kstep;
;       const char* a2 = last ? nA : cA + (size_t)(t + 2) * kstep; const char* b2 = last ? nB : cB + (size_t)(t + 2) * kstep;
;       const char* a3 = a2 + kstep; const char* b3 = b2 + kstep;
;       PG8_LDB(B0, 0, 0); PG8_SCHED; PG8_LDA(At, 0, 0); PG8_STAGE(PG8_SA(1, 1), a1 + hstep, voffA);
;       PG8_WAIT_L(8); PG8_BAR; PG8_WAIT_L(0); PG8_MMA(0, 0, At, B0); PG8_BAR; PG8_SCHED;
;       PG8_LDB(B1, 0, 1); PG8_STAGE(PG8_SB(0, 0), b2, voffB);
;       PG8_BAR; PG8_WAIT_L(0); PG8_MMA(0, 1, At, B1); PG8_BAR;
;       PG8_LDA(At, 0, 1); PG8_STAGE(PG8_SA(0, 0), a2, voffA);
;       PG8_BAR; PG8_WAIT_L(0); PG8_MMA(1, 0, At, B0); PG8_BAR; PG8_SCHED;
;       PG8_STAGE(PG8_SB(0, 1), b2 + hstep, voffB);
;       PG8_WAIT_V(6); PG8_BAR; PG8_MMA(1, 1, At, B1); PG8_BAR;
;       PG8_LDB(B0, 1, 0); PG8_SCHED; PG8_LDA(At, 1, 0); PG8_STAGE(PG8_SA(0, 1), a2 + hstep, voffA);
;       PG8_WAIT_L(8); PG8_BAR; PG8_WAIT_L(0); PG8_MMA(0, 0, At, B0); PG8_BAR; PG8_SCHED;
;       PG8_LDB(B1, 1, 1); PG8_STAGE(PG8_SB(1, 0), b3, voffB);
;       PG8_BAR; PG8_WAIT_L(0); PG8_MMA(0, 1, At, B1); PG8_BAR;
.LBB0_1644:
	s_add_u32 s4, s2, 0xfffc0080
	s_addc_u32 s5, s3, -1
	s_add_i32 s55, 0, 0x10000
	v_add_u32_e32 v152, s55, v158
	ds_read_b128 v[128:131], v152
	ds_read_b128 v[132:135], v152 offset:1024
	ds_read_b128 v[148:151], v152 offset:2048
	ds_read_b128 v[152:155], v152 offset:3072
	s_cmp_eq_u32 s54, 12
	s_cselect_b32 s29, s19, s5
	s_cselect_b32 s28, s35, s4
	s_cselect_b32 s5, s17, s53
	s_cselect_b32 s4, s51, s52
	v_lshl_add_u64 v[156:157], s[2:3], 0, v[142:143]
	s_add_i32 m0, s41, 0xc000
	ds_read_b128 v[160:163], v159
	ds_read_b128 v[164:167], v159 offset:1024
	ds_read_b128 v[168:171], v159 offset:2048
	ds_read_b128 v[172:175], v159 offset:3072
	ds_read_b128 v[176:179], v159 offset:4096
	ds_read_b128 v[196:199], v159 offset:5120
	ds_read_b128 v[200:203], v159 offset:6144
	ds_read_b128 v[204:207], v159 offset:7168
	global_load_lds_dwordx4 v[156:157], off
	v_lshl_add_u64 v[156:157], s[2:3], 0, v[146:147]
	s_add_i32 m0, s41, 0xe000
	s_nop 0
	global_load_lds_dwordx4 v[156:157], off
	s_waitcnt lgkmcnt(8)
	s_barrier
	s_waitcnt lgkmcnt(0)
	v_mfma_f32_16x16x32_bf16 v[124:127], v[128:131], v[160:163], v[124:127]
	v_mfma_f32_16x16x32_bf16 v[120:123], v[148:151], v[160:163], v[120:123]
	v_mfma_f32_16x16x32_bf16 v[108:111], v[128:131], v[168:171], v[108:111]
	v_mfma_f32_16x16x32_bf16 v[104:107], v[148:151], v[168:171], v[104:107]
	v_mfma_f32_16x16x32_bf16 v[92:95], v[128:131], v[176:179], v[92:95]
	v_mfma_f32_16x16x32_bf16 v[88:91], v[148:151], v[176:179], v[88:91]
	v_mfma_f32_16x16x32_bf16 v[76:79], v[128:131], v[200:203], v[76:79]
	v_mfma_f32_16x16x32_bf16 v[72:75], v[148:151], v[200:203], v[72:75]
	v_mfma_f32_16x16x32_bf16 v[124:127], v[132:135], v[164:167], v[124:127]
	v_mfma_f32_16x16x32_bf16 v[120:123], v[152:155], v[164:167], v[120:123]
	v_mfma_f32_16x16x32_bf16 v[108:111], v[132:135], v[172:175], v[108:111]
	v_mfma_f32_16x16x32_bf16 v[104:107], v[152:155], v[172:175], v[104:107]
	v_mfma_f32_16x16x32_bf16 v[92:95], v[132:135], v[196:199], v[92:95]
	v_mfma_f32_16x16x32_bf16 v[88:91], v[152:155], v[196:199], v[88:91]
	v_mfma_f32_16x16x32_bf16 v[76:79], v[132:135], v[204:207], v[76:79]
	v_mfma_f32_16x16x32_bf16 v[72:75], v[152:155], v[204:207], v[72:75]
	s_barrier
	s_add_i32 s58, 0, 0x14000
	v_add_u32_e32 v156, s58, v158
	s_add_i32 s55, s55, s40
	ds_read_b128 v[208:211], v156
	ds_read_b128 v[212:215], v156 offset:1024
	ds_read_b128 v[216:219], v156 offset:2048
	ds_read_b128 v[220:223], v156 offset:3072
	v_lshl_add_u64 v[156:157], s[4:5], 0, v[144:145]
	s_mov_b32 m0, s55
	v_lshl_add_u64 v[180:181], s[4:5], 0, v[136:137]
	global_load_lds_dwordx4 v[156:157], off
	s_add_i32 m0, s55, 0x2000
	s_nop 0
	global_load_lds_dwordx4 v[180:181], off
	s_barrier
	s_waitcnt lgkmcnt(0)
	v_mfma_f32_16x16x32_bf16 v[116:119], v[208:211], v[160:163], v[116:119]
	v_mfma_f32_16x16x32_bf16 v[112:115], v[216:219], v[160:163], v[112:115]
	v_mfma_f32_16x16x32_bf16 v[100:103], v[208:211], v[168:171], v[100:103]
	v_mfma_f32_16x16x32_bf16 v[96:99], v[216:219], v[168:171], v[96:99]
	v_mfma_f32_16x16x32_bf16 v[84:87], v[208:211], v[176:179], v[84:87]
	v_mfma_f32_16x16x32_bf16 v[80:83], v[216:219], v[176:179], v[80:83]
	v_mfma_f32_16x16x32_bf16 v[68:71], v[208:211], v[200:203], v[68:71]
	v_mfma_f32_16x16x32_bf16 v[64:67], v[216:219], v[200:203], v[64:67]
	v_mfma_f32_16x16x32_bf16 v[116:119], v[212:215], v[164:167], v[116:119]
	v_mfma_f32_16x16x32_bf16 v[112:115], v[220:223], v[164:167], v[112:115]
	v_mfma_f32_16x16x32_bf16 v[100:103], v[212:215], v[172:175], v[100:103]
	v_mfma_f32_16x16x32_bf16 v[96:99], v[220:223], v[172:175], v[96:99]
	v_mfma_f32_16x16x32_bf16 v[84:87], v[212:215], v[196:199], v[84:87]
	v_mfma_f32_16x16x32_bf16 v[80:83], v[220:223], v[196:199], v[80:83]
	v_mfma_f32_16x16x32_bf16 v[68:71], v[212:215], v[204:207], v[68:71]
	v_mfma_f32_16x16x32_bf16 v[64:67], v[220:223], v[204:207], v[64:67]
	s_mov_b32 m0, s41
	v_lshl_add_u64 v[224:225], s[28:29], 0, v[140:141]
	s_barrier
	ds_read_b128 v[160:163], v159 offset:16384
	ds_read_b128 v[164:167], v159 offset:17408
	ds_read_b128 v[168:171], v159 offset:18432
	ds_read_b128 v[172:175], v159 offset:19456
	ds_read_b128 v[176:179], v159 offset:20480
	ds_read_b128 v[196:199], v159 offset:21504
	ds_read_b128 v[200:203], v159 offset:22528
	ds_read_b128 v[204:207], v159 offset:23552
	global_load_lds_dwordx4 v[224:225], off
	v_lshl_add_u64 v[226:227], s[28:29], 0, v[138:139]
	s_mov_b32 m0, s42
	s_nop 0
	global_load_lds_dwordx4 v[226:227], off
	s_barrier
	s_waitcnt lgkmcnt(0)
	v_mfma_f32_16x16x32_bf16 v[60:63], v[128:131], v[160:163], v[60:63]
	v_mfma_f32_16x16x32_bf16 v[56:59], v[148:151], v[160:163], v[56:59]
	v_mfma_f32_16x16x32_bf16 v[44:47], v[128:131], v[168:171], v[44:47]
	v_mfma_f32_16x16x32_bf16 v[40:43], v[148:151], v[168:171], v[40:43]
	v_mfma_f32_16x16x32_bf16 v[28:31], v[128:131], v[176:179], v[28:31]
	v_mfma_f32_16x16x32_bf16 v[24:27], v[148:151], v[176:179], v[24:27]
	v_mfma_f32_16x16x32_bf16 v[12:15], v[128:131], v[200:203], v[12:15]
	v_mfma_f32_16x16x32_bf16 v[8:11], v[148:151], v[200:203], v[8:11]
	v_mfma_f32_16x16x32_bf16 v[60:63], v[132:135], v[164:167], v[60:63]
	v_mfma_f32_16x16x32_bf16 v[56:59], v[152:155], v[164:167], v[56:59]
	v_mfma_f32_16x16x32_bf16 v[44:47], v[132:135], v[172:175], v[44:47]
	v_mfma_f32_16x16x32_bf16 v[40:43], v[152:155], v[172:175], v[40:43]
	v_mfma_f32_16x16x32_bf16 v[28:31], v[132:135], v[196:199], v[28:31]
	v_mfma_f32_16x16x32_bf16 v[24:27], v[152:155], v[196:199], v[24:27]
	v_mfma_f32_16x16x32_bf16 v[12:15], v[132:135], v[204:207], v[12:15]
	v_mfma_f32_16x16x32_bf16 v[8:11], v[152:155], v[204:207], v[8:11]
	s_barrier
; #define PG8_STAGE(bufoff, gbase, voff) do { _Pragma("unroll") for (int _i = 0; _i < 2; ++_i) \
;     __builtin_amdgcn_global_load_lds((const unsigned*)((const char*)(gbase) + (voff)[_i]), (LAS unsigned*)(lds + (bufoff) + ldsw + _i * 8192), 16, 0, 0); } while (0)
; #define PG8_LDA(dst, b, h) do { _Pragma("unroll") for (int m = 0; m < 4; ++m) _Pragma("unroll") for (int k = 0; k < 2; ++k) dst[m][k] = *(const LAS bf16x8*)(lds + PG8_SA(b, h) + aoff + m * 2048 + k * 1024); } while (0)
; #define PG8_LDB(dst, b, h) do { _Pragma("unroll") for (int n = 0; n < 2; ++n) _Pragma("unroll") for (int k = 0; k < 2; ++k) dst[n][k] = *(const LAS bf16x8*)(lds + PG8_SB(b, h) + boff + n * 2048 + k * 1024); } while (0)
; #define PG8_MMA(ai, bj, At, Bt) do { __builtin_amdgcn_s_setprio(1); _Pragma("unroll") for (int m = 0; m < 4; ++m) _Pragma("unroll") for (int n = 0; n < 2; ++n) _Pragma("unroll") for (int k = 0; k < 2; ++k) \
;     acc[ai][bj][m][n] = __builtin_amdgcn_mfma_f32_16x16x32_bf16(Bt[n][k], At[m][k], acc[ai][bj][m][n], 0, 0, 0); __builtin_amdgcn_s_setprio(0); } while (0)
; #define PG8_WAIT_V(n) asm volatile("s_waitcnt vmcnt(" #n ")" ::: "memory")
; #define PG8_WAIT_L(n) asm volatile("s_waitcnt lgkmcnt(" #n ")" ::: "memory")
; #define PG8_BAR __builtin_amdgcn_s_barrier()
; #define PG8_SCHED __builtin_amdgcn_sched_barrier(0)
; template <class Epi, class Sched>
; DI void gemm_phase(LAS unsigned char* lds, const Gemm g, const Sched& S, const Epi& E) {
;     ...
;       PG8_BAR; PG8_WAIT_L(0); PG8_MMA(1, 0, At, B0); PG8_BAR; PG8_SCHED;
;       PG8_STAGE(PG8_SB(0, 1), b2 + hstep, voffB);
;       PG8_WAIT_V(6); PG8_BAR; PG8_MMA(1, 1, At, B1); PG8_BAR;
;       PG8_LDB(B0, 1, 0); PG8_SCHED; PG8_LDA(At, 1, 0); PG8_STAGE(PG8_SA(0, 1), a2 + hstep, voffA);
;       PG8_WAIT_L(8); PG8_BAR; PG8_WAIT_L(0); PG8_MMA(0, 0, At, B0); PG8_BAR; PG8_SCHED;
;       PG8_LDB(B1, 1, 1); PG8_STAGE(PG8_SB(1, 0), b3, voffB);
;       PG8_BAR; PG8_WAIT_L(0); PG8_MMA(0, 1, At, B1); PG8_BAR;
;       PG8_LDA(At, 1, 1); PG8_STAGE(PG8_SA(1, 0), a3, voffA);
;       PG8_BAR; PG8_WAIT_L(0); PG8_MMA(1, 0, At, B0); PG8_BAR; PG8_SCHED;
	s_add_u32 s56, s4, 0x40000
	s_addc_u32 s57, s5, 0
	s_add_i32 s55, s58, s40
	v_lshl_add_u64 v[128:129], s[56:57], 0, v[144:145]
	s_mov_b32 m0, s55
	s_nop 0
	global_load_lds_dwordx4 v[128:129], off
	v_lshl_add_u64 v[128:129], s[56:57], 0, v[136:137]
	s_add_i32 m0, s55, 0x2000
	s_nop 0
	global_load_lds_dwordx4 v[128:129], off
	s_waitcnt vmcnt(6)
	s_barrier
	v_mfma_f32_16x16x32_bf16 v[52:55], v[208:211], v[160:163], v[52:55]
	v_mfma_f32_16x16x32_bf16 v[48:51], v[216:219], v[160:163], v[48:51]
	v_mfma_f32_16x16x32_bf16 v[36:39], v[208:211], v[168:171], v[36:39]
	v_mfma_f32_16x16x32_bf16 v[32:35], v[216:219], v[168:171], v[32:35]
	v_mfma_f32_16x16x32_bf16 v[20:23], v[208:211], v[176:179], v[20:23]
	v_mfma_f32_16x16x32_bf16 v[16:19], v[216:219], v[176:179], v[16:19]
	v_mfma_f32_16x16x32_bf16 v[4:7], v[208:211], v[200:203], v[4:7]
	v_mfma_f32_16x16x32_bf16 v[0:3], v[216:219], v[200:203], v[0:3]
	v_mfma_f32_16x16x32_bf16 v[52:55], v[212:215], v[164:167], v[52:55]
	v_mfma_f32_16x16x32_bf16 v[48:51], v[220:223], v[164:167], v[48:51]
	v_mfma_f32_16x16x32_bf16 v[36:39], v[212:215], v[172:175], v[36:39]
	v_mfma_f32_16x16x32_bf16 v[32:35], v[220:223], v[172:175], v[32:35]
	v_mfma_f32_16x16x32_bf16 v[20:23], v[212:215], v[196:199], v[20:23]
	v_mfma_f32_16x16x32_bf16 v[16:19], v[220:223], v[196:199], v[16:19]
	v_mfma_f32_16x16x32_bf16 v[4:7], v[212:215], v[204:207], v[4:7]
	v_mfma_f32_16x16x32_bf16 v[0:3], v[220:223], v[204:207], v[0:3]
	s_add_i32 s55, 0, 0x18000
	v_add_u32_e32 v152, s55, v158
	s_barrier
	ds_read_b128 v[128:131], v152
	ds_read_b128 v[132:135], v152 offset:1024
	ds_read_b128 v[148:151], v152 offset:2048
	ds_read_b128 v[152:155], v152 offset:3072
	s_add_u32 s28, s28, 0x40000
	s_addc_u32 s29, s29, 0
	s_mov_b32 m0, s43
	v_lshl_add_u64 v[208:209], s[28:29], 0, v[140:141]
	ds_read_b128 v[160:163], v159 offset:32768
	ds_read_b128 v[164:167], v159 offset:33792
	ds_read_b128 v[168:171], v159 offset:34816
	ds_read_b128 v[172:175], v159 offset:35840
	ds_read_b128 v[176:179], v159 offset:36864
	ds_read_b128 v[196:199], v159 offset:37888
	ds_read_b128 v[200:203], v159 offset:38912
	ds_read_b128 v[204:207], v159 offset:39936
	global_load_lds_dwordx4 v[208:209], off
	v_lshl_add_u64 v[208:209], s[28:29], 0, v[138:139]
	s_mov_b32 m0, s44
	s_nop 0
	global_load_lds_dwordx4 v[208:209], off
	s_waitcnt lgkmcnt(8)
	s_barrier
	s_waitcnt lgkmcnt(0)
	v_mfma_f32_16x16x32_bf16 v[124:127], v[128:131], v[160:163], v[124:127]
	v_mfma_f32_16x16x32_bf16 v[120:123], v[148:151], v[160:163], v[120:123]
	v_mfma_f32_16x16x32_bf16 v[108:111], v[128:131], v[168:171], v[108:111]
	v_mfma_f32_16x16x32_bf16 v[104:107], v[148:151], v[168:171], v[104:107]
	v_mfma_f32_16x16x32_bf16 v[92:95], v[128:131], v[176:179], v[92:95]
	v_mfma_f32_16x16x32_bf16 v[88:91], v[148:151], v[176:179], v[88:91]
	v_mfma_f32_16x16x32_bf16 v[76:79], v[128:131], v[200:203], v[76:79]
	v_mfma_f32_16x16x32_bf16 v[72:75], v[148:151], v[200:203], v[72:75]
	v_mfma_f32_16x16x32_bf16 v[124:127], v[132:135], v[164:167], v[124:127]
	v_mfma_f32_16x16x32_bf16 v[120:123], v[152:155], v[164:167], v[120:123]
	v_mfma_f32_16x16x32_bf16 v[108:111], v[132:135], v[172:175], v[108:111]
	v_mfma_f32_16x16x32_bf16 v[104:107], v[152:155], v[172:175], v[104:107]
	v_mfma_f32_16x16x32_bf16 v[92:95], v[132:135], v[196:199], v[92:95]
	v_mfma_f32_16x16x32_bf16 v[88:91], v[152:155], v[196:199], v[88:91]
	v_mfma_f32_16x16x32_bf16 v[76:79], v[132:135], v[204:207], v[76:79]
	v_mfma_f32_16x16x32_bf16 v[72:75], v[152:155], v[204:207], v[72:75]
	s_barrier
	s_add_i32 s28, 0, 0x1c000
	s_add_i32 s29, s55, s40
	v_add_u32_e32 v220, s28, v158
	v_lshl_add_u64 v[156:157], v[156:157], 0, s[0:1]
	s_mov_b32 m0, s29
	ds_read_b128 v[208:211], v220
	ds_read_b128 v[212:215], v220 offset:1024
	ds_read_b128 v[216:219], v220 offset:2048
	ds_read_b128 v[220:223], v220 offset:3072
	global_load_lds_dwordx4 v[156:157], off
	v_lshl_add_u64 v[156:157], v[180:181], 0, s[0:1]
	s_add_i32 m0, s29, 0x2000
	s_nop 0
	global_load_lds_dwordx4 v[156:157], off
	s_barrier
; DI float bf2f(unsigned v) { return __uint_as_float(v << 16); }
; #define PG8_STAGE(bufoff, gbase, voff) do { _Pragma("unroll") for (int _i = 0; _i < 2; ++_i) \
;     __builtin_amdgcn_global_load_lds((const unsigned*)((const char*)(gbase) + (voff)[_i]), (LAS unsigned*)(lds + (bufoff) + ldsw + _i * 8192), 16, 0, 0); } while (0)
; #define PG8_LDA(dst, b, h) do { _Pragma("unroll") for (int m = 0; m < 4; ++m) _Pragma("unroll") for (int k = 0; k < 2; ++k) dst[m][k] = *(const LAS bf16x8*)(lds + PG8_SA(b, h) + aoff + m * 2048 + k * 1024); } while (0)
; #define PG8_MMA(ai, bj, At, Bt) do { __builtin_amdgcn_s_setprio(1); _Pragma("unroll") for (int m = 0; m < 4; ++m) _Pragma("unroll") for (int n = 0; n < 2; ++n) _Pragma("unroll") for (int k = 0; k < 2; ++k) \
;     acc[ai][bj][m][n] = __builtin_amdgcn_mfma_f32_16x16x32_bf16(Bt[n][k], At[m][k], acc[ai][bj][m][n], 0, 0, 0); __builtin_amdgcn_s_setprio(0); } while (0)
; #define PG8_WAIT_V(n) asm volatile("s_waitcnt vmcnt(" #n ")" ::: "memory")
; #define PG8_WAIT_L(n) asm volatile("s_waitcnt lgkmcnt(" #n ")" ::: "memory")
; template <class Epi, class Sched>
; DI void gemm_phase(LAS unsigned char* lds, const Gemm g, const Sched& S, const Epi& E) {
;     ...
;       PG8_BAR; PG8_WAIT_L(0); PG8_MMA(0, 1, At, B1); PG8_BAR;
;       PG8_LDA(At, 1, 1); PG8_STAGE(PG8_SA(1, 0), a3, voffA);
;       PG8_BAR; PG8_WAIT_L(0); PG8_MMA(1, 0, At, B0); PG8_BAR; PG8_SCHED;
;       PG8_STAGE(PG8_SB(1, 1), b3 + hstep, voffB);
;       PG8_WAIT_V(6); PG8_BAR; PG8_MMA(1, 1, At, B1); PG8_BAR;
;   DI void operator()(const f32x4 (&acc)[2][2][4][2], const pg8::Unit& u, int wr, int wc, int fr_, int fq_) const {
;     ...
;             } else if (EPI == EPI_RESID) {
;               if (n == 0) {
;                 const int f8 = u.pn * 256 + bj * 128 + wc * 32 + 8 * fq;
;                 const f32x4 v1 = acc[ai][bj][m][1];
;                 f32x4 r0, r1;
;                 if (rsrc) {
;                   r0 = *(const f32x4*)(rsrc + (size_t)token * 1024 + f8); r1 = *(const f32x4*)(rsrc + (size_t)token * 1024 + f8 + 4);
;                 } else {
;                   const u32x4 xu = *(const u32x4*)(xr + (size_t)token * 1024 + f8);
;                   r0 = (f32x4){bf2f(xu.x & 0xffffu), bf2f(xu.x >> 16), bf2f(xu.y & 0xffffu), bf2f(xu.y >> 16)};
;                   r1 = (f32x4){bf2f(xu.z & 0xffffu), bf2f(xu.z >> 16), bf2f(xu.w & 0xffffu), bf2f(xu.w >> 16)};
;                 }
	s_waitcnt lgkmcnt(0)
	v_mfma_f32_16x16x32_bf16 v[116:119], v[208:211], v[160:163], v[116:119]
	v_mfma_f32_16x16x32_bf16 v[112:115], v[216:219], v[160:163], v[112:115]
	v_mfma_f32_16x16x32_bf16 v[100:103], v[208:211], v[168:171], v[100:103]
	v_mfma_f32_16x16x32_bf16 v[96:99], v[216:219], v[168:171], v[96:99]
	v_mfma_f32_16x16x32_bf16 v[84:87], v[208:211], v[176:179], v[84:87]
	v_mfma_f32_16x16x32_bf16 v[80:83], v[216:219], v[176:179], v[80:83]
	v_mfma_f32_16x16x32_bf16 v[68:71], v[208:211], v[200:203], v[68:71]
	v_mfma_f32_16x16x32_bf16 v[64:67], v[216:219], v[200:203], v[64:67]
	v_mfma_f32_16x16x32_bf16 v[116:119], v[212:215], v[164:167], v[116:119]
	v_mfma_f32_16x16x32_bf16 v[112:115], v[220:223], v[164:167], v[112:115]
	v_mfma_f32_16x16x32_bf16 v[100:103], v[212:215], v[172:175], v[100:103]
	v_mfma_f32_16x16x32_bf16 v[96:99], v[220:223], v[172:175], v[96:99]
	v_mfma_f32_16x16x32_bf16 v[84:87], v[212:215], v[196:199], v[84:87]
	v_mfma_f32_16x16x32_bf16 v[80:83], v[220:223], v[196:199], v[80:83]
	v_mfma_f32_16x16x32_bf16 v[68:71], v[212:215], v[204:207], v[68:71]
	v_mfma_f32_16x16x32_bf16 v[64:67], v[220:223], v[204:207], v[64:67]
	s_mov_b32 m0, s49
	v_lshl_add_u64 v[156:157], v[224:225], 0, s[0:1]
	s_barrier
	ds_read_b128 v[160:163], v159 offset:49152
	ds_read_b128 v[164:167], v159 offset:50176
	ds_read_b128 v[168:171], v159 offset:51200
	ds_read_b128 v[172:175], v159 offset:52224
	ds_read_b128 v[176:179], v159 offset:53248
	ds_read_b128 v[196:199], v159 offset:54272
	ds_read_b128 v[200:203], v159 offset:55296
	ds_read_b128 v[204:207], v159 offset:56320
	global_load_lds_dwordx4 v[156:157], off
	v_lshl_add_u64 v[156:157], v[226:227], 0, s[0:1]
	s_mov_b32 m0, s50
	s_nop 0
	global_load_lds_dwordx4 v[156:157], off
	s_barrier
	s_waitcnt lgkmcnt(0)
	v_mfma_f32_16x16x32_bf16 v[60:63], v[128:131], v[160:163], v[60:63]
	v_mfma_f32_16x16x32_bf16 v[56:59], v[148:151], v[160:163], v[56:59]
	v_mfma_f32_16x16x32_bf16 v[44:47], v[128:131], v[168:171], v[44:47]
	v_mfma_f32_16x16x32_bf16 v[40:43], v[148:151], v[168:171], v[40:43]
	v_mfma_f32_16x16x32_bf16 v[28:31], v[128:131], v[176:179], v[28:31]
	v_mfma_f32_16x16x32_bf16 v[24:27], v[148:151], v[176:179], v[24:27]
	v_mfma_f32_16x16x32_bf16 v[12:15], v[128:131], v[200:203], v[12:15]
	v_mfma_f32_16x16x32_bf16 v[8:11], v[148:151], v[200:203], v[8:11]
	v_mfma_f32_16x16x32_bf16 v[60:63], v[132:135], v[164:167], v[60:63]
	v_mfma_f32_16x16x32_bf16 v[56:59], v[152:155], v[164:167], v[56:59]
	v_mfma_f32_16x16x32_bf16 v[44:47], v[132:135], v[172:175], v[44:47]
	v_mfma_f32_16x16x32_bf16 v[40:43], v[152:155], v[172:175], v[40:43]
	v_mfma_f32_16x16x32_bf16 v[28:31], v[132:135], v[196:199], v[28:31]
	v_mfma_f32_16x16x32_bf16 v[24:27], v[152:155], v[196:199], v[24:27]
	v_mfma_f32_16x16x32_bf16 v[12:15], v[132:135], v[204:207], v[12:15]
	v_mfma_f32_16x16x32_bf16 v[8:11], v[152:155], v[204:207], v[8:11]
	s_barrier
	s_add_u32 s4, s4, 0x40080
	s_addc_u32 s5, s5, 0
	s_add_i32 s28, s28, s40
	v_lshl_add_u64 v[128:129], s[4:5], 0, v[144:145]
	s_mov_b32 m0, s28
	s_nop 0
	global_load_lds_dwordx4 v[128:129], off
	v_lshl_add_u64 v[128:129], s[4:5], 0, v[136:137]
	s_add_i32 m0, s28, 0x2000
	s_nop 0
	global_load_lds_dwordx4 v[128:129], off
	s_waitcnt vmcnt(6)
	s_barrier
	v_mfma_f32_16x16x32_bf16 v[52:55], v[208:211], v[160:163], v[52:55]
	v_mfma_f32_16x16x32_bf16 v[48:51], v[216:219], v[160:163], v[48:51]
	v_mfma_f32_16x16x32_bf16 v[36:39], v[208:211], v[168:171], v[36:39]
	v_mfma_f32_16x16x32_bf16 v[32:35], v[216:219], v[168:171], v[32:35]
	v_mfma_f32_16x16x32_bf16 v[20:23], v[208:211], v[176:179], v[20:23]
	v_mfma_f32_16x16x32_bf16 v[16:19], v[216:219], v[176:179], v[16:19]
	v_mfma_f32_16x16x32_bf16 v[4:7], v[208:211], v[200:203], v[4:7]
	v_mfma_f32_16x16x32_bf16 v[0:3], v[216:219], v[200:203], v[0:3]
	v_mfma_f32_16x16x32_bf16 v[52:55], v[212:215], v[164:167], v[52:55]
	v_mfma_f32_16x16x32_bf16 v[48:51], v[220:223], v[164:167], v[48:51]
	v_mfma_f32_16x16x32_bf16 v[36:39], v[212:215], v[172:175], v[36:39]
	v_mfma_f32_16x16x32_bf16 v[32:35], v[220:223], v[172:175], v[32:35]
	v_mfma_f32_16x16x32_bf16 v[20:23], v[212:215], v[196:199], v[20:23]
	v_mfma_f32_16x16x32_bf16 v[16:19], v[220:223], v[196:199], v[16:19]
	v_mfma_f32_16x16x32_bf16 v[4:7], v[212:215], v[204:207], v[4:7]
	v_mfma_f32_16x16x32_bf16 v[0:3], v[220:223], v[204:207], v[0:3]
	s_add_i32 s54, s54, 2
	s_add_u32 s2, s2, 0x100
	s_addc_u32 s3, s3, 0
	s_add_u32 s52, s52, 0x100
	s_addc_u32 s53, s53, 0
	s_cmp_gt_u32 s54, 13
	s_barrier
	s_cbranch_scc0 .LBB0_1644
	s_lshl_b32 s2, s34, 8
	v_mov_b32_e32 v161, v182
	s_add_i32 s2, s2, s47
	v_cndmask_b32_e64 v130, 0, 1, s[14:15]
	v_and_or_b32 v150, v161, 15, s2
	s_lshl_b32 s2, s24, 8
	v_bfe_u32 v160, v161, 4, 2
	s_or_b32 s2, s2, s48
	v_ashrrev_i32_e32 v151, 31, v150
	v_lshl_or_b32 v148, v160, 3, s2
	v_lshlrev_b64 v[128:129], 12, v[150:151]
	v_ashrrev_i32_e32 v149, 31, v148
	v_lshl_add_u64 v[128:129], s[6:7], 0, v[128:129]
	v_cmp_ne_u32_e64 s[2:3], 1, v130
	s_andn2_b64 vcc, exec, s[14:15]
	v_lshl_add_u64 v[154:155], v[148:149], 2, v[128:129]
	s_cbranch_vccnz .LBB0_1647
	global_load_dwordx4 v[132:135], v[154:155], off offset:16
	global_load_dwordx4 v[128:131], v[154:155], off
	s_mov_b64 s[4:5], 0
	s_branch .LBB0_1648

; #define PG8_STAGE(bufoff, gbase, voff) do { _Pragma("unroll") for (int _i = 0; _i < 2; ++_i) \
;     __builtin_amdgcn_global_load_lds((const unsigned*)((const char*)(gbase) + (voff)[_i]), (LAS unsigned*)(lds + (bufoff) + ldsw + _i * 8192), 16, 0, 0); } while (0)
; #define PG8_LDA(dst, b, h) do { _Pragma("unroll") for (int m = 0; m < 4; ++m) _Pragma("unroll") for (int k = 0; k < 2; ++k) dst[m][k] = *(const LAS bf16x8*)(lds + PG8_SA(b, h) + aoff + m * 2048 + k * 1024); } while (0)
; #define PG8_LDB(dst, b, h) do { _Pragma("unroll") for (int n = 0; n < 2; ++n) _Pragma("unroll") for (int k = 0; k < 2; ++k) dst[n][k] = *(const LAS bf16x8*)(lds + PG8_SB(b, h) + boff + n * 2048 + k * 1024); } while (0)
; #define PG8_MMA(ai, bj, At, Bt) do { __builtin_amdgcn_s_setprio(1); _Pragma("unroll") for (int m = 0; m < 4; ++m) _Pragma("unroll") for (int n = 0; n < 2; ++n) _Pragma("unroll") for (int k = 0; k < 2; ++k) \
;     acc[ai][bj][m][n] = __builtin_amdgcn_mfma_f32_16x16x32_bf16(Bt[n][k], At[m][k], acc[ai][bj][m][n], 0, 0, 0); __builtin_amdgcn_s_setprio(0); } while (0)
; template <class Epi, class Sched>
; DI void gemm_phase(LAS unsigned char* lds, const Gemm g, const Sched& S, const Epi& E) {
;     ...
;       const bool last = (t == nt - 2);
;       const char* a1 = cA + (size_t)(t + 1) * kstep;
;       const char* a2 = last ? nA : cA + (size_t)(t + 2) * kstep; const char* b2 = last ? nB : cB + (size_t)(t + 2) * kstep;
;       const char* a3 = a2 + kstep; const char* b3 = b2 + kstep;
;       PG8_LDB(B0, 0, 0); PG8_SCHED; PG8_LDA(At, 0, 0); PG8_STAGE(PG8_SA(1, 1), a1 + hstep, voffA);
;       PG8_WAIT_L(8); PG8_BAR; PG8_WAIT_L(0); PG8_MMA(0, 0, At, B0); PG8_BAR; PG8_SCHED;
;       PG8_LDB(B1, 0, 1); PG8_STAGE(PG8_SB(0, 0), b2, voffB);
;       PG8_BAR; PG8_WAIT_L(0); PG8_MMA(0, 1, At, B1); PG8_BAR;
;       PG8_LDA(At, 0, 1); PG8_STAGE(PG8_SA(0, 0), a2, voffA);
;       PG8_BAR; PG8_WAIT_L(0); PG8_MMA(1, 0, At, B0); PG8_BAR; PG8_SCHED;
;       PG8_STAGE(PG8_SB(0, 1), b2 + hstep, voffB);
;       PG8_WAIT_V(6); PG8_BAR; PG8_MMA(1, 1, At, B1); PG8_BAR;
;       PG8_LDB(B0, 1, 0); PG8_SCHED; PG8_LDA(At, 1, 0); PG8_STAGE(PG8_SA(0, 1), a2 + hstep, voffA);
;       PG8_WAIT_L(8); PG8_BAR; PG8_WAIT_L(0); PG8_MMA(0, 0, At, B0); PG8_BAR; PG8_SCHED;
;       PG8_LDB(B1, 1, 1); PG8_STAGE(PG8_SB(1, 0), b3, voffB);
;       PG8_BAR; PG8_WAIT_L(0); PG8_MMA(0, 1, At, B1); PG8_BAR;
.LBB0_1829:
	s_add_u32 s16, s14, 0xfffc0080
	s_addc_u32 s17, s15, -1
	s_add_i32 s51, 0, 0x10000
	v_add_u32_e32 v140, s51, v142
	ds_read_b128 v[146:149], v140
	ds_read_b128 v[150:153], v140 offset:1024
	ds_read_b128 v[154:157], v140 offset:2048
	ds_read_b128 v[158:161], v140 offset:3072
	s_cmp_eq_u32 s50, 12
	s_cselect_b32 s19, s7, s17
	s_cselect_b32 s18, s46, s16
	s_cselect_b32 s17, s5, s49
	s_cselect_b32 s16, s47, s48
	v_lshl_add_u64 v[140:141], s[14:15], 0, v[136:137]
	s_add_i32 m0, s29, 0xc000
	ds_read_b128 v[162:165], v143
	ds_read_b128 v[166:169], v143 offset:1024
	ds_read_b128 v[170:173], v143 offset:2048
	ds_read_b128 v[174:177], v143 offset:3072
	ds_read_b128 v[178:181], v143 offset:4096
	ds_read_b128 v[196:199], v143 offset:5120
	ds_read_b128 v[200:203], v143 offset:6144
	ds_read_b128 v[204:207], v143 offset:7168
	global_load_lds_dwordx4 v[140:141], off
	v_lshl_add_u64 v[140:141], s[14:15], 0, v[138:139]
	s_add_i32 m0, s29, 0xe000
	s_nop 0
	global_load_lds_dwordx4 v[140:141], off
	s_waitcnt lgkmcnt(8)
	s_barrier
	s_waitcnt lgkmcnt(0)
	v_mfma_f32_16x16x32_bf16 v[124:127], v[146:149], v[162:165], v[124:127]
	v_mfma_f32_16x16x32_bf16 v[120:123], v[154:157], v[162:165], v[120:123]
	v_mfma_f32_16x16x32_bf16 v[112:115], v[146:149], v[170:173], v[112:115]
	v_mfma_f32_16x16x32_bf16 v[104:107], v[154:157], v[170:173], v[104:107]
	v_mfma_f32_16x16x32_bf16 v[92:95], v[146:149], v[178:181], v[92:95]
	v_mfma_f32_16x16x32_bf16 v[88:91], v[154:157], v[178:181], v[88:91]
	v_mfma_f32_16x16x32_bf16 v[80:83], v[146:149], v[200:203], v[80:83]
	v_mfma_f32_16x16x32_bf16 v[72:75], v[154:157], v[200:203], v[72:75]
	v_mfma_f32_16x16x32_bf16 v[124:127], v[150:153], v[166:169], v[124:127]
	v_mfma_f32_16x16x32_bf16 v[120:123], v[158:161], v[166:169], v[120:123]
	v_mfma_f32_16x16x32_bf16 v[112:115], v[150:153], v[174:177], v[112:115]
	v_mfma_f32_16x16x32_bf16 v[104:107], v[158:161], v[174:177], v[104:107]
	v_mfma_f32_16x16x32_bf16 v[92:95], v[150:153], v[196:199], v[92:95]
	v_mfma_f32_16x16x32_bf16 v[88:91], v[158:161], v[196:199], v[88:91]
	v_mfma_f32_16x16x32_bf16 v[80:83], v[150:153], v[204:207], v[80:83]
	v_mfma_f32_16x16x32_bf16 v[72:75], v[158:161], v[204:207], v[72:75]
	s_barrier
	s_add_i32 s54, 0, 0x14000
	v_add_u32_e32 v140, s54, v142
	s_add_i32 s51, s51, s20
	ds_read_b128 v[208:211], v140
	ds_read_b128 v[212:215], v140 offset:1024
	ds_read_b128 v[216:219], v140 offset:2048
	ds_read_b128 v[220:223], v140 offset:3072
	v_lshl_add_u64 v[140:141], s[16:17], 0, v[132:133]
	s_mov_b32 m0, s51
	v_lshl_add_u64 v[224:225], s[16:17], 0, v[128:129]
	global_load_lds_dwordx4 v[140:141], off
	s_add_i32 m0, s51, 0x2000
	s_nop 0
	global_load_lds_dwordx4 v[224:225], off
	s_barrier
	s_waitcnt lgkmcnt(0)
	v_mfma_f32_16x16x32_bf16 v[116:119], v[208:211], v[162:165], v[116:119]
	v_mfma_f32_16x16x32_bf16 v[108:111], v[216:219], v[162:165], v[108:111]
	v_mfma_f32_16x16x32_bf16 v[100:103], v[208:211], v[170:173], v[100:103]
	v_mfma_f32_16x16x32_bf16 v[96:99], v[216:219], v[170:173], v[96:99]
	v_mfma_f32_16x16x32_bf16 v[84:87], v[208:211], v[178:181], v[84:87]
	v_mfma_f32_16x16x32_bf16 v[76:79], v[216:219], v[178:181], v[76:79]
	v_mfma_f32_16x16x32_bf16 v[68:71], v[208:211], v[200:203], v[68:71]
	v_mfma_f32_16x16x32_bf16 v[64:67], v[216:219], v[200:203], v[64:67]
	v_mfma_f32_16x16x32_bf16 v[116:119], v[212:215], v[166:169], v[116:119]
	v_mfma_f32_16x16x32_bf16 v[108:111], v[220:223], v[166:169], v[108:111]
	v_mfma_f32_16x16x32_bf16 v[100:103], v[212:215], v[174:177], v[100:103]
	v_mfma_f32_16x16x32_bf16 v[96:99], v[220:223], v[174:177], v[96:99]
	v_mfma_f32_16x16x32_bf16 v[84:87], v[212:215], v[196:199], v[84:87]
	v_mfma_f32_16x16x32_bf16 v[76:79], v[220:223], v[196:199], v[76:79]
	v_mfma_f32_16x16x32_bf16 v[68:71], v[212:215], v[204:207], v[68:71]
	v_mfma_f32_16x16x32_bf16 v[64:67], v[220:223], v[204:207], v[64:67]
	s_mov_b32 m0, s29
	v_lshl_add_u64 v[226:227], s[18:19], 0, v[134:135]
	s_barrier
	ds_read_b128 v[162:165], v143 offset:16384
	ds_read_b128 v[166:169], v143 offset:17408
	ds_read_b128 v[170:173], v143 offset:18432
	ds_read_b128 v[174:177], v143 offset:19456
	ds_read_b128 v[178:181], v143 offset:20480
	ds_read_b128 v[196:199], v143 offset:21504
	ds_read_b128 v[200:203], v143 offset:22528
	ds_read_b128 v[204:207], v143 offset:23552
	global_load_lds_dwordx4 v[226:227], off
	v_lshl_add_u64 v[228:229], s[18:19], 0, v[130:131]
	s_mov_b32 m0, s34
	s_nop 0
	global_load_lds_dwordx4 v[228:229], off
	s_barrier
	s_waitcnt lgkmcnt(0)
	v_mfma_f32_16x16x32_bf16 v[60:63], v[146:149], v[162:165], v[60:63]
	v_mfma_f32_16x16x32_bf16 v[56:59], v[154:157], v[162:165], v[56:59]
	v_mfma_f32_16x16x32_bf16 v[48:51], v[146:149], v[170:173], v[48:51]
	v_mfma_f32_16x16x32_bf16 v[40:43], v[154:157], v[170:173], v[40:43]
	v_mfma_f32_16x16x32_bf16 v[28:31], v[146:149], v[178:181], v[28:31]
	v_mfma_f32_16x16x32_bf16 v[24:27], v[154:157], v[178:181], v[24:27]
	v_mfma_f32_16x16x32_bf16 v[16:19], v[146:149], v[200:203], v[16:19]
	v_mfma_f32_16x16x32_bf16 v[8:11], v[154:157], v[200:203], v[8:11]
	v_mfma_f32_16x16x32_bf16 v[60:63], v[150:153], v[166:169], v[60:63]
	v_mfma_f32_16x16x32_bf16 v[56:59], v[158:161], v[166:169], v[56:59]
	v_mfma_f32_16x16x32_bf16 v[48:51], v[150:153], v[174:177], v[48:51]
	v_mfma_f32_16x16x32_bf16 v[40:43], v[158:161], v[174:177], v[40:43]
	v_mfma_f32_16x16x32_bf16 v[28:31], v[150:153], v[196:199], v[28:31]
	v_mfma_f32_16x16x32_bf16 v[24:27], v[158:161], v[196:199], v[24:27]
	v_mfma_f32_16x16x32_bf16 v[16:19], v[150:153], v[204:207], v[16:19]
	v_mfma_f32_16x16x32_bf16 v[8:11], v[158:161], v[204:207], v[8:11]
	s_barrier
; #define PG8_STAGE(bufoff, gbase, voff) do { _Pragma("unroll") for (int _i = 0; _i < 2; ++_i) \
;     __builtin_amdgcn_global_load_lds((const unsigned*)((const char*)(gbase) + (voff)[_i]), (LAS unsigned*)(lds + (bufoff) + ldsw + _i * 8192), 16, 0, 0); } while (0)
; #define PG8_LDA(dst, b, h) do { _Pragma("unroll") for (int m = 0; m < 4; ++m) _Pragma("unroll") for (int k = 0; k < 2; ++k) dst[m][k] = *(const LAS bf16x8*)(lds + PG8_SA(b, h) + aoff + m * 2048 + k * 1024); } while (0)
; #define PG8_LDB(dst, b, h) do { _Pragma("unroll") for (int n = 0; n < 2; ++n) _Pragma("unroll") for (int k = 0; k < 2; ++k) dst[n][k] = *(const LAS bf16x8*)(lds + PG8_SB(b, h) + boff + n * 2048 + k * 1024); } while (0)
; #define PG8_MMA(ai, bj, At, Bt) do { __builtin_amdgcn_s_setprio(1); _Pragma("unroll") for (int m = 0; m < 4; ++m) _Pragma("unroll") for (int n = 0; n < 2; ++n) _Pragma("unroll") for (int k = 0; k < 2; ++k) \
;     acc[ai][bj][m][n] = __builtin_amdgcn_mfma_f32_16x16x32_bf16(Bt[n][k], At[m][k], acc[ai][bj][m][n], 0, 0, 0); __builtin_amdgcn_s_setprio(0); } while (0)
; #define PG8_WAIT_V(n) asm volatile("s_waitcnt vmcnt(" #n ")" ::: "memory")
; #define PG8_WAIT_L(n) asm volatile("s_waitcnt lgkmcnt(" #n ")" ::: "memory")
; #define PG8_BAR __builtin_amdgcn_s_barrier()
; #define PG8_SCHED __builtin_amdgcn_sched_barrier(0)
; template <class Epi, class Sched>
; DI void gemm_phase(LAS unsigned char* lds, const Gemm g, const Sched& S, const Epi& E) {
;     ...
;       PG8_BAR; PG8_WAIT_L(0); PG8_MMA(1, 0, At, B0); PG8_BAR; PG8_SCHED;
;       PG8_STAGE(PG8_SB(0, 1), b2 + hstep, voffB);
;       PG8_WAIT_V(6); PG8_BAR; PG8_MMA(1, 1, At, B1); PG8_BAR;
;       PG8_LDB(B0, 1, 0); PG8_SCHED; PG8_LDA(At, 1, 0); PG8_STAGE(PG8_SA(0, 1), a2 + hstep, voffA);
;       PG8_WAIT_L(8); PG8_BAR; PG8_WAIT_L(0); PG8_MMA(0, 0, At, B0); PG8_BAR; PG8_SCHED;
;       PG8_LDB(B1, 1, 1); PG8_STAGE(PG8_SB(1, 0), b3, voffB);
;       PG8_BAR; PG8_WAIT_L(0); PG8_MMA(0, 1, At, B1); PG8_BAR;
;       PG8_LDA(At, 1, 1); PG8_STAGE(PG8_SA(1, 0), a3, voffA);
;       PG8_BAR; PG8_WAIT_L(0); PG8_MMA(1, 0, At, B0); PG8_BAR; PG8_SCHED;
	s_add_u32 s52, s16, 0x40000
	s_addc_u32 s53, s17, 0
	s_add_i32 s51, s54, s20
	v_lshl_add_u64 v[146:147], s[52:53], 0, v[132:133]
	s_mov_b32 m0, s51
	s_nop 0
	global_load_lds_dwordx4 v[146:147], off
	v_lshl_add_u64 v[146:147], s[52:53], 0, v[128:129]
	s_add_i32 m0, s51, 0x2000
	s_nop 0
	global_load_lds_dwordx4 v[146:147], off
	s_waitcnt vmcnt(6)
	s_barrier
	v_mfma_f32_16x16x32_bf16 v[52:55], v[208:211], v[162:165], v[52:55]
	v_mfma_f32_16x16x32_bf16 v[44:47], v[216:219], v[162:165], v[44:47]
	v_mfma_f32_16x16x32_bf16 v[36:39], v[208:211], v[170:173], v[36:39]
	v_mfma_f32_16x16x32_bf16 v[32:35], v[216:219], v[170:173], v[32:35]
	v_mfma_f32_16x16x32_bf16 v[20:23], v[208:211], v[178:181], v[20:23]
	v_mfma_f32_16x16x32_bf16 v[12:15], v[216:219], v[178:181], v[12:15]
	v_mfma_f32_16x16x32_bf16 v[4:7], v[208:211], v[200:203], v[4:7]
	v_mfma_f32_16x16x32_bf16 v[0:3], v[216:219], v[200:203], v[0:3]
	v_mfma_f32_16x16x32_bf16 v[52:55], v[212:215], v[166:169], v[52:55]
	v_mfma_f32_16x16x32_bf16 v[44:47], v[220:223], v[166:169], v[44:47]
	v_mfma_f32_16x16x32_bf16 v[36:39], v[212:215], v[174:177], v[36:39]
	v_mfma_f32_16x16x32_bf16 v[32:35], v[220:223], v[174:177], v[32:35]
	v_mfma_f32_16x16x32_bf16 v[20:23], v[212:215], v[196:199], v[20:23]
	v_mfma_f32_16x16x32_bf16 v[12:15], v[220:223], v[196:199], v[12:15]
	v_mfma_f32_16x16x32_bf16 v[4:7], v[212:215], v[204:207], v[4:7]
	v_mfma_f32_16x16x32_bf16 v[0:3], v[220:223], v[204:207], v[0:3]
	s_add_i32 s51, 0, 0x18000
	v_add_u32_e32 v144, s51, v142
	s_barrier
	ds_read_b128 v[146:149], v144
	ds_read_b128 v[150:153], v144 offset:1024
	ds_read_b128 v[154:157], v144 offset:2048
	ds_read_b128 v[158:161], v144 offset:3072
	s_add_u32 s18, s18, 0x40000
	s_addc_u32 s19, s19, 0
	s_mov_b32 m0, s35
	v_lshl_add_u64 v[208:209], s[18:19], 0, v[134:135]
	ds_read_b128 v[162:165], v143 offset:32768
	ds_read_b128 v[166:169], v143 offset:33792
	ds_read_b128 v[170:173], v143 offset:34816
	ds_read_b128 v[174:177], v143 offset:35840
	ds_read_b128 v[178:181], v143 offset:36864
	ds_read_b128 v[196:199], v143 offset:37888
	ds_read_b128 v[200:203], v143 offset:38912
	ds_read_b128 v[204:207], v143 offset:39936
	global_load_lds_dwordx4 v[208:209], off
	v_lshl_add_u64 v[208:209], s[18:19], 0, v[130:131]
	s_mov_b32 m0, s38
	s_nop 0
	global_load_lds_dwordx4 v[208:209], off
	s_waitcnt lgkmcnt(8)
	s_barrier
	s_waitcnt lgkmcnt(0)
	v_mfma_f32_16x16x32_bf16 v[124:127], v[146:149], v[162:165], v[124:127]
	v_mfma_f32_16x16x32_bf16 v[120:123], v[154:157], v[162:165], v[120:123]
	v_mfma_f32_16x16x32_bf16 v[112:115], v[146:149], v[170:173], v[112:115]
	v_mfma_f32_16x16x32_bf16 v[104:107], v[154:157], v[170:173], v[104:107]
	v_mfma_f32_16x16x32_bf16 v[92:95], v[146:149], v[178:181], v[92:95]
	v_mfma_f32_16x16x32_bf16 v[88:91], v[154:157], v[178:181], v[88:91]
	v_mfma_f32_16x16x32_bf16 v[80:83], v[146:149], v[200:203], v[80:83]
	v_mfma_f32_16x16x32_bf16 v[72:75], v[154:157], v[200:203], v[72:75]
	v_mfma_f32_16x16x32_bf16 v[124:127], v[150:153], v[166:169], v[124:127]
	v_mfma_f32_16x16x32_bf16 v[120:123], v[158:161], v[166:169], v[120:123]
	v_mfma_f32_16x16x32_bf16 v[112:115], v[150:153], v[174:177], v[112:115]
	v_mfma_f32_16x16x32_bf16 v[104:107], v[158:161], v[174:177], v[104:107]
	v_mfma_f32_16x16x32_bf16 v[92:95], v[150:153], v[196:199], v[92:95]
	v_mfma_f32_16x16x32_bf16 v[88:91], v[158:161], v[196:199], v[88:91]
	v_mfma_f32_16x16x32_bf16 v[80:83], v[150:153], v[204:207], v[80:83]
	v_mfma_f32_16x16x32_bf16 v[72:75], v[158:161], v[204:207], v[72:75]
	s_barrier
	s_add_i32 s18, 0, 0x1c000
	s_add_i32 s19, s51, s20
	v_add_u32_e32 v144, s18, v142
	v_lshl_add_u64 v[140:141], v[140:141], 0, s[0:1]
	s_mov_b32 m0, s19
	ds_read_b128 v[208:211], v144
	ds_read_b128 v[212:215], v144 offset:1024
	ds_read_b128 v[216:219], v144 offset:2048
	ds_read_b128 v[220:223], v144 offset:3072
	global_load_lds_dwordx4 v[140:141], off
	v_lshl_add_u64 v[140:141], v[224:225], 0, s[0:1]
	s_add_i32 m0, s19, 0x2000
	s_nop 0
	global_load_lds_dwordx4 v[140:141], off
	s_barrier
	s_waitcnt lgkmcnt(0)
	v_mfma_f32_16x16x32_bf16 v[116:119], v[208:211], v[162:165], v[116:119]
	v_mfma_f32_16x16x32_bf16 v[108:111], v[216:219], v[162:165], v[108:111]
	v_mfma_f32_16x16x32_bf16 v[100:103], v[208:211], v[170:173], v[100:103]
	v_mfma_f32_16x16x32_bf16 v[96:99], v[216:219], v[170:173], v[96:99]
	v_mfma_f32_16x16x32_bf16 v[84:87], v[208:211], v[178:181], v[84:87]
	v_mfma_f32_16x16x32_bf16 v[76:79], v[216:219], v[178:181], v[76:79]
	v_mfma_f32_16x16x32_bf16 v[68:71], v[208:211], v[200:203], v[68:71]
	v_mfma_f32_16x16x32_bf16 v[64:67], v[216:219], v[200:203], v[64:67]
	v_mfma_f32_16x16x32_bf16 v[116:119], v[212:215], v[166:169], v[116:119]
	v_mfma_f32_16x16x32_bf16 v[108:111], v[220:223], v[166:169], v[108:111]
	v_mfma_f32_16x16x32_bf16 v[100:103], v[212:215], v[174:177], v[100:103]
	v_mfma_f32_16x16x32_bf16 v[96:99], v[220:223], v[174:177], v[96:99]
	v_mfma_f32_16x16x32_bf16 v[84:87], v[212:215], v[196:199], v[84:87]
	v_mfma_f32_16x16x32_bf16 v[76:79], v[220:223], v[196:199], v[76:79]
	v_mfma_f32_16x16x32_bf16 v[68:71], v[212:215], v[204:207], v[68:71]
	v_mfma_f32_16x16x32_bf16 v[64:67], v[220:223], v[204:207], v[64:67]
	s_mov_b32 m0, s40
	v_lshl_add_u64 v[140:141], v[226:227], 0, s[0:1]
	s_barrier
	ds_read_b128 v[162:165], v143 offset:49152
	ds_read_b128 v[166:169], v143 offset:50176
	ds_read_b128 v[170:173], v143 offset:51200
	ds_read_b128 v[174:177], v143 offset:52224
	ds_read_b128 v[178:181], v143 offset:53248
	ds_read_b128 v[196:199], v143 offset:54272
	ds_read_b128 v[200:203], v143 offset:55296
	ds_read_b128 v[204:207], v143 offset:56320
	global_load_lds_dwordx4 v[140:141], off
	v_lshl_add_u64 v[140:141], v[228:229], 0, s[0:1]
	s_mov_b32 m0, s41
	s_nop 0
	global_load_lds_dwordx4 v[140:141], off
	s_barrier
; #define PG8_STAGE(bufoff, gbase, voff) do { _Pragma("unroll") for (int _i = 0; _i < 2; ++_i) \
;     __builtin_amdgcn_global_load_lds((const unsigned*)((const char*)(gbase) + (voff)[_i]), (LAS unsigned*)(lds + (bufoff) + ldsw + _i * 8192), 16, 0, 0); } while (0)
; #define PG8_MMA(ai, bj, At, Bt) do { __builtin_amdgcn_s_setprio(1); _Pragma("unroll") for (int m = 0; m < 4; ++m) _Pragma("unroll") for (int n = 0; n < 2; ++n) _Pragma("unroll") for (int k = 0; k < 2; ++k) \
;     acc[ai][bj][m][n] = __builtin_amdgcn_mfma_f32_16x16x32_bf16(Bt[n][k], At[m][k], acc[ai][bj][m][n], 0, 0, 0); __builtin_amdgcn_s_setprio(0); } while (0)
; #define PG8_WAIT_V(n) asm volatile("s_waitcnt vmcnt(" #n ")" ::: "memory")
; #define PG8_WAIT_L(n) asm volatile("s_waitcnt lgkmcnt(" #n ")" ::: "memory")
; #define PG8_BAR __builtin_amdgcn_s_barrier()
; #define PG8_SCHED __builtin_amdgcn_sched_barrier(0)
; template <class Epi, class Sched>
; DI void gemm_phase(LAS unsigned char* lds, const Gemm g, const Sched& S, const Epi& E) {
;     ...
;       PG8_BAR; PG8_WAIT_L(0); PG8_MMA(1, 0, At, B0); PG8_BAR; PG8_SCHED;
;       PG8_STAGE(PG8_SB(1, 1), b3 + hstep, voffB);
;       PG8_WAIT_V(6); PG8_BAR; PG8_MMA(1, 1, At, B1); PG8_BAR;
;   DI void operator()(const f32x4 (&acc)[2][2][4][2], const pg8::Unit& u, int wr, int wc, int fr_, int fq_) const {
;     ...
;               if (n == 0) {
;                 const f32x4 v1 = acc[ai][bj][m][1];
;                 u32x4 o4;
;                 { const float t0 = fmaxf(v[0], 0.f) * rinv, t1 = fmaxf(v[1], 0.f) * rinv, t2 = fmaxf(v[2], 0.f) * rinv, t3 = fmaxf(v[3], 0.f) * rinv;
;                   o4.x = pack2(t0 * t0, t1 * t1); o4.y = pack2(t2 * t2, t3 * t3); }
;                 { const float t0 = fmaxf(v1[0], 0.f) * rinv, t1 = fmaxf(v1[1], 0.f) * rinv, t2 = fmaxf(v1[2], 0.f) * rinv, t3 = fmaxf(v1[3], 0.f) * rinv;
;                   o4.z = pack2(t0 * t0, t1 * t1); o4.w = pack2(t2 * t2, t3 * t3); }
;                 *(u32x4*)((u16*)big + (size_t)token * 4096 + u.pn * 256 + bj * 128 + wc * 32 + 8 * fq) = o4;
	s_waitcnt lgkmcnt(0)
	v_mfma_f32_16x16x32_bf16 v[60:63], v[146:149], v[162:165], v[60:63]
	v_mfma_f32_16x16x32_bf16 v[56:59], v[154:157], v[162:165], v[56:59]
	v_mfma_f32_16x16x32_bf16 v[48:51], v[146:149], v[170:173], v[48:51]
	v_mfma_f32_16x16x32_bf16 v[40:43], v[154:157], v[170:173], v[40:43]
	v_mfma_f32_16x16x32_bf16 v[28:31], v[146:149], v[178:181], v[28:31]
	v_mfma_f32_16x16x32_bf16 v[24:27], v[154:157], v[178:181], v[24:27]
	v_mfma_f32_16x16x32_bf16 v[16:19], v[146:149], v[200:203], v[16:19]
	v_mfma_f32_16x16x32_bf16 v[8:11], v[154:157], v[200:203], v[8:11]
	v_mfma_f32_16x16x32_bf16 v[60:63], v[150:153], v[166:169], v[60:63]
	v_mfma_f32_16x16x32_bf16 v[56:59], v[158:161], v[166:169], v[56:59]
	v_mfma_f32_16x16x32_bf16 v[48:51], v[150:153], v[174:177], v[48:51]
	v_mfma_f32_16x16x32_bf16 v[40:43], v[158:161], v[174:177], v[40:43]
	v_mfma_f32_16x16x32_bf16 v[28:31], v[150:153], v[196:199], v[28:31]
	v_mfma_f32_16x16x32_bf16 v[24:27], v[158:161], v[196:199], v[24:27]
	v_mfma_f32_16x16x32_bf16 v[16:19], v[150:153], v[204:207], v[16:19]
	v_mfma_f32_16x16x32_bf16 v[8:11], v[158:161], v[204:207], v[8:11]
	s_barrier
	s_add_u32 s16, s16, 0x40080
	s_addc_u32 s17, s17, 0
	s_add_i32 s18, s18, s20
	v_lshl_add_u64 v[140:141], s[16:17], 0, v[132:133]
	s_mov_b32 m0, s18
	s_nop 0
	global_load_lds_dwordx4 v[140:141], off
	v_lshl_add_u64 v[140:141], s[16:17], 0, v[128:129]
	s_add_i32 m0, s18, 0x2000
	s_nop 0
	global_load_lds_dwordx4 v[140:141], off
	s_waitcnt vmcnt(6)
	s_barrier
	v_mfma_f32_16x16x32_bf16 v[52:55], v[208:211], v[162:165], v[52:55]
	v_mfma_f32_16x16x32_bf16 v[44:47], v[216:219], v[162:165], v[44:47]
	v_mfma_f32_16x16x32_bf16 v[36:39], v[208:211], v[170:173], v[36:39]
	v_mfma_f32_16x16x32_bf16 v[32:35], v[216:219], v[170:173], v[32:35]
	v_mfma_f32_16x16x32_bf16 v[20:23], v[208:211], v[178:181], v[20:23]
	v_mfma_f32_16x16x32_bf16 v[12:15], v[216:219], v[178:181], v[12:15]
	v_mfma_f32_16x16x32_bf16 v[4:7], v[208:211], v[200:203], v[4:7]
	v_mfma_f32_16x16x32_bf16 v[0:3], v[216:219], v[200:203], v[0:3]
	v_mfma_f32_16x16x32_bf16 v[52:55], v[212:215], v[166:169], v[52:55]
	v_mfma_f32_16x16x32_bf16 v[44:47], v[220:223], v[166:169], v[44:47]
	v_mfma_f32_16x16x32_bf16 v[36:39], v[212:215], v[174:177], v[36:39]
	v_mfma_f32_16x16x32_bf16 v[32:35], v[220:223], v[174:177], v[32:35]
	v_mfma_f32_16x16x32_bf16 v[20:23], v[212:215], v[196:199], v[20:23]
	v_mfma_f32_16x16x32_bf16 v[12:15], v[220:223], v[196:199], v[12:15]
	v_mfma_f32_16x16x32_bf16 v[4:7], v[212:215], v[204:207], v[4:7]
	v_mfma_f32_16x16x32_bf16 v[0:3], v[220:223], v[204:207], v[0:3]
	s_add_i32 s50, s50, 2
	s_add_u32 s14, s14, 0x100
	s_addc_u32 s15, s15, 0
	s_add_u32 s48, s48, 0x100
	s_addc_u32 s49, s49, 0
	s_cmp_gt_u32 s50, 13
	s_barrier
	s_cbranch_scc0 .LBB0_1829
	v_mov_b32_e32 v144, v182
	s_lshl_b32 s5, s43, 10
	s_add_i32 s5, s5, 0
	v_and_or_b32 v141, v144, 15, s39
	v_lshl_add_u32 v140, s44, 8, v141
	v_lshl_add_u32 v141, v141, 2, s5
	v_add_u32_e32 v146, 0x20000, v141
	ds_read2_b32 v[148:149], v146 offset1:16
	v_max_f32_e32 v124, 0, v124
	v_max_f32_e32 v125, 0, v125
	v_max_f32_e32 v126, 0, v126
	v_max_f32_e32 v127, 0, v127
	v_max_f32_e32 v120, 0, v120
	v_max_f32_e32 v121, 0, v121
	s_waitcnt lgkmcnt(0)
	v_pk_mul_f32 v[124:125], v[124:125], v[148:149] op_sel_hi:[1,0]
	v_pk_mul_f32 v[126:127], v[126:127], v[148:149] op_sel_hi:[1,0]
	v_pk_mul_f32 v[120:121], v[120:121], v[148:149] op_sel_hi:[1,0]
	v_pk_mul_f32 v[124:125], v[124:125], v[124:125]
	v_pk_mul_f32 v[126:127], v[126:127], v[126:127]
	v_max_f32_e32 v122, 0, v122
	v_max_f32_e32 v123, 0, v123
	v_pk_mul_f32 v[120:121], v[120:121], v[120:121]
	v_max_f32_e32 v116, 0, v116
	v_max_f32_e32 v117, 0, v117
	v_max_f32_e32 v118, 0, v118
	v_max_f32_e32 v119, 0, v119
	v_max_f32_e32 v108, 0, v108
	v_max_f32_e32 v109, 0, v109
	s_lshl_b32 s14, s45, 8
	v_ashrrev_i32_e32 v141, 31, v140
	v_cvt_pk_bf16_f32 v124, v124, v125
	v_cvt_pk_bf16_f32 v125, v126, v127
	v_cvt_pk_bf16_f32 v126, v120, v121
	v_pk_mul_f32 v[120:121], v[122:123], v[148:149] op_sel_hi:[1,0]
	v_pk_mul_f32 v[116:117], v[116:117], v[148:149] op_sel_hi:[1,0]
	v_pk_mul_f32 v[118:119], v[118:119], v[148:149] op_sel_hi:[1,0]
	v_pk_mul_f32 v[108:109], v[108:109], v[148:149] op_sel_hi:[1,0]
	s_ashr_i32 s15, s14, 31
	v_lshlrev_b64 v[150:151], 13, v[140:141]
	v_pk_mul_f32 v[120:121], v[120:121], v[120:121]
	v_pk_mul_f32 v[116:117], v[116:117], v[116:117]
	v_pk_mul_f32 v[118:119], v[118:119], v[118:119]
	v_max_f32_e32 v110, 0, v110
	v_max_f32_e32 v111, 0, v111
	v_pk_mul_f32 v[108:109], v[108:109], v[108:109]
	v_cvt_pk_bf16_f32 v127, v120, v121
	v_lshl_add_u64 v[120:121], s[2:3], 0, v[150:151]
	s_lshl_b64 s[14:15], s[14:15], 1
	v_cvt_pk_bf16_f32 v116, v116, v117
	v_cvt_pk_bf16_f32 v117, v118, v119
	v_cvt_pk_bf16_f32 v118, v108, v109
	v_pk_mul_f32 v[108:109], v[110:111], v[148:149] op_sel_hi:[1,0]
	v_lshl_add_u64 v[120:121], v[120:121], 0, s[14:15]
	v_pk_mul_f32 v[108:109], v[108:109], v[108:109]
	v_lshl_add_u64 v[120:121], v[120:121], 0, s[24:25]
	v_and_b32_e32 v144, 48, v144
	v_cvt_pk_bf16_f32 v119, v108, v109
	v_add_u32_e32 v108, 16, v140
	v_lshl_add_u64 v[120:121], v[120:121], 0, v[144:145]
	v_ashrrev_i32_e32 v109, 31, v108
	global_store_dwordx4 v[120:121], v[116:119], off offset:256
	v_max_f32_e32 v100, 0, v100
	v_max_f32_e32 v101, 0, v101
	v_lshlrev_b64 v[116:117], 13, v[108:109]
	v_max_f32_e32 v108, v112, v112
	v_mov_b32_e32 v112, v149
	v_max_f32_e32 v102, 0, v102
	v_max_f32_e32 v103, 0, v103
	v_max_f32_e32 v96, 0, v96
	v_max_f32_e32 v97, 0, v97
	v_pk_mul_f32 v[100:101], v[100:101], v[112:113] op_sel_hi:[1,0]
	v_pk_mul_f32 v[102:103], v[102:103], v[112:113] op_sel_hi:[1,0]
	v_pk_mul_f32 v[96:97], v[96:97], v[112:113] op_sel_hi:[1,0]
	v_pk_mul_f32 v[100:101], v[100:101], v[100:101]
	v_pk_mul_f32 v[102:103], v[102:103], v[102:103]
	v_max_f32_e32 v98, 0, v98
	v_max_f32_e32 v99, 0, v99
	v_pk_mul_f32 v[96:97], v[96:97], v[96:97]
	v_cvt_pk_bf16_f32 v100, v100, v101
	v_cvt_pk_bf16_f32 v101, v102, v103
	v_cvt_pk_bf16_f32 v102, v96, v97
	v_pk_mul_f32 v[96:97], v[98:99], v[112:113] op_sel_hi:[1,0]
	ds_read2_b32 v[98:99], v146 offset0:32 offset1:48
	v_max_f32_e32 v92, 0, v92
	v_max_f32_e32 v93, 0, v93
	v_max_f32_e32 v94, 0, v94
	v_max_f32_e32 v95, 0, v95
	v_max_f32_e32 v88, 0, v88
	v_max_f32_e32 v89, 0, v89
	v_pk_mul_f32 v[96:97], v[96:97], v[96:97]
	s_waitcnt lgkmcnt(0)
;   DI void operator()(const f32x4 (&acc)[2][2][4][2], const pg8::Unit& u, int wr, int wc, int fr_, int fq_) const {
;     ...
;               if (n == 0) {
;                 const f32x4 v1 = acc[ai][bj][m][1];
;                 u32x4 o4;
;                 { const float t0 = fmaxf(v[0], 0.f) * rinv, t1 = fmaxf(v[1], 0.f) * rinv, t2 = fmaxf(v[2], 0.f) * rinv, t3 = fmaxf(v[3], 0.f) * rinv;
;                   o4.x = pack2(t0 * t0, t1 * t1); o4.y = pack2(t2 * t2, t3 * t3); }
;                 { const float t0 = fmaxf(v1[0], 0.f) * rinv, t1 = fmaxf(v1[1], 0.f) * rinv, t2 = fmaxf(v1[2], 0.f) * rinv, t3 = fmaxf(v1[3], 0.f) * rinv;
;                   o4.z = pack2(t0 * t0, t1 * t1); o4.w = pack2(t2 * t2, t3 * t3); }
;                 *(u32x4*)((u16*)big + (size_t)token * 4096 + u.pn * 256 + bj * 128 + wc * 32 + 8 * fq) = o4;
	v_pk_mul_f32 v[92:93], v[92:93], v[98:99] op_sel_hi:[1,0]
	v_pk_mul_f32 v[94:95], v[94:95], v[98:99] op_sel_hi:[1,0]
	v_pk_mul_f32 v[88:89], v[88:89], v[98:99] op_sel_hi:[1,0]
	v_cvt_pk_bf16_f32 v103, v96, v97
	v_add_u32_e32 v96, 32, v140
	v_pk_mul_f32 v[92:93], v[92:93], v[92:93]
	v_pk_mul_f32 v[94:95], v[94:95], v[94:95]
	v_max_f32_e32 v90, 0, v90
	v_max_f32_e32 v91, 0, v91
	v_pk_mul_f32 v[88:89], v[88:89], v[88:89]
	v_max_f32_e32 v84, 0, v84
	v_max_f32_e32 v85, 0, v85
	v_max_f32_e32 v86, 0, v86
	v_max_f32_e32 v87, 0, v87
	v_max_f32_e32 v76, 0, v76
	v_max_f32_e32 v77, 0, v77
	v_ashrrev_i32_e32 v97, 31, v96
	v_cvt_pk_bf16_f32 v92, v92, v93
	v_cvt_pk_bf16_f32 v93, v94, v95
	v_cvt_pk_bf16_f32 v94, v88, v89
	v_pk_mul_f32 v[88:89], v[90:91], v[98:99] op_sel_hi:[1,0]
	v_pk_mul_f32 v[84:85], v[84:85], v[98:99] op_sel_hi:[1,0]
	v_pk_mul_f32 v[86:87], v[86:87], v[98:99] op_sel_hi:[1,0]
	v_pk_mul_f32 v[76:77], v[76:77], v[98:99] op_sel_hi:[1,0]
	v_lshlrev_b64 v[96:97], 13, v[96:97]
	v_pk_mul_f32 v[88:89], v[88:89], v[88:89]
	v_pk_mul_f32 v[84:85], v[84:85], v[84:85]
	v_pk_mul_f32 v[86:87], v[86:87], v[86:87]
	v_max_f32_e32 v78, 0, v78
	v_max_f32_e32 v79, 0, v79
	v_pk_mul_f32 v[76:77], v[76:77], v[76:77]
	v_cvt_pk_bf16_f32 v95, v88, v89
	v_lshl_add_u64 v[88:89], s[2:3], 0, v[96:97]
	v_cvt_pk_bf16_f32 v84, v84, v85
	v_cvt_pk_bf16_f32 v85, v86, v87
	v_cvt_pk_bf16_f32 v86, v76, v77
	v_pk_mul_f32 v[76:77], v[78:79], v[98:99] op_sel_hi:[1,0]
	v_lshl_add_u64 v[88:89], v[88:89], 0, s[14:15]
	v_pk_mul_f32 v[76:77], v[76:77], v[76:77]
	v_lshl_add_u64 v[88:89], v[88:89], 0, s[24:25]
	v_cvt_pk_bf16_f32 v87, v76, v77
	v_add_u32_e32 v76, 48, v140
	v_lshl_add_u64 v[88:89], v[88:89], 0, v[144:145]
	v_ashrrev_i32_e32 v77, 31, v76
	global_store_dwordx4 v[88:89], v[84:87], off offset:256
	v_max_f32_e32 v68, 0, v68
	v_max_f32_e32 v69, 0, v69
	v_lshlrev_b64 v[84:85], 13, v[76:77]
	v_max_f32_e32 v76, v80, v80
	v_mov_b32_e32 v80, v99
	v_max_f32_e32 v70, 0, v70
	v_max_f32_e32 v71, 0, v71
	v_max_f32_e32 v64, 0, v64
	v_max_f32_e32 v65, 0, v65
	v_pk_mul_f32 v[68:69], v[68:69], v[80:81] op_sel_hi:[1,0]
	v_pk_mul_f32 v[70:71], v[70:71], v[80:81] op_sel_hi:[1,0]
	v_pk_mul_f32 v[64:65], v[64:65], v[80:81] op_sel_hi:[1,0]
	v_pk_mul_f32 v[68:69], v[68:69], v[68:69]
	v_pk_mul_f32 v[70:71], v[70:71], v[70:71]
	v_max_f32_e32 v66, 0, v66
	v_max_f32_e32 v67, 0, v67
	v_pk_mul_f32 v[64:65], v[64:65], v[64:65]
	v_cvt_pk_bf16_f32 v68, v68, v69
	v_cvt_pk_bf16_f32 v69, v70, v71
	v_cvt_pk_bf16_f32 v70, v64, v65
	v_pk_mul_f32 v[64:65], v[66:67], v[80:81] op_sel_hi:[1,0]
	ds_read2_b32 v[66:67], v146 offset0:128 offset1:144
	v_max_f32_e32 v60, 0, v60
	v_max_f32_e32 v61, 0, v61
	v_max_f32_e32 v62, 0, v62
	v_max_f32_e32 v63, 0, v63
	v_max_f32_e32 v56, 0, v56
	v_max_f32_e32 v57, 0, v57
	v_pk_mul_f32 v[64:65], v[64:65], v[64:65]
	s_waitcnt lgkmcnt(0)
	v_pk_mul_f32 v[60:61], v[60:61], v[66:67] op_sel_hi:[1,0]
	v_pk_mul_f32 v[62:63], v[62:63], v[66:67] op_sel_hi:[1,0]
	v_pk_mul_f32 v[56:57], v[56:57], v[66:67] op_sel_hi:[1,0]
	v_cvt_pk_bf16_f32 v71, v64, v65
	v_add_u32_e32 v64, 0x80, v140
	v_pk_mul_f32 v[60:61], v[60:61], v[60:61]
	v_pk_mul_f32 v[62:63], v[62:63], v[62:63]
	v_max_f32_e32 v58, 0, v58
	v_max_f32_e32 v59, 0, v59
	v_pk_mul_f32 v[56:57], v[56:57], v[56:57]
	v_max_f32_e32 v52, 0, v52
	v_max_f32_e32 v53, 0, v53
	v_max_f32_e32 v54, 0, v54
	v_max_f32_e32 v55, 0, v55
	v_max_f32_e32 v44, 0, v44
	v_max_f32_e32 v45, 0, v45
	v_ashrrev_i32_e32 v65, 31, v64
	v_cvt_pk_bf16_f32 v60, v60, v61
	v_cvt_pk_bf16_f32 v61, v62, v63
	v_cvt_pk_bf16_f32 v62, v56, v57
	v_pk_mul_f32 v[56:57], v[58:59], v[66:67] op_sel_hi:[1,0]
	v_pk_mul_f32 v[52:53], v[52:53], v[66:67] op_sel_hi:[1,0]
	v_pk_mul_f32 v[54:55], v[54:55], v[66:67] op_sel_hi:[1,0]
	v_pk_mul_f32 v[44:45], v[44:45], v[66:67] op_sel_hi:[1,0]
	v_lshlrev_b64 v[64:65], 13, v[64:65]
	v_pk_mul_f32 v[56:57], v[56:57], v[56:57]
	v_pk_mul_f32 v[52:53], v[52:53], v[52:53]
	v_pk_mul_f32 v[54:55], v[54:55], v[54:55]
	v_max_f32_e32 v46, 0, v46
	v_max_f32_e32 v47, 0, v47
	v_pk_mul_f32 v[44:45], v[44:45], v[44:45]
	v_cvt_pk_bf16_f32 v63, v56, v57
	v_lshl_add_u64 v[56:57], s[2:3], 0, v[64:65]
	v_cvt_pk_bf16_f32 v52, v52, v53
	v_cvt_pk_bf16_f32 v53, v54, v55
	v_cvt_pk_bf16_f32 v54, v44, v45
	v_pk_mul_f32 v[44:45], v[46:47], v[66:67] op_sel_hi:[1,0]
	v_lshl_add_u64 v[56:57], v[56:57], 0, s[14:15]
	v_pk_mul_f32 v[44:45], v[44:45], v[44:45]
	v_lshl_add_u64 v[56:57], v[56:57], 0, s[24:25]
	v_cvt_pk_bf16_f32 v55, v44, v45
	v_add_u32_e32 v44, 0x90, v140
	v_lshl_add_u64 v[56:57], v[56:57], 0, v[144:145]
	v_ashrrev_i32_e32 v45, 31, v44
	global_store_dwordx4 v[56:57], v[52:55], off offset:256
	v_max_f32_e32 v36, 0, v36
	v_max_f32_e32 v37, 0, v37
	v_lshlrev_b64 v[52:53], 13, v[44:45]
	v_max_f32_e32 v44, v48, v48
	v_mov_b32_e32 v48, v67
	v_max_f32_e32 v38, 0, v38
	v_max_f32_e32 v39, 0, v39
	v_max_f32_e32 v32, 0, v32
	v_max_f32_e32 v33, 0, v33
	v_pk_mul_f32 v[36:37], v[36:37], v[48:49] op_sel_hi:[1,0]
	v_pk_mul_f32 v[38:39], v[38:39], v[48:49] op_sel_hi:[1,0]
	v_pk_mul_f32 v[32:33], v[32:33], v[48:49] op_sel_hi:[1,0]
	v_pk_mul_f32 v[36:37], v[36:37], v[36:37]
	v_pk_mul_f32 v[38:39], v[38:39], v[38:39]
	v_max_f32_e32 v34, 0, v34
	v_max_f32_e32 v35, 0, v35
	v_pk_mul_f32 v[32:33], v[32:33], v[32:33]
	v_cvt_pk_bf16_f32 v36, v36, v37
	v_cvt_pk_bf16_f32 v37, v38, v39
	v_cvt_pk_bf16_f32 v38, v32, v33
	v_pk_mul_f32 v[32:33], v[34:35], v[48:49] op_sel_hi:[1,0]
	ds_read2_b32 v[34:35], v146 offset0:160 offset1:176
	v_max_f32_e32 v28, 0, v28
	v_max_f32_e32 v29, 0, v29
	v_max_f32_e32 v30, 0, v30
	v_max_f32_e32 v31, 0, v31
	v_max_f32_e32 v24, 0, v24
	v_max_f32_e32 v25, 0, v25
	v_pk_mul_f32 v[32:33], v[32:33], v[32:33]
	s_waitcnt lgkmcnt(0)
;   DI void operator()(const f32x4 (&acc)[2][2][4][2], const pg8::Unit& u, int wr, int wc, int fr_, int fq_) const {
;     ...
;               if (n == 0) {
;                 const f32x4 v1 = acc[ai][bj][m][1];
;                 u32x4 o4;
;                 { const float t0 = fmaxf(v[0], 0.f) * rinv, t1 = fmaxf(v[1], 0.f) * rinv, t2 = fmaxf(v[2], 0.f) * rinv, t3 = fmaxf(v[3], 0.f) * rinv;
;                   o4.x = pack2(t0 * t0, t1 * t1); o4.y = pack2(t2 * t2, t3 * t3); }
;                 { const float t0 = fmaxf(v1[0], 0.f) * rinv, t1 = fmaxf(v1[1], 0.f) * rinv, t2 = fmaxf(v1[2], 0.f) * rinv, t3 = fmaxf(v1[3], 0.f) * rinv;
;                   o4.z = pack2(t0 * t0, t1 * t1); o4.w = pack2(t2 * t2, t3 * t3); }
;                 *(u32x4*)((u16*)big + (size_t)token * 4096 + u.pn * 256 + bj * 128 + wc * 32 + 8 * fq) = o4;
	v_pk_mul_f32 v[28:29], v[28:29], v[34:35] op_sel_hi:[1,0]
	v_pk_mul_f32 v[30:31], v[30:31], v[34:35] op_sel_hi:[1,0]
	v_pk_mul_f32 v[24:25], v[24:25], v[34:35] op_sel_hi:[1,0]
	v_cvt_pk_bf16_f32 v39, v32, v33
	v_add_u32_e32 v32, 0xa0, v140
	v_pk_mul_f32 v[28:29], v[28:29], v[28:29]
	v_pk_mul_f32 v[30:31], v[30:31], v[30:31]
	v_max_f32_e32 v26, 0, v26
	v_max_f32_e32 v27, 0, v27
	v_pk_mul_f32 v[24:25], v[24:25], v[24:25]
	v_max_f32_e32 v20, 0, v20
	v_max_f32_e32 v21, 0, v21
	v_max_f32_e32 v22, 0, v22
	v_max_f32_e32 v23, 0, v23
	v_max_f32_e32 v12, 0, v12
	v_max_f32_e32 v13, 0, v13
	v_ashrrev_i32_e32 v33, 31, v32
	v_cvt_pk_bf16_f32 v28, v28, v29
	v_cvt_pk_bf16_f32 v29, v30, v31
	v_cvt_pk_bf16_f32 v30, v24, v25
	v_pk_mul_f32 v[24:25], v[26:27], v[34:35] op_sel_hi:[1,0]
	v_pk_mul_f32 v[20:21], v[20:21], v[34:35] op_sel_hi:[1,0]
	v_pk_mul_f32 v[22:23], v[22:23], v[34:35] op_sel_hi:[1,0]
	v_pk_mul_f32 v[12:13], v[12:13], v[34:35] op_sel_hi:[1,0]
	v_lshlrev_b64 v[32:33], 13, v[32:33]
	v_pk_mul_f32 v[24:25], v[24:25], v[24:25]
	v_pk_mul_f32 v[20:21], v[20:21], v[20:21]
	v_pk_mul_f32 v[22:23], v[22:23], v[22:23]
	v_max_f32_e32 v14, 0, v14
	v_max_f32_e32 v15, 0, v15
	v_pk_mul_f32 v[12:13], v[12:13], v[12:13]
	v_cvt_pk_bf16_f32 v31, v24, v25
	v_lshl_add_u64 v[24:25], s[2:3], 0, v[32:33]
	v_cvt_pk_bf16_f32 v20, v20, v21
	v_cvt_pk_bf16_f32 v21, v22, v23
	v_cvt_pk_bf16_f32 v22, v12, v13
	v_pk_mul_f32 v[12:13], v[14:15], v[34:35] op_sel_hi:[1,0]
	v_lshl_add_u64 v[24:25], v[24:25], 0, s[14:15]
	v_pk_mul_f32 v[12:13], v[12:13], v[12:13]
	v_lshl_add_u64 v[24:25], v[24:25], 0, s[24:25]
	v_cvt_pk_bf16_f32 v23, v12, v13
	v_add_u32_e32 v12, 0xb0, v140
	v_lshl_add_u64 v[24:25], v[24:25], 0, v[144:145]
	v_ashrrev_i32_e32 v13, 31, v12
	v_max_f32_e32 v109, v113, v113
	v_max_f32_e32 v110, v114, v114
	v_max_f32_e32 v111, v115, v115
	v_max_f32_e32 v77, v81, v81
	v_max_f32_e32 v78, v82, v82
	v_max_f32_e32 v79, v83, v83
	v_max_f32_e32 v45, v49, v49
	v_max_f32_e32 v46, v50, v50
	v_max_f32_e32 v47, v51, v51
	global_store_dwordx4 v[24:25], v[20:23], off offset:256
	v_max_f32_e32 v14, v18, v18
	v_max_f32_e32 v15, v19, v19
	v_lshlrev_b64 v[20:21], 13, v[12:13]
	v_max_f32_e32 v12, v16, v16
	v_max_f32_e32 v13, v17, v17
	v_max_f32_e32 v108, 0, v108
	v_max_f32_e32 v109, 0, v109
	v_max_f32_e32 v110, 0, v110
	v_max_f32_e32 v111, 0, v111
	v_max_f32_e32 v104, 0, v104
	v_max_f32_e32 v105, 0, v105
	v_max_f32_e32 v76, 0, v76
	v_max_f32_e32 v77, 0, v77
	v_max_f32_e32 v78, 0, v78
	v_max_f32_e32 v79, 0, v79
	v_max_f32_e32 v72, 0, v72
	v_max_f32_e32 v73, 0, v73
	v_max_f32_e32 v44, 0, v44
	v_max_f32_e32 v45, 0, v45
	v_max_f32_e32 v46, 0, v46
	v_max_f32_e32 v47, 0, v47
	v_max_f32_e32 v40, 0, v40
	v_max_f32_e32 v41, 0, v41
	v_max_f32_e32 v12, 0, v12
	v_max_f32_e32 v13, 0, v13
	v_max_f32_e32 v14, 0, v14
	v_max_f32_e32 v15, 0, v15
	v_mov_b32_e32 v16, v35
	v_max_f32_e32 v8, 0, v8
	v_max_f32_e32 v9, 0, v9
	v_pk_mul_f32 v[108:109], v[108:109], v[112:113] op_sel_hi:[1,0]
	v_pk_mul_f32 v[110:111], v[110:111], v[112:113] op_sel_hi:[1,0]
	v_pk_mul_f32 v[104:105], v[104:105], v[112:113] op_sel_hi:[1,0]
	v_pk_mul_f32 v[76:77], v[76:77], v[80:81] op_sel_hi:[1,0]
	v_pk_mul_f32 v[78:79], v[78:79], v[80:81] op_sel_hi:[1,0]
	v_pk_mul_f32 v[72:73], v[72:73], v[80:81] op_sel_hi:[1,0]
	v_pk_mul_f32 v[44:45], v[44:45], v[48:49] op_sel_hi:[1,0]
	v_pk_mul_f32 v[46:47], v[46:47], v[48:49] op_sel_hi:[1,0]
	v_pk_mul_f32 v[40:41], v[40:41], v[48:49] op_sel_hi:[1,0]
	v_pk_mul_f32 v[12:13], v[12:13], v[16:17] op_sel_hi:[1,0]
	v_pk_mul_f32 v[14:15], v[14:15], v[16:17] op_sel_hi:[1,0]
	v_pk_mul_f32 v[8:9], v[8:9], v[16:17] op_sel_hi:[1,0]
	v_pk_mul_f32 v[108:109], v[108:109], v[108:109]
	v_pk_mul_f32 v[110:111], v[110:111], v[110:111]
	v_max_f32_e32 v106, 0, v106
	v_max_f32_e32 v107, 0, v107
	v_pk_mul_f32 v[104:105], v[104:105], v[104:105]
; #define PG8_WAIT_V(n) asm volatile("s_waitcnt vmcnt(" #n ")" ::: "memory")
; #define PG8_BAR __builtin_amdgcn_s_barrier()
; template <class Epi, class Sched>
; DI void gemm_phase(LAS unsigned char* lds, const Gemm g, const Sched& S, const Epi& E) {
;     ...
;     E(acc, cur, wr, wc, fr, fq);
;     if (!has_next) break;
; #pragma unroll
;     for (int a = 0; a < 2; ++a)
; #pragma unroll
;       for (int b = 0; b < 2; ++b)
; #pragma unroll
;         for (int m = 0; m < 4; ++m)
; #pragma unroll
;           for (int n = 0; n < 2; ++n) acc[a][b][m][n] = (f32x4){0.f, 0.f, 0.f, 0.f};
;     cur = nxt; cA = nA; cB = nB; ++ui;
;   }
;   PG8_WAIT_V(0);
;   if (wr == 0) PG8_BAR;
;   PG8_BAR;
;   DI void operator()(const f32x4 (&acc)[2][2][4][2], const pg8::Unit& u, int wr, int wc, int fr_, int fq_) const {
;     ...
;               if (n == 0) {
;                 const f32x4 v1 = acc[ai][bj][m][1];
;                 u32x4 o4;
;                 { const float t0 = fmaxf(v[0], 0.f) * rinv, t1 = fmaxf(v[1], 0.f) * rinv, t2 = fmaxf(v[2], 0.f) * rinv, t3 = fmaxf(v[3], 0.f) * rinv;
;                   o4.x = pack2(t0 * t0, t1 * t1); o4.y = pack2(t2 * t2, t3 * t3); }
;                 { const float t0 = fmaxf(v1[0], 0.f) * rinv, t1 = fmaxf(v1[1], 0.f) * rinv, t2 = fmaxf(v1[2], 0.f) * rinv, t3 = fmaxf(v1[3], 0.f) * rinv;
;                   o4.z = pack2(t0 * t0, t1 * t1); o4.w = pack2(t2 * t2, t3 * t3); }
;                 *(u32x4*)((u16*)big + (size_t)token * 4096 + u.pn * 256 + bj * 128 + wc * 32 + 8 * fq) = o4;
	v_pk_mul_f32 v[76:77], v[76:77], v[76:77]
	v_pk_mul_f32 v[78:79], v[78:79], v[78:79]
	v_max_f32_e32 v74, 0, v74
	v_max_f32_e32 v75, 0, v75
	v_pk_mul_f32 v[72:73], v[72:73], v[72:73]
	v_pk_mul_f32 v[44:45], v[44:45], v[44:45]
	v_pk_mul_f32 v[46:47], v[46:47], v[46:47]
	v_max_f32_e32 v42, 0, v42
	v_max_f32_e32 v43, 0, v43
	v_pk_mul_f32 v[40:41], v[40:41], v[40:41]
	v_pk_mul_f32 v[12:13], v[12:13], v[12:13]
	v_pk_mul_f32 v[14:15], v[14:15], v[14:15]
	v_max_f32_e32 v10, 0, v10
	v_max_f32_e32 v11, 0, v11
	v_pk_mul_f32 v[8:9], v[8:9], v[8:9]
	v_cvt_pk_bf16_f32 v108, v108, v109
	v_cvt_pk_bf16_f32 v109, v110, v111
	v_cvt_pk_bf16_f32 v110, v104, v105
	v_pk_mul_f32 v[104:105], v[106:107], v[112:113] op_sel_hi:[1,0]
	v_cvt_pk_bf16_f32 v76, v76, v77
	v_cvt_pk_bf16_f32 v77, v78, v79
	v_cvt_pk_bf16_f32 v78, v72, v73
	v_pk_mul_f32 v[72:73], v[74:75], v[80:81] op_sel_hi:[1,0]
	v_cvt_pk_bf16_f32 v44, v44, v45
	v_cvt_pk_bf16_f32 v45, v46, v47
	v_cvt_pk_bf16_f32 v46, v40, v41
	v_pk_mul_f32 v[40:41], v[42:43], v[48:49] op_sel_hi:[1,0]
	v_cvt_pk_bf16_f32 v12, v12, v13
	v_cvt_pk_bf16_f32 v13, v14, v15
	v_cvt_pk_bf16_f32 v14, v8, v9
	v_pk_mul_f32 v[8:9], v[10:11], v[16:17] op_sel_hi:[1,0]
	v_max_f32_e32 v4, 0, v4
	v_max_f32_e32 v5, 0, v5
	v_max_f32_e32 v6, 0, v6
	v_max_f32_e32 v7, 0, v7
	v_max_f32_e32 v0, 0, v0
	v_max_f32_e32 v1, 0, v1
	v_pk_mul_f32 v[104:105], v[104:105], v[104:105]
	v_pk_mul_f32 v[72:73], v[72:73], v[72:73]
	v_pk_mul_f32 v[40:41], v[40:41], v[40:41]
	v_pk_mul_f32 v[8:9], v[8:9], v[8:9]
	v_pk_mul_f32 v[4:5], v[4:5], v[16:17] op_sel_hi:[1,0]
	v_pk_mul_f32 v[6:7], v[6:7], v[16:17] op_sel_hi:[1,0]
	v_pk_mul_f32 v[0:1], v[0:1], v[16:17] op_sel_hi:[1,0]
	v_cvt_pk_bf16_f32 v111, v104, v105
	v_lshl_add_u64 v[104:105], s[2:3], 0, v[116:117]
	v_cvt_pk_bf16_f32 v79, v72, v73
	v_lshl_add_u64 v[72:73], s[2:3], 0, v[84:85]
	v_cvt_pk_bf16_f32 v47, v40, v41
	v_lshl_add_u64 v[40:41], s[2:3], 0, v[52:53]
	v_cvt_pk_bf16_f32 v15, v8, v9
	v_lshl_add_u64 v[8:9], s[2:3], 0, v[20:21]
	v_pk_mul_f32 v[4:5], v[4:5], v[4:5]
	v_pk_mul_f32 v[6:7], v[6:7], v[6:7]
	v_max_f32_e32 v2, 0, v2
	v_max_f32_e32 v3, 0, v3
	v_pk_mul_f32 v[0:1], v[0:1], v[0:1]
	v_lshl_add_u64 v[104:105], v[104:105], 0, s[14:15]
	v_lshl_add_u64 v[72:73], v[72:73], 0, s[14:15]
	v_lshl_add_u64 v[40:41], v[40:41], 0, s[14:15]
	v_lshl_add_u64 v[8:9], v[8:9], 0, s[14:15]
	v_cvt_pk_bf16_f32 v4, v4, v5
	v_cvt_pk_bf16_f32 v5, v6, v7
	v_cvt_pk_bf16_f32 v6, v0, v1
	v_pk_mul_f32 v[0:1], v[2:3], v[16:17] op_sel_hi:[1,0]
	v_lshl_add_u64 v[104:105], v[104:105], 0, s[24:25]
	v_lshl_add_u64 v[72:73], v[72:73], 0, s[24:25]
	v_lshl_add_u64 v[40:41], v[40:41], 0, s[24:25]
	v_lshl_add_u64 v[8:9], v[8:9], 0, s[24:25]
	v_pk_mul_f32 v[0:1], v[0:1], v[0:1]
	v_lshl_add_u64 v[104:105], v[104:105], 0, v[144:145]
	v_lshl_add_u64 v[72:73], v[72:73], 0, v[144:145]
	v_lshl_add_u64 v[40:41], v[40:41], 0, v[144:145]
	v_lshl_add_u64 v[8:9], v[8:9], 0, v[144:145]
	v_cvt_pk_bf16_f32 v7, v0, v1
	s_and_b64 vcc, exec, s[36:37]
	s_mov_b32 s43, s42
	s_mov_b32 s45, s4
	s_mov_b32 s44, s6
	s_mov_b64 s[16:17], s[12:13]
	s_mov_b64 s[14:15], s[10:11]
	v_readlane_b32 s51, v237, 11
	global_store_dwordx4 v[120:121], v[124:127], off
	global_store_dwordx4 v[104:105], v[108:111], off
	global_store_dwordx4 v[104:105], v[100:103], off offset:256
	global_store_dwordx4 v[88:89], v[92:95], off
	global_store_dwordx4 v[72:73], v[76:79], off
	global_store_dwordx4 v[72:73], v[68:71], off offset:256
	global_store_dwordx4 v[56:57], v[60:63], off
	global_store_dwordx4 v[40:41], v[44:47], off
	global_store_dwordx4 v[40:41], v[36:39], off offset:256
	global_store_dwordx4 v[24:25], v[28:31], off
	global_store_dwordx4 v[8:9], v[12:15], off
	global_store_dwordx4 v[8:9], v[4:7], off offset:256
	s_cbranch_vccz .LBB0_1822
	s_waitcnt vmcnt(0)
	s_cmpk_gt_u32 s9, 0xff
	s_cbranch_scc1 .LBB0_1833
	s_barrier

; #define PG8_STAGE(bufoff, gbase, voff) do { _Pragma("unroll") for (int _i = 0; _i < 2; ++_i) \
;     __builtin_amdgcn_global_load_lds((const unsigned*)((const char*)(gbase) + (voff)[_i]), (LAS unsigned*)(lds + (bufoff) + ldsw + _i * 8192), 16, 0, 0); } while (0)
; #define PG8_LDA(dst, b, h) do { _Pragma("unroll") for (int m = 0; m < 4; ++m) _Pragma("unroll") for (int k = 0; k < 2; ++k) dst[m][k] = *(const LAS bf16x8*)(lds + PG8_SA(b, h) + aoff + m * 2048 + k * 1024); } while (0)
; #define PG8_LDB(dst, b, h) do { _Pragma("unroll") for (int n = 0; n < 2; ++n) _Pragma("unroll") for (int k = 0; k < 2; ++k) dst[n][k] = *(const LAS bf16x8*)(lds + PG8_SB(b, h) + boff + n * 2048 + k * 1024); } while (0)
; #define PG8_MMA(ai, bj, At, Bt) do { __builtin_amdgcn_s_setprio(1); _Pragma("unroll") for (int m = 0; m < 4; ++m) _Pragma("unroll") for (int n = 0; n < 2; ++n) _Pragma("unroll") for (int k = 0; k < 2; ++k) \
;     acc[ai][bj][m][n] = __builtin_amdgcn_mfma_f32_16x16x32_bf16(Bt[n][k], At[m][k], acc[ai][bj][m][n], 0, 0, 0); __builtin_amdgcn_s_setprio(0); } while (0)
; template <class Epi, class Sched>
; DI void gemm_phase(LAS unsigned char* lds, const Gemm g, const Sched& S, const Epi& E) {
;     ...
;       const bool last = (t == nt - 2);
;       const char* a1 = cA + (size_t)(t + 1) * kstep;
;       const char* a2 = last ? nA : cA + (size_t)(t + 2) * kstep; const char* b2 = last ? nB : cB + (size_t)(t + 2) * kstep;
;       const char* a3 = a2 + kstep; const char* b3 = b2 + kstep;
;       PG8_LDB(B0, 0, 0); PG8_SCHED; PG8_LDA(At, 0, 0); PG8_STAGE(PG8_SA(1, 1), a1 + hstep, voffA);
;       PG8_WAIT_L(8); PG8_BAR; PG8_WAIT_L(0); PG8_MMA(0, 0, At, B0); PG8_BAR; PG8_SCHED;
;       PG8_LDB(B1, 0, 1); PG8_STAGE(PG8_SB(0, 0), b2, voffB);
;       PG8_BAR; PG8_WAIT_L(0); PG8_MMA(0, 1, At, B1); PG8_BAR;
;       PG8_LDA(At, 0, 1); PG8_STAGE(PG8_SA(0, 0), a2, voffA);
;       PG8_BAR; PG8_WAIT_L(0); PG8_MMA(1, 0, At, B0); PG8_BAR; PG8_SCHED;
;       PG8_STAGE(PG8_SB(0, 1), b2 + hstep, voffB);
;       PG8_WAIT_V(6); PG8_BAR; PG8_MMA(1, 1, At, B1); PG8_BAR;
;       PG8_LDB(B0, 1, 0); PG8_SCHED; PG8_LDA(At, 1, 0); PG8_STAGE(PG8_SA(0, 1), a2 + hstep, voffA);
;       PG8_WAIT_L(8); PG8_BAR; PG8_WAIT_L(0); PG8_MMA(0, 0, At, B0); PG8_BAR; PG8_SCHED;
;       PG8_LDB(B1, 1, 1); PG8_STAGE(PG8_SB(1, 0), b3, voffB);
;       PG8_BAR; PG8_WAIT_L(0); PG8_MMA(0, 1, At, B1); PG8_BAR;
.LBB0_1905:
	s_add_u32 s22, s20, 0xfff00080
	s_addc_u32 s23, s21, -1
	s_add_i32 s51, 0, 0x10000
	v_add_u32_e32 v142, s51, v146
	ds_read_b128 v[138:141], v142
	ds_read_b128 v[148:151], v142 offset:1024
	ds_read_b128 v[152:155], v142 offset:2048
	ds_read_b128 v[156:159], v142 offset:3072
	s_cmp_eq_u32 s50, 60
	s_cselect_b32 s29, s11, s23
	s_cselect_b32 s28, s17, s22
	s_cselect_b32 s23, s7, s49
	s_cselect_b32 s22, s19, s24
	v_lshl_add_u64 v[142:143], s[20:21], 0, v[134:135]
	s_add_i32 m0, s39, 0xc000
	ds_read_b128 v[160:163], v147
	ds_read_b128 v[164:167], v147 offset:1024
	ds_read_b128 v[168:171], v147 offset:2048
	ds_read_b128 v[172:175], v147 offset:3072
	ds_read_b128 v[176:179], v147 offset:4096
	ds_read_b128 v[196:199], v147 offset:5120
	ds_read_b128 v[200:203], v147 offset:6144
	ds_read_b128 v[204:207], v147 offset:7168
	global_load_lds_dwordx4 v[142:143], off
	v_lshl_add_u64 v[142:143], s[20:21], 0, v[136:137]
	s_add_i32 m0, s39, 0xe000
	s_nop 0
	global_load_lds_dwordx4 v[142:143], off
	s_waitcnt lgkmcnt(8)
	s_barrier
	s_waitcnt lgkmcnt(0)
	v_mfma_f32_16x16x32_bf16 v[124:127], v[138:141], v[160:163], v[124:127]
	v_mfma_f32_16x16x32_bf16 v[120:123], v[152:155], v[160:163], v[120:123]
	v_mfma_f32_16x16x32_bf16 v[108:111], v[138:141], v[168:171], v[108:111]
	v_mfma_f32_16x16x32_bf16 v[104:107], v[152:155], v[168:171], v[104:107]
	v_mfma_f32_16x16x32_bf16 v[92:95], v[138:141], v[176:179], v[92:95]
	v_mfma_f32_16x16x32_bf16 v[88:91], v[152:155], v[176:179], v[88:91]
	v_mfma_f32_16x16x32_bf16 v[76:79], v[138:141], v[200:203], v[76:79]
	v_mfma_f32_16x16x32_bf16 v[72:75], v[152:155], v[200:203], v[72:75]
	v_mfma_f32_16x16x32_bf16 v[124:127], v[148:151], v[164:167], v[124:127]
	v_mfma_f32_16x16x32_bf16 v[120:123], v[156:159], v[164:167], v[120:123]
	v_mfma_f32_16x16x32_bf16 v[108:111], v[148:151], v[172:175], v[108:111]
	v_mfma_f32_16x16x32_bf16 v[104:107], v[156:159], v[172:175], v[104:107]
	v_mfma_f32_16x16x32_bf16 v[92:95], v[148:151], v[196:199], v[92:95]
	v_mfma_f32_16x16x32_bf16 v[88:91], v[156:159], v[196:199], v[88:91]
	v_mfma_f32_16x16x32_bf16 v[76:79], v[148:151], v[204:207], v[76:79]
	v_mfma_f32_16x16x32_bf16 v[72:75], v[156:159], v[204:207], v[72:75]
	s_barrier
	s_add_i32 s54, 0, 0x14000
	v_add_u32_e32 v142, s54, v146
	s_add_i32 s51, s51, s38
	ds_read_b128 v[208:211], v142
	ds_read_b128 v[212:215], v142 offset:1024
	ds_read_b128 v[216:219], v142 offset:2048
	ds_read_b128 v[220:223], v142 offset:3072
	v_lshl_add_u64 v[142:143], s[22:23], 0, v[144:145]
	s_mov_b32 m0, s51
	v_lshl_add_u64 v[180:181], s[22:23], 0, v[132:133]
	global_load_lds_dwordx4 v[142:143], off
	s_add_i32 m0, s51, 0x2000
	s_nop 0
	global_load_lds_dwordx4 v[180:181], off
	s_barrier
	s_waitcnt lgkmcnt(0)
	v_mfma_f32_16x16x32_bf16 v[116:119], v[208:211], v[160:163], v[116:119]
	v_mfma_f32_16x16x32_bf16 v[112:115], v[216:219], v[160:163], v[112:115]
	v_mfma_f32_16x16x32_bf16 v[100:103], v[208:211], v[168:171], v[100:103]
	v_mfma_f32_16x16x32_bf16 v[96:99], v[216:219], v[168:171], v[96:99]
	v_mfma_f32_16x16x32_bf16 v[84:87], v[208:211], v[176:179], v[84:87]
	v_mfma_f32_16x16x32_bf16 v[80:83], v[216:219], v[176:179], v[80:83]
	v_mfma_f32_16x16x32_bf16 v[68:71], v[208:211], v[200:203], v[68:71]
	v_mfma_f32_16x16x32_bf16 v[64:67], v[216:219], v[200:203], v[64:67]
	v_mfma_f32_16x16x32_bf16 v[116:119], v[212:215], v[164:167], v[116:119]
	v_mfma_f32_16x16x32_bf16 v[112:115], v[220:223], v[164:167], v[112:115]
	v_mfma_f32_16x16x32_bf16 v[100:103], v[212:215], v[172:175], v[100:103]
	v_mfma_f32_16x16x32_bf16 v[96:99], v[220:223], v[172:175], v[96:99]
	v_mfma_f32_16x16x32_bf16 v[84:87], v[212:215], v[196:199], v[84:87]
	v_mfma_f32_16x16x32_bf16 v[80:83], v[220:223], v[196:199], v[80:83]
	v_mfma_f32_16x16x32_bf16 v[68:71], v[212:215], v[204:207], v[68:71]
	v_mfma_f32_16x16x32_bf16 v[64:67], v[220:223], v[204:207], v[64:67]
	s_mov_b32 m0, s39
	v_lshl_add_u64 v[224:225], s[28:29], 0, v[128:129]
	s_barrier
	ds_read_b128 v[160:163], v147 offset:16384
	ds_read_b128 v[164:167], v147 offset:17408
	ds_read_b128 v[168:171], v147 offset:18432
	ds_read_b128 v[172:175], v147 offset:19456
	ds_read_b128 v[176:179], v147 offset:20480
	ds_read_b128 v[196:199], v147 offset:21504
	ds_read_b128 v[200:203], v147 offset:22528
	ds_read_b128 v[204:207], v147 offset:23552
	global_load_lds_dwordx4 v[224:225], off
	v_lshl_add_u64 v[226:227], s[28:29], 0, v[130:131]
	s_mov_b32 m0, s40
	s_nop 0
	global_load_lds_dwordx4 v[226:227], off
	s_barrier
	s_waitcnt lgkmcnt(0)
	v_mfma_f32_16x16x32_bf16 v[60:63], v[138:141], v[160:163], v[60:63]
	v_mfma_f32_16x16x32_bf16 v[56:59], v[152:155], v[160:163], v[56:59]
	v_mfma_f32_16x16x32_bf16 v[44:47], v[138:141], v[168:171], v[44:47]
	v_mfma_f32_16x16x32_bf16 v[40:43], v[152:155], v[168:171], v[40:43]
	v_mfma_f32_16x16x32_bf16 v[28:31], v[138:141], v[176:179], v[28:31]
	v_mfma_f32_16x16x32_bf16 v[24:27], v[152:155], v[176:179], v[24:27]
	v_mfma_f32_16x16x32_bf16 v[12:15], v[138:141], v[200:203], v[12:15]
	v_mfma_f32_16x16x32_bf16 v[8:11], v[152:155], v[200:203], v[8:11]
	v_mfma_f32_16x16x32_bf16 v[60:63], v[148:151], v[164:167], v[60:63]
	v_mfma_f32_16x16x32_bf16 v[56:59], v[156:159], v[164:167], v[56:59]
	v_mfma_f32_16x16x32_bf16 v[44:47], v[148:151], v[172:175], v[44:47]
	v_mfma_f32_16x16x32_bf16 v[40:43], v[156:159], v[172:175], v[40:43]
	v_mfma_f32_16x16x32_bf16 v[28:31], v[148:151], v[196:199], v[28:31]
	v_mfma_f32_16x16x32_bf16 v[24:27], v[156:159], v[196:199], v[24:27]
	v_mfma_f32_16x16x32_bf16 v[12:15], v[148:151], v[204:207], v[12:15]
	v_mfma_f32_16x16x32_bf16 v[8:11], v[156:159], v[204:207], v[8:11]
	s_barrier
; #define PG8_STAGE(bufoff, gbase, voff) do { _Pragma("unroll") for (int _i = 0; _i < 2; ++_i) \
;     __builtin_amdgcn_global_load_lds((const unsigned*)((const char*)(gbase) + (voff)[_i]), (LAS unsigned*)(lds + (bufoff) + ldsw + _i * 8192), 16, 0, 0); } while (0)
; #define PG8_LDA(dst, b, h) do { _Pragma("unroll") for (int m = 0; m < 4; ++m) _Pragma("unroll") for (int k = 0; k < 2; ++k) dst[m][k] = *(const LAS bf16x8*)(lds + PG8_SA(b, h) + aoff + m * 2048 + k * 1024); } while (0)
; #define PG8_LDB(dst, b, h) do { _Pragma("unroll") for (int n = 0; n < 2; ++n) _Pragma("unroll") for (int k = 0; k < 2; ++k) dst[n][k] = *(const LAS bf16x8*)(lds + PG8_SB(b, h) + boff + n * 2048 + k * 1024); } while (0)
; #define PG8_MMA(ai, bj, At, Bt) do { __builtin_amdgcn_s_setprio(1); _Pragma("unroll") for (int m = 0; m < 4; ++m) _Pragma("unroll") for (int n = 0; n < 2; ++n) _Pragma("unroll") for (int k = 0; k < 2; ++k) \
;     acc[ai][bj][m][n] = __builtin_amdgcn_mfma_f32_16x16x32_bf16(Bt[n][k], At[m][k], acc[ai][bj][m][n], 0, 0, 0); __builtin_amdgcn_s_setprio(0); } while (0)
; #define PG8_WAIT_V(n) asm volatile("s_waitcnt vmcnt(" #n ")" ::: "memory")
; #define PG8_WAIT_L(n) asm volatile("s_waitcnt lgkmcnt(" #n ")" ::: "memory")
; #define PG8_BAR __builtin_amdgcn_s_barrier()
; #define PG8_SCHED __builtin_amdgcn_sched_barrier(0)
; template <class Epi, class Sched>
; DI void gemm_phase(LAS unsigned char* lds, const Gemm g, const Sched& S, const Epi& E) {
;     ...
;       PG8_BAR; PG8_WAIT_L(0); PG8_MMA(1, 0, At, B0); PG8_BAR; PG8_SCHED;
;       PG8_STAGE(PG8_SB(0, 1), b2 + hstep, voffB);
;       PG8_WAIT_V(6); PG8_BAR; PG8_MMA(1, 1, At, B1); PG8_BAR;
;       PG8_LDB(B0, 1, 0); PG8_SCHED; PG8_LDA(At, 1, 0); PG8_STAGE(PG8_SA(0, 1), a2 + hstep, voffA);
;       PG8_WAIT_L(8); PG8_BAR; PG8_WAIT_L(0); PG8_MMA(0, 0, At, B0); PG8_BAR; PG8_SCHED;
;       PG8_LDB(B1, 1, 1); PG8_STAGE(PG8_SB(1, 0), b3, voffB);
;       PG8_BAR; PG8_WAIT_L(0); PG8_MMA(0, 1, At, B1); PG8_BAR;
;       PG8_LDA(At, 1, 1); PG8_STAGE(PG8_SA(1, 0), a3, voffA);
;       PG8_BAR; PG8_WAIT_L(0); PG8_MMA(1, 0, At, B0); PG8_BAR; PG8_SCHED;
	s_add_u32 s52, s22, 0x100000
	s_addc_u32 s53, s23, 0
	s_add_i32 s51, s54, s38
	v_lshl_add_u64 v[138:139], s[52:53], 0, v[144:145]
	s_mov_b32 m0, s51
	s_nop 0
	global_load_lds_dwordx4 v[138:139], off
	v_lshl_add_u64 v[138:139], s[52:53], 0, v[132:133]
	s_add_i32 m0, s51, 0x2000
	s_nop 0
	global_load_lds_dwordx4 v[138:139], off
	s_waitcnt vmcnt(6)
	s_barrier
	v_mfma_f32_16x16x32_bf16 v[52:55], v[208:211], v[160:163], v[52:55]
	v_mfma_f32_16x16x32_bf16 v[48:51], v[216:219], v[160:163], v[48:51]
	v_mfma_f32_16x16x32_bf16 v[36:39], v[208:211], v[168:171], v[36:39]
	v_mfma_f32_16x16x32_bf16 v[32:35], v[216:219], v[168:171], v[32:35]
	v_mfma_f32_16x16x32_bf16 v[20:23], v[208:211], v[176:179], v[20:23]
	v_mfma_f32_16x16x32_bf16 v[16:19], v[216:219], v[176:179], v[16:19]
	v_mfma_f32_16x16x32_bf16 v[4:7], v[208:211], v[200:203], v[4:7]
	v_mfma_f32_16x16x32_bf16 v[0:3], v[216:219], v[200:203], v[0:3]
	v_mfma_f32_16x16x32_bf16 v[52:55], v[212:215], v[164:167], v[52:55]
	v_mfma_f32_16x16x32_bf16 v[48:51], v[220:223], v[164:167], v[48:51]
	v_mfma_f32_16x16x32_bf16 v[36:39], v[212:215], v[172:175], v[36:39]
	v_mfma_f32_16x16x32_bf16 v[32:35], v[220:223], v[172:175], v[32:35]
	v_mfma_f32_16x16x32_bf16 v[20:23], v[212:215], v[196:199], v[20:23]
	v_mfma_f32_16x16x32_bf16 v[16:19], v[220:223], v[196:199], v[16:19]
	v_mfma_f32_16x16x32_bf16 v[4:7], v[212:215], v[204:207], v[4:7]
	v_mfma_f32_16x16x32_bf16 v[0:3], v[220:223], v[204:207], v[0:3]
	s_add_i32 s51, 0, 0x18000
	v_add_u32_e32 v156, s51, v146
	s_barrier
	ds_read_b128 v[138:141], v156
	ds_read_b128 v[148:151], v156 offset:1024
	ds_read_b128 v[152:155], v156 offset:2048
	ds_read_b128 v[156:159], v156 offset:3072
	s_add_u32 s28, s28, 0x100000
	s_addc_u32 s29, s29, 0
	s_mov_b32 m0, s41
	v_lshl_add_u64 v[208:209], s[28:29], 0, v[128:129]
	ds_read_b128 v[160:163], v147 offset:32768
	ds_read_b128 v[164:167], v147 offset:33792
	ds_read_b128 v[168:171], v147 offset:34816
	ds_read_b128 v[172:175], v147 offset:35840
	ds_read_b128 v[176:179], v147 offset:36864
	ds_read_b128 v[196:199], v147 offset:37888
	ds_read_b128 v[200:203], v147 offset:38912
	ds_read_b128 v[204:207], v147 offset:39936
	global_load_lds_dwordx4 v[208:209], off
	v_lshl_add_u64 v[208:209], s[28:29], 0, v[130:131]
	s_mov_b32 m0, s42
	s_nop 0
	global_load_lds_dwordx4 v[208:209], off
	s_waitcnt lgkmcnt(8)
	s_barrier
	s_waitcnt lgkmcnt(0)
	v_mfma_f32_16x16x32_bf16 v[124:127], v[138:141], v[160:163], v[124:127]
	v_mfma_f32_16x16x32_bf16 v[120:123], v[152:155], v[160:163], v[120:123]
	v_mfma_f32_16x16x32_bf16 v[108:111], v[138:141], v[168:171], v[108:111]
	v_mfma_f32_16x16x32_bf16 v[104:107], v[152:155], v[168:171], v[104:107]
	v_mfma_f32_16x16x32_bf16 v[92:95], v[138:141], v[176:179], v[92:95]
	v_mfma_f32_16x16x32_bf16 v[88:91], v[152:155], v[176:179], v[88:91]
	v_mfma_f32_16x16x32_bf16 v[76:79], v[138:141], v[200:203], v[76:79]
	v_mfma_f32_16x16x32_bf16 v[72:75], v[152:155], v[200:203], v[72:75]
	v_mfma_f32_16x16x32_bf16 v[124:127], v[148:151], v[164:167], v[124:127]
	v_mfma_f32_16x16x32_bf16 v[120:123], v[156:159], v[164:167], v[120:123]
	v_mfma_f32_16x16x32_bf16 v[108:111], v[148:151], v[172:175], v[108:111]
	v_mfma_f32_16x16x32_bf16 v[104:107], v[156:159], v[172:175], v[104:107]
	v_mfma_f32_16x16x32_bf16 v[92:95], v[148:151], v[196:199], v[92:95]
	v_mfma_f32_16x16x32_bf16 v[88:91], v[156:159], v[196:199], v[88:91]
	v_mfma_f32_16x16x32_bf16 v[76:79], v[148:151], v[204:207], v[76:79]
	v_mfma_f32_16x16x32_bf16 v[72:75], v[156:159], v[204:207], v[72:75]
	s_barrier
	s_add_i32 s28, 0, 0x1c000
	s_add_i32 s29, s51, s38
	v_add_u32_e32 v220, s28, v146
	v_lshl_add_u64 v[142:143], v[142:143], 0, s[0:1]
	s_mov_b32 m0, s29
	ds_read_b128 v[208:211], v220
	ds_read_b128 v[212:215], v220 offset:1024
	ds_read_b128 v[216:219], v220 offset:2048
	ds_read_b128 v[220:223], v220 offset:3072
	global_load_lds_dwordx4 v[142:143], off
	v_lshl_add_u64 v[142:143], v[180:181], 0, s[0:1]
	s_add_i32 m0, s29, 0x2000
	s_nop 0
	global_load_lds_dwordx4 v[142:143], off
	s_barrier
	s_waitcnt lgkmcnt(0)
	v_mfma_f32_16x16x32_bf16 v[116:119], v[208:211], v[160:163], v[116:119]
	v_mfma_f32_16x16x32_bf16 v[112:115], v[216:219], v[160:163], v[112:115]
	v_mfma_f32_16x16x32_bf16 v[100:103], v[208:211], v[168:171], v[100:103]
	v_mfma_f32_16x16x32_bf16 v[96:99], v[216:219], v[168:171], v[96:99]
	v_mfma_f32_16x16x32_bf16 v[84:87], v[208:211], v[176:179], v[84:87]
	v_mfma_f32_16x16x32_bf16 v[80:83], v[216:219], v[176:179], v[80:83]
	v_mfma_f32_16x16x32_bf16 v[68:71], v[208:211], v[200:203], v[68:71]
	v_mfma_f32_16x16x32_bf16 v[64:67], v[216:219], v[200:203], v[64:67]
	v_mfma_f32_16x16x32_bf16 v[116:119], v[212:215], v[164:167], v[116:119]
	v_mfma_f32_16x16x32_bf16 v[112:115], v[220:223], v[164:167], v[112:115]
	v_mfma_f32_16x16x32_bf16 v[100:103], v[212:215], v[172:175], v[100:103]
	v_mfma_f32_16x16x32_bf16 v[96:99], v[220:223], v[172:175], v[96:99]
	v_mfma_f32_16x16x32_bf16 v[84:87], v[212:215], v[196:199], v[84:87]
	v_mfma_f32_16x16x32_bf16 v[80:83], v[220:223], v[196:199], v[80:83]
	v_mfma_f32_16x16x32_bf16 v[68:71], v[212:215], v[204:207], v[68:71]
	v_mfma_f32_16x16x32_bf16 v[64:67], v[220:223], v[204:207], v[64:67]
	s_mov_b32 m0, s46
	v_lshl_add_u64 v[142:143], v[224:225], 0, s[0:1]
	s_barrier
	ds_read_b128 v[160:163], v147 offset:49152
	ds_read_b128 v[164:167], v147 offset:50176
	ds_read_b128 v[168:171], v147 offset:51200
	ds_read_b128 v[172:175], v147 offset:52224
	ds_read_b128 v[176:179], v147 offset:53248
	ds_read_b128 v[196:199], v147 offset:54272
	ds_read_b128 v[200:203], v147 offset:55296
	ds_read_b128 v[204:207], v147 offset:56320
	global_load_lds_dwordx4 v[142:143], off
	v_lshl_add_u64 v[142:143], v[226:227], 0, s[0:1]
	s_mov_b32 m0, s47
	s_nop 0
	global_load_lds_dwordx4 v[142:143], off
	s_barrier
; template <class Epi, class Sched>
; DI void gemm_phase(LAS unsigned char* lds, const Gemm g, const Sched& S, const Epi& E) {
;     ...
;       PG8_BAR; PG8_WAIT_L(0); PG8_MMA(1, 0, At, B0); PG8_BAR; PG8_SCHED;
;       PG8_STAGE(PG8_SB(1, 1), b3 + hstep, voffB);
;       PG8_WAIT_V(6); PG8_BAR; PG8_MMA(1, 1, At, B1); PG8_BAR;
;   DI void operator()(const f32x4 (&acc)[2][2][4][2], const pg8::Unit& u, int wr, int wc, int fr_, int fq_) const {
;     ...
;             } else if (EPI == EPI_RESID) {
;               if (n == 0) {
;                 const int f8 = u.pn * 256 + bj * 128 + wc * 32 + 8 * fq;
;                 const f32x4 v1 = acc[ai][bj][m][1];
;                 f32x4 r0, r1;
;                 if (rsrc) {
;                   r0 = *(const f32x4*)(rsrc + (size_t)token * 1024 + f8); r1 = *(const f32x4*)(rsrc + (size_t)token * 1024 + f8 + 4);
;                 } else {
;                   const u32x4 xu = *(const u32x4*)(xr + (size_t)token * 1024 + f8);
;                   r0 = (f32x4){bf2f(xu.x & 0xffffu), bf2f(xu.x >> 16), bf2f(xu.y & 0xffffu), bf2f(xu.y >> 16)};
;                   r1 = (f32x4){bf2f(xu.z & 0xffffu), bf2f(xu.z >> 16), bf2f(xu.w & 0xffffu), bf2f(xu.w >> 16)};
;                 }
;                 r0 += v; r1 += v1;
;                 st_bf8(xr + (size_t)token * 1024 + f8, r0, r1, 1.f);
;                 ssq += r0[0] * r0[0] + r0[1] * r0[1] + r0[2] * r0[2] + r0[3] * r0[3] + r1[0] * r1[0] + r1[1] * r1[1] + r1[2] * r1[2] + r1[3] * r1[3];
;               }
;             } else {
;               if (n == 0) {
;                 const f32x4 v1 = acc[ai][bj][m][1];
;                 u32x4 o4;
;                 { const float t0 = fmaxf(v[0], 0.f) * rinv, t1 = fmaxf(v[1], 0.f) * rinv, t2 = fmaxf(v[2], 0.f) * rinv, t3 = fmaxf(v[3], 0.f) * rinv;
;                   o4.x = pack2(t0 * t0, t1 * t1); o4.y = pack2(t2 * t2, t3 * t3); }
;                 { const float t0 = fmaxf(v1[0], 0.f) * rinv, t1 = fmaxf(v1[1], 0.f) * rinv, t2 = fmaxf(v1[2], 0.f) * rinv, t3 = fmaxf(v1[3], 0.f) * rinv;
;                   o4.z = pack2(t0 * t0, t1 * t1); o4.w = pack2(t2 * t2, t3 * t3); }
;                 *(u32x4*)((u16*)big + (size_t)token * 4096 + u.pn * 256 + bj * 128 + wc * 32 + 8 * fq) = o4;
;               }
;             }
;           }
;         if (EPI == EPI_RESID) {
;           ssq += shx(ssq, 16, t_ & 63);
;           ssq += shx(ssq, 32, t_ & 63);
	s_waitcnt lgkmcnt(0)
	v_mfma_f32_16x16x32_bf16 v[60:63], v[138:141], v[160:163], v[60:63]
	v_mfma_f32_16x16x32_bf16 v[56:59], v[152:155], v[160:163], v[56:59]
	v_mfma_f32_16x16x32_bf16 v[44:47], v[138:141], v[168:171], v[44:47]
	v_mfma_f32_16x16x32_bf16 v[40:43], v[152:155], v[168:171], v[40:43]
	v_mfma_f32_16x16x32_bf16 v[28:31], v[138:141], v[176:179], v[28:31]
	v_mfma_f32_16x16x32_bf16 v[24:27], v[152:155], v[176:179], v[24:27]
	v_mfma_f32_16x16x32_bf16 v[12:15], v[138:141], v[200:203], v[12:15]
	v_mfma_f32_16x16x32_bf16 v[8:11], v[152:155], v[200:203], v[8:11]
	v_mfma_f32_16x16x32_bf16 v[60:63], v[148:151], v[164:167], v[60:63]
	v_mfma_f32_16x16x32_bf16 v[56:59], v[156:159], v[164:167], v[56:59]
	v_mfma_f32_16x16x32_bf16 v[44:47], v[148:151], v[172:175], v[44:47]
	v_mfma_f32_16x16x32_bf16 v[40:43], v[156:159], v[172:175], v[40:43]
	v_mfma_f32_16x16x32_bf16 v[28:31], v[148:151], v[196:199], v[28:31]
	v_mfma_f32_16x16x32_bf16 v[24:27], v[156:159], v[196:199], v[24:27]
	v_mfma_f32_16x16x32_bf16 v[12:15], v[148:151], v[204:207], v[12:15]
	v_mfma_f32_16x16x32_bf16 v[8:11], v[156:159], v[204:207], v[8:11]
	s_barrier
	s_add_u32 s22, s22, 0x100080
	s_addc_u32 s23, s23, 0
	s_add_i32 s28, s28, s38
	v_lshl_add_u64 v[138:139], s[22:23], 0, v[144:145]
	s_mov_b32 m0, s28
	s_nop 0
	global_load_lds_dwordx4 v[138:139], off
	v_lshl_add_u64 v[138:139], s[22:23], 0, v[132:133]
	s_add_i32 m0, s28, 0x2000
	s_nop 0
	global_load_lds_dwordx4 v[138:139], off
	s_waitcnt vmcnt(6)
	s_barrier
	v_mfma_f32_16x16x32_bf16 v[52:55], v[208:211], v[160:163], v[52:55]
	v_mfma_f32_16x16x32_bf16 v[48:51], v[216:219], v[160:163], v[48:51]
	v_mfma_f32_16x16x32_bf16 v[36:39], v[208:211], v[168:171], v[36:39]
	v_mfma_f32_16x16x32_bf16 v[32:35], v[216:219], v[168:171], v[32:35]
	v_mfma_f32_16x16x32_bf16 v[20:23], v[208:211], v[176:179], v[20:23]
	v_mfma_f32_16x16x32_bf16 v[16:19], v[216:219], v[176:179], v[16:19]
	v_mfma_f32_16x16x32_bf16 v[4:7], v[208:211], v[200:203], v[4:7]
	v_mfma_f32_16x16x32_bf16 v[0:3], v[216:219], v[200:203], v[0:3]
	v_mfma_f32_16x16x32_bf16 v[52:55], v[212:215], v[164:167], v[52:55]
	v_mfma_f32_16x16x32_bf16 v[48:51], v[220:223], v[164:167], v[48:51]
	v_mfma_f32_16x16x32_bf16 v[36:39], v[212:215], v[172:175], v[36:39]
	v_mfma_f32_16x16x32_bf16 v[32:35], v[220:223], v[172:175], v[32:35]
	v_mfma_f32_16x16x32_bf16 v[20:23], v[212:215], v[196:199], v[20:23]
	v_mfma_f32_16x16x32_bf16 v[16:19], v[220:223], v[196:199], v[16:19]
	v_mfma_f32_16x16x32_bf16 v[4:7], v[212:215], v[204:207], v[4:7]
	v_mfma_f32_16x16x32_bf16 v[0:3], v[220:223], v[204:207], v[0:3]
	s_add_i32 s50, s50, 2
	s_add_u32 s20, s20, 0x100
	s_addc_u32 s21, s21, 0
	s_add_u32 s24, s24, 0x100
	s_addc_u32 s49, s49, 0
	s_cmp_gt_u32 s50, 61
	s_barrier
	s_cbranch_scc0 .LBB0_1905
	s_lshl_b32 s7, s18, 8
	v_mov_b32_e32 v139, v182
	s_add_i32 s7, s7, s44
	s_nop 0
	v_and_or_b32 v140, v139, 15, s7
	s_lshl_b32 s7, s16, 8
	v_bfe_u32 v141, v139, 4, 2
	s_or_b32 s7, s7, s45
	v_lshl_or_b32 v138, v141, 3, s7
	v_cmp_eq_u32_e32 vcc, 0, v141
	v_ashrrev_i32_e32 v141, 31, v140
	v_lshlrev_b32_e32 v139, 2, v139
	s_movk_i32 s7, 0x80
	v_lshlrev_b64 v[142:143], 11, v[140:141]
	v_bitop3_b32 v149, v139, 64, v190 bitop3:0x6c
	v_bitop3_b32 v148, v139, s7, v190 bitop3:0x6c
	v_ashrrev_i32_e32 v139, 31, v138
	v_lshl_add_u64 v[142:143], s[4:5], 0, v[142:143]
	v_lshl_add_u64 v[142:143], v[138:139], 1, v[142:143]
	global_load_dwordx4 v[150:153], v[142:143], off
	s_lshl_b32 s16, s16, 2
	s_ashr_i32 s17, s16, 31
	s_waitcnt vmcnt(0)
	v_lshlrev_b32_e32 v154, 16, v150
	v_and_b32_e32 v155, 0xffff0000, v150
	v_lshlrev_b32_e32 v150, 16, v151
	v_and_b32_e32 v151, 0xffff0000, v151
	v_lshlrev_b32_e32 v156, 16, v152
	v_and_b32_e32 v157, 0xffff0000, v152
	v_lshlrev_b32_e32 v152, 16, v153
	v_and_b32_e32 v153, 0xffff0000, v153
	v_pk_add_f32 v[126:127], v[126:127], v[150:151]
	v_pk_add_f32 v[124:125], v[124:125], v[154:155]
	v_pk_add_f32 v[150:151], v[122:123], v[152:153]
	v_pk_add_f32 v[152:153], v[120:121], v[156:157]
	v_cvt_pk_bf16_f32 v120, v124, v125
	v_cvt_pk_bf16_f32 v121, v126, v127
	v_cvt_pk_bf16_f32 v122, v152, v153
	v_cvt_pk_bf16_f32 v123, v150, v151
	global_store_dwordx4 v[142:143], v[120:123], off
	global_load_dwordx4 v[120:123], v[142:143], off offset:256
	v_mul_f32_e32 v154, v125, v125
	v_fmac_f32_e32 v154, v124, v124
	v_fmac_f32_e32 v154, v126, v126
	v_fmac_f32_e32 v154, v127, v127
	v_fmac_f32_e32 v154, v152, v152
	v_fmac_f32_e32 v154, v153, v153
	v_fmac_f32_e32 v154, v150, v150
	v_fmac_f32_e32 v154, v151, v151
	s_waitcnt vmcnt(0)
	v_lshlrev_b32_e32 v124, 16, v120
	v_and_b32_e32 v125, 0xffff0000, v120
	v_lshlrev_b32_e32 v120, 16, v121
	v_and_b32_e32 v121, 0xffff0000, v121
	v_lshlrev_b32_e32 v126, 16, v122
	v_and_b32_e32 v127, 0xffff0000, v122
	v_lshlrev_b32_e32 v122, 16, v123
	v_and_b32_e32 v123, 0xffff0000, v123
	v_pk_add_f32 v[118:119], v[118:119], v[120:121]
	v_pk_add_f32 v[116:117], v[116:117], v[124:125]
	v_pk_add_f32 v[120:121], v[114:115], v[122:123]
	v_pk_add_f32 v[122:123], v[112:113], v[126:127]
	v_cvt_pk_bf16_f32 v112, v116, v117
	v_cvt_pk_bf16_f32 v113, v118, v119
	v_cvt_pk_bf16_f32 v114, v122, v123
	v_cvt_pk_bf16_f32 v115, v120, v121
	global_store_dwordx4 v[142:143], v[112:115], off offset:256
	s_nop 1
	v_mul_f32_e32 v112, v117, v117
	v_fmac_f32_e32 v112, v116, v116
	v_fmac_f32_e32 v112, v118, v118
	v_fmac_f32_e32 v112, v119, v119
	v_fmac_f32_e32 v112, v122, v122
	v_fmac_f32_e32 v112, v123, v123
	v_fmac_f32_e32 v112, v120, v120
	v_fmac_f32_e32 v112, v121, v121
	v_add_f32_e32 v112, v154, v112
	ds_bpermute_b32 v113, v149, v112
	s_waitcnt lgkmcnt(0)
	v_add_f32_e32 v112, v112, v113
	ds_bpermute_b32 v113, v148, v112
	s_and_saveexec_b64 s[18:19], vcc
	s_cbranch_execz .LBB0_1908
	s_waitcnt lgkmcnt(0)
	v_add_f32_e32 v114, v112, v113
	v_lshlrev_b64 v[112:113], 6, v[140:141]
	v_lshl_add_u64 v[112:113], s[2:3], 0, v[112:113]
	v_lshl_add_u64 v[112:113], s[16:17], 2, v[112:113]
	s_lshl_b32 s24, s43, 2
	v_lshl_add_u64 v[112:113], v[112:113], 0, s[24:25]
	global_store_dword v[112:113], v114, off
